# snake MFMA order in all 7 GEMM K-loops (operand reuse between consecutive MFMAs)
# baseline (speedup 1.0000x reference)
;     __device__ __forceinline__ const char* tile(const Unit& u, int t) const { return A + (size_t)u.pm * 2 * hstep() + (size_t)t * (BK * 2); }
;     __device__ __forceinline__ const char* tile(const Unit& u, int t) const { return U + (long)(t >> 2) * xoff + (size_t)u.pn * (1024 * 512) + (size_t)u.pm * 2 * hstep() + (size_t)(t & 3) * (BK * 2); }
; #define PG8_STAGE(bufoff, gbase, voff) do { _Pragma("unroll") for (int _i = 0; _i < 2; ++_i) \
;         __builtin_amdgcn_global_load_lds((const unsigned*)((const char*)(gbase) + (voff)[_i]), (PG8_LAS unsigned*)(lds + (bufoff) + ldsw + _i * 8192), 16, 0, 0); } while (0)
; #define PG8_LDA(dst, b, h) do { _Pragma("unroll") for (int m = 0; m < 4; ++m) _Pragma("unroll") for (int k = 0; k < 2; ++k) dst[m][k] = *(const PG8_LAS bf16x8*)(lds + PG8_SA(b, h) + aoff + m * 2048 + k * 1024); } while (0)
; #define PG8_LDB(dst, b, h) do { _Pragma("unroll") for (int n = 0; n < 2; ++n) _Pragma("unroll") for (int k = 0; k < 2; ++k) dst[n][k] = *(const PG8_LAS bf16x8*)(lds + PG8_SB(b, h) + boff + n * 2048 + k * 1024); } while (0)
; #define PG8_MMA(ai, bj, At, Bt) do { __builtin_amdgcn_s_setprio(1); _Pragma("unroll") for (int m = 0; m < 4; ++m) _Pragma("unroll") for (int n = 0; n < 2; ++n) _Pragma("unroll") for (int k = 0; k < 2; ++k) \
;         acc[ai][bj][m][n] = __builtin_amdgcn_mfma_f32_16x16x32_bf16(Bt[n][k], At[m][k], acc[ai][bj][m][n], 0, 0, 0); __builtin_amdgcn_s_setprio(0); } while (0)
; #define PG8_WAIT_V(n) asm volatile("s_waitcnt vmcnt(" #n ")" ::: "memory")
;     ...
;             const bool last = (t == nt - 2);
;             const char* a1 = AS.tile(cur, t + 1);
;             const char* a2 = last ? AS.tile(nu, 0) : AS.tile(cur, t + 2); const char* b2 = last ? nB : cB + (size_t)(t + 2) * kstep;
;             const char* a3 = last ? AS.tile(nu, 1) : AS.tile(cur, t + 3); const char* b3 = b2 + kstep;
;             PG8_LDB(B0, 0, 0); PG8_LDB(B1, 0, 1); PG8_SCHED; PG8_LDA(At, 0, 0); PG8_STAGE(PG8_SA(1, 1), a1 + hstepA, voffA);
;             PG8_WAIT_V(8); PG8_WAIT_L(0); PG8_BAR; PG8_MMA(0, 0, At, B0); PG8_MMA(0, 1, At, B1); PG8_BAR; PG8_SCHED;
;             PG8_LDA(At, 0, 1); PG8_STAGE(PG8_SB(0, 0), b2, voffB); PG8_STAGE(PG8_SB(0, 1), b2 + hstepB, voffB); PG8_STAGE(PG8_SA(0, 0), a2, voffA);
;             PG8_WAIT_V(8); PG8_WAIT_L(0); PG8_BAR; PG8_MMA(1, 0, At, B0); PG8_MMA(1, 1, At, B1); PG8_BAR; PG8_SCHED;
.LBB0_380:
	s_add_u32 s28, s1, s2
	s_addc_u32 s29, s77, s3
	s_add_u32 s48, s28, 0x100
	s_addc_u32 s49, s29, 0
	s_add_u32 s46, s82, s2
	s_addc_u32 s47, s83, s3
	s_add_u32 s28, s28, 0x180
	s_addc_u32 s29, s29, 0
	s_add_i32 s85, 0, 0x10000
	s_add_i32 s88, 0, 0x14000
	v_add_u32_e32 v158, s85, v174
	v_add_u32_e32 v186, s88, v174
	ds_read_b128 v[132:135], v158
	ds_read_b128 v[136:139], v158 offset:1024
	ds_read_b128 v[140:143], v158 offset:2048
	ds_read_b128 v[158:161], v158 offset:3072
	ds_read_b128 v[162:165], v186
	ds_read_b128 v[166:169], v186 offset:1024
	ds_read_b128 v[182:185], v186 offset:2048
	ds_read_b128 v[186:189], v186 offset:3072
	s_cmpk_eq_i32 s2, 0x700
	s_cselect_b32 s29, s81, s29
	s_cselect_b32 s28, s80, s28
	s_cselect_b32 s47, s76, s47
	s_cselect_b32 s46, s75, s46
	s_cselect_b32 s49, s79, s49
	s_cselect_b32 s48, s78, s48
	v_lshl_add_u64 v[222:223], v[128:129], 0, s[2:3]
	s_add_i32 m0, s27, 0xc000
	ds_read_b128 v[190:193], v180
	ds_read_b128 v[194:197], v180 offset:1024
	ds_read_b128 v[198:201], v180 offset:2048
	ds_read_b128 v[204:207], v180 offset:3072
	ds_read_b128 v[218:221], v180 offset:4096
	ds_read_b128 v[238:241], v180 offset:5120
	ds_read_b128 v[242:245], v180 offset:6144
	ds_read_b128 v[246:249], v180 offset:7168
	global_load_lds_dwordx4 v[222:223], off
	v_lshl_add_u64 v[222:223], v[130:131], 0, s[2:3]
	s_add_i32 m0, s27, 0xe000
	s_nop 0
	global_load_lds_dwordx4 v[222:223], off
	s_waitcnt vmcnt(8)
	s_waitcnt lgkmcnt(0)
	s_barrier
	s_setprio 1
	s_waitcnt lgkmcnt(0)
	v_mfma_f32_16x16x32_bf16 v[124:127], v[132:135], v[190:193], v[124:127]
	v_mfma_f32_16x16x32_bf16 v[120:123], v[140:143], v[190:193], v[120:123]
	v_mfma_f32_16x16x32_bf16 v[104:107], v[140:143], v[198:201], v[104:107]
	v_mfma_f32_16x16x32_bf16 v[108:111], v[132:135], v[198:201], v[108:111]
	v_mfma_f32_16x16x32_bf16 v[92:95], v[132:135], v[218:221], v[92:95]
	v_mfma_f32_16x16x32_bf16 v[88:91], v[140:143], v[218:221], v[88:91]
	v_mfma_f32_16x16x32_bf16 v[72:75], v[140:143], v[242:245], v[72:75]
	v_mfma_f32_16x16x32_bf16 v[76:79], v[132:135], v[242:245], v[76:79]
	v_mfma_f32_16x16x32_bf16 v[124:127], v[136:139], v[194:197], v[124:127]
	v_mfma_f32_16x16x32_bf16 v[120:123], v[158:161], v[194:197], v[120:123]
	v_mfma_f32_16x16x32_bf16 v[104:107], v[158:161], v[204:207], v[104:107]
	v_mfma_f32_16x16x32_bf16 v[108:111], v[136:139], v[204:207], v[108:111]
	v_mfma_f32_16x16x32_bf16 v[92:95], v[136:139], v[238:241], v[92:95]
	v_mfma_f32_16x16x32_bf16 v[88:91], v[158:161], v[238:241], v[88:91]
	v_mfma_f32_16x16x32_bf16 v[72:75], v[158:161], v[246:249], v[72:75]
	v_mfma_f32_16x16x32_bf16 v[76:79], v[136:139], v[246:249], v[76:79]
	s_setprio 0
	s_setprio 1
	v_mfma_f32_16x16x32_bf16 v[116:119], v[162:165], v[190:193], v[116:119]
	v_mfma_f32_16x16x32_bf16 v[112:115], v[182:185], v[190:193], v[112:115]
	v_mfma_f32_16x16x32_bf16 v[96:99], v[182:185], v[198:201], v[96:99]
	v_mfma_f32_16x16x32_bf16 v[100:103], v[162:165], v[198:201], v[100:103]
	v_mfma_f32_16x16x32_bf16 v[84:87], v[162:165], v[218:221], v[84:87]
	v_mfma_f32_16x16x32_bf16 v[80:83], v[182:185], v[218:221], v[80:83]
	v_mfma_f32_16x16x32_bf16 v[64:67], v[182:185], v[242:245], v[64:67]
	v_mfma_f32_16x16x32_bf16 v[68:71], v[162:165], v[242:245], v[68:71]
	v_mfma_f32_16x16x32_bf16 v[116:119], v[166:169], v[194:197], v[116:119]
	v_mfma_f32_16x16x32_bf16 v[112:115], v[186:189], v[194:197], v[112:115]
	v_mfma_f32_16x16x32_bf16 v[96:99], v[186:189], v[204:207], v[96:99]
	v_mfma_f32_16x16x32_bf16 v[100:103], v[166:169], v[204:207], v[100:103]
	v_mfma_f32_16x16x32_bf16 v[84:87], v[166:169], v[238:241], v[84:87]
	v_mfma_f32_16x16x32_bf16 v[80:83], v[186:189], v[238:241], v[80:83]
	v_mfma_f32_16x16x32_bf16 v[64:67], v[186:189], v[246:249], v[64:67]
	v_mfma_f32_16x16x32_bf16 v[68:71], v[166:169], v[246:249], v[68:71]
	s_setprio 0
	s_barrier
	s_add_i32 s85, s85, s52
	v_lshl_add_u64 v[222:223], s[46:47], 0, v[146:147]
	s_mov_b32 m0, s85
	ds_read_b128 v[190:193], v180 offset:16384
	ds_read_b128 v[194:197], v180 offset:17408
	ds_read_b128 v[198:201], v180 offset:18432
	ds_read_b128 v[204:207], v180 offset:19456
	ds_read_b128 v[218:221], v180 offset:20480
	ds_read_b128 v[238:241], v180 offset:21504
	ds_read_b128 v[242:245], v180 offset:22528
	ds_read_b128 v[246:249], v180 offset:23552
	global_load_lds_dwordx4 v[222:223], off
	s_add_i32 m0, s85, 0x2000
	s_add_u32 s86, s46, 0x40000
	v_lshl_add_u64 v[224:225], s[46:47], 0, v[150:151]
	s_addc_u32 s87, s47, 0
	s_add_i32 s85, s88, s52
	global_load_lds_dwordx4 v[224:225], off
	v_lshl_add_u64 v[250:251], s[86:87], 0, v[146:147]
	s_mov_b32 m0, s85
	s_nop 0
	global_load_lds_dwordx4 v[250:251], off
	v_lshl_add_u64 v[250:251], s[86:87], 0, v[150:151]
	s_add_i32 m0, s85, 0x2000
	s_nop 0
	global_load_lds_dwordx4 v[250:251], off
	v_lshl_add_u64 v[250:251], s[48:49], 0, v[144:145]
	s_mov_b32 m0, s27
	s_nop 0
	global_load_lds_dwordx4 v[250:251], off
	v_lshl_add_u64 v[250:251], s[48:49], 0, v[148:149]
	s_mov_b32 m0, s57
	s_nop 0
	global_load_lds_dwordx4 v[250:251], off
	s_waitcnt vmcnt(8)
	s_waitcnt lgkmcnt(0)
	s_barrier
; #define PG8_STAGE(bufoff, gbase, voff) do { _Pragma("unroll") for (int _i = 0; _i < 2; ++_i) \
;         __builtin_amdgcn_global_load_lds((const unsigned*)((const char*)(gbase) + (voff)[_i]), (PG8_LAS unsigned*)(lds + (bufoff) + ldsw + _i * 8192), 16, 0, 0); } while (0)
; #define PG8_LDA(dst, b, h) do { _Pragma("unroll") for (int m = 0; m < 4; ++m) _Pragma("unroll") for (int k = 0; k < 2; ++k) dst[m][k] = *(const PG8_LAS bf16x8*)(lds + PG8_SA(b, h) + aoff + m * 2048 + k * 1024); } while (0)
; #define PG8_LDB(dst, b, h) do { _Pragma("unroll") for (int n = 0; n < 2; ++n) _Pragma("unroll") for (int k = 0; k < 2; ++k) dst[n][k] = *(const PG8_LAS bf16x8*)(lds + PG8_SB(b, h) + boff + n * 2048 + k * 1024); } while (0)
; #define PG8_MMA(ai, bj, At, Bt) do { __builtin_amdgcn_s_setprio(1); _Pragma("unroll") for (int m = 0; m < 4; ++m) _Pragma("unroll") for (int n = 0; n < 2; ++n) _Pragma("unroll") for (int k = 0; k < 2; ++k) \
;         acc[ai][bj][m][n] = __builtin_amdgcn_mfma_f32_16x16x32_bf16(Bt[n][k], At[m][k], acc[ai][bj][m][n], 0, 0, 0); __builtin_amdgcn_s_setprio(0); } while (0)
; #define PG8_WAIT_V(n) asm volatile("s_waitcnt vmcnt(" #n ")" ::: "memory")
; #define PG8_WAIT_L(n) asm volatile("s_waitcnt lgkmcnt(" #n ")" ::: "memory")
; #define PG8_BAR __builtin_amdgcn_s_barrier()
; #define PG8_SCHED __builtin_amdgcn_sched_barrier(0)
;     ...
;             PG8_WAIT_V(8); PG8_WAIT_L(0); PG8_BAR; PG8_MMA(1, 0, At, B0); PG8_MMA(1, 1, At, B1); PG8_BAR; PG8_SCHED;
;             PG8_LDB(B0, 1, 0); PG8_LDB(B1, 1, 1); PG8_SCHED; PG8_LDA(At, 1, 0); PG8_STAGE(PG8_SA(0, 1), a2 + hstepA, voffA);
;             PG8_WAIT_V(8); PG8_WAIT_L(0); PG8_BAR; PG8_MMA(0, 0, At, B0); PG8_MMA(0, 1, At, B1); PG8_BAR; PG8_SCHED;
	s_setprio 1
	s_waitcnt lgkmcnt(0)
	v_mfma_f32_16x16x32_bf16 v[60:63], v[132:135], v[190:193], v[60:63]
	v_mfma_f32_16x16x32_bf16 v[56:59], v[140:143], v[190:193], v[56:59]
	v_mfma_f32_16x16x32_bf16 v[40:43], v[140:143], v[198:201], v[40:43]
	v_mfma_f32_16x16x32_bf16 v[44:47], v[132:135], v[198:201], v[44:47]
	v_mfma_f32_16x16x32_bf16 v[28:31], v[132:135], v[218:221], v[28:31]
	v_mfma_f32_16x16x32_bf16 v[24:27], v[140:143], v[218:221], v[24:27]
	v_mfma_f32_16x16x32_bf16 v[8:11], v[140:143], v[242:245], v[8:11]
	v_mfma_f32_16x16x32_bf16 v[12:15], v[132:135], v[242:245], v[12:15]
	v_mfma_f32_16x16x32_bf16 v[60:63], v[136:139], v[194:197], v[60:63]
	v_mfma_f32_16x16x32_bf16 v[56:59], v[158:161], v[194:197], v[56:59]
	v_mfma_f32_16x16x32_bf16 v[40:43], v[158:161], v[204:207], v[40:43]
	v_mfma_f32_16x16x32_bf16 v[44:47], v[136:139], v[204:207], v[44:47]
	v_mfma_f32_16x16x32_bf16 v[28:31], v[136:139], v[238:241], v[28:31]
	v_mfma_f32_16x16x32_bf16 v[24:27], v[158:161], v[238:241], v[24:27]
	v_mfma_f32_16x16x32_bf16 v[8:11], v[158:161], v[246:249], v[8:11]
	v_mfma_f32_16x16x32_bf16 v[12:15], v[136:139], v[246:249], v[12:15]
	s_setprio 0
	s_setprio 1
	v_mfma_f32_16x16x32_bf16 v[52:55], v[162:165], v[190:193], v[52:55]
	v_mfma_f32_16x16x32_bf16 v[48:51], v[182:185], v[190:193], v[48:51]
	v_mfma_f32_16x16x32_bf16 v[32:35], v[182:185], v[198:201], v[32:35]
	v_mfma_f32_16x16x32_bf16 v[36:39], v[162:165], v[198:201], v[36:39]
	v_mfma_f32_16x16x32_bf16 v[20:23], v[162:165], v[218:221], v[20:23]
	v_mfma_f32_16x16x32_bf16 v[16:19], v[182:185], v[218:221], v[16:19]
	v_mfma_f32_16x16x32_bf16 v[0:3], v[182:185], v[242:245], v[0:3]
	v_mfma_f32_16x16x32_bf16 v[4:7], v[162:165], v[242:245], v[4:7]
	v_mfma_f32_16x16x32_bf16 v[52:55], v[166:169], v[194:197], v[52:55]
	v_mfma_f32_16x16x32_bf16 v[48:51], v[186:189], v[194:197], v[48:51]
	v_mfma_f32_16x16x32_bf16 v[32:35], v[186:189], v[204:207], v[32:35]
	v_mfma_f32_16x16x32_bf16 v[36:39], v[166:169], v[204:207], v[36:39]
	v_mfma_f32_16x16x32_bf16 v[20:23], v[166:169], v[238:241], v[20:23]
	v_mfma_f32_16x16x32_bf16 v[16:19], v[186:189], v[238:241], v[16:19]
	v_mfma_f32_16x16x32_bf16 v[0:3], v[186:189], v[246:249], v[0:3]
	v_mfma_f32_16x16x32_bf16 v[4:7], v[166:169], v[246:249], v[4:7]
	s_setprio 0
	s_barrier
	s_add_i32 s85, 0, 0x18000
	s_add_i32 s86, 0, 0x1c000
	v_add_u32_e32 v158, s85, v174
	v_add_u32_e32 v186, s86, v174
	ds_read_b128 v[132:135], v158
	ds_read_b128 v[136:139], v158 offset:1024
	ds_read_b128 v[140:143], v158 offset:2048
	ds_read_b128 v[158:161], v158 offset:3072
	ds_read_b128 v[162:165], v186
	ds_read_b128 v[166:169], v186 offset:1024
	ds_read_b128 v[182:185], v186 offset:2048
	ds_read_b128 v[186:189], v186 offset:3072
	s_add_u32 s48, s48, 0x40000
	s_addc_u32 s49, s49, 0
	s_mov_b32 m0, s58
	v_lshl_add_u64 v[250:251], s[48:49], 0, v[144:145]
	ds_read_b128 v[190:193], v180 offset:32768
	ds_read_b128 v[194:197], v180 offset:33792
	ds_read_b128 v[198:201], v180 offset:34816
	ds_read_b128 v[204:207], v180 offset:35840
	ds_read_b128 v[218:221], v180 offset:36864
	ds_read_b128 v[238:241], v180 offset:37888
	ds_read_b128 v[242:245], v180 offset:38912
	ds_read_b128 v[246:249], v180 offset:39936
	global_load_lds_dwordx4 v[250:251], off
	v_lshl_add_u64 v[250:251], s[48:49], 0, v[148:149]
	s_mov_b32 m0, s59
	s_nop 0
	global_load_lds_dwordx4 v[250:251], off
	s_waitcnt vmcnt(8)
	s_waitcnt lgkmcnt(0)
	s_barrier
	s_setprio 1
	s_waitcnt lgkmcnt(0)
	v_mfma_f32_16x16x32_bf16 v[124:127], v[132:135], v[190:193], v[124:127]
	v_mfma_f32_16x16x32_bf16 v[120:123], v[140:143], v[190:193], v[120:123]
	v_mfma_f32_16x16x32_bf16 v[104:107], v[140:143], v[198:201], v[104:107]
	v_mfma_f32_16x16x32_bf16 v[108:111], v[132:135], v[198:201], v[108:111]
	v_mfma_f32_16x16x32_bf16 v[92:95], v[132:135], v[218:221], v[92:95]
	v_mfma_f32_16x16x32_bf16 v[88:91], v[140:143], v[218:221], v[88:91]
	v_mfma_f32_16x16x32_bf16 v[72:75], v[140:143], v[242:245], v[72:75]
	v_mfma_f32_16x16x32_bf16 v[76:79], v[132:135], v[242:245], v[76:79]
	v_mfma_f32_16x16x32_bf16 v[124:127], v[136:139], v[194:197], v[124:127]
	v_mfma_f32_16x16x32_bf16 v[120:123], v[158:161], v[194:197], v[120:123]
	v_mfma_f32_16x16x32_bf16 v[104:107], v[158:161], v[204:207], v[104:107]
	v_mfma_f32_16x16x32_bf16 v[108:111], v[136:139], v[204:207], v[108:111]
	v_mfma_f32_16x16x32_bf16 v[92:95], v[136:139], v[238:241], v[92:95]
	v_mfma_f32_16x16x32_bf16 v[88:91], v[158:161], v[238:241], v[88:91]
	v_mfma_f32_16x16x32_bf16 v[72:75], v[158:161], v[246:249], v[72:75]
	v_mfma_f32_16x16x32_bf16 v[76:79], v[136:139], v[246:249], v[76:79]
	s_setprio 0
	s_setprio 1
	v_mfma_f32_16x16x32_bf16 v[116:119], v[162:165], v[190:193], v[116:119]
	v_mfma_f32_16x16x32_bf16 v[112:115], v[182:185], v[190:193], v[112:115]
	v_mfma_f32_16x16x32_bf16 v[96:99], v[182:185], v[198:201], v[96:99]
	v_mfma_f32_16x16x32_bf16 v[100:103], v[162:165], v[198:201], v[100:103]
	v_mfma_f32_16x16x32_bf16 v[84:87], v[162:165], v[218:221], v[84:87]
	v_mfma_f32_16x16x32_bf16 v[80:83], v[182:185], v[218:221], v[80:83]
	v_mfma_f32_16x16x32_bf16 v[64:67], v[182:185], v[242:245], v[64:67]
	v_mfma_f32_16x16x32_bf16 v[68:71], v[162:165], v[242:245], v[68:71]
	v_mfma_f32_16x16x32_bf16 v[116:119], v[166:169], v[194:197], v[116:119]
	v_mfma_f32_16x16x32_bf16 v[112:115], v[186:189], v[194:197], v[112:115]
	v_mfma_f32_16x16x32_bf16 v[96:99], v[186:189], v[204:207], v[96:99]
	v_mfma_f32_16x16x32_bf16 v[100:103], v[166:169], v[204:207], v[100:103]
	v_mfma_f32_16x16x32_bf16 v[84:87], v[166:169], v[238:241], v[84:87]
	v_mfma_f32_16x16x32_bf16 v[80:83], v[186:189], v[238:241], v[80:83]
	v_mfma_f32_16x16x32_bf16 v[64:67], v[186:189], v[246:249], v[64:67]
	v_mfma_f32_16x16x32_bf16 v[68:71], v[166:169], v[246:249], v[68:71]
	s_setprio 0
	s_barrier
; #define PG8_STAGE(bufoff, gbase, voff) do { _Pragma("unroll") for (int _i = 0; _i < 2; ++_i) \
;         __builtin_amdgcn_global_load_lds((const unsigned*)((const char*)(gbase) + (voff)[_i]), (PG8_LAS unsigned*)(lds + (bufoff) + ldsw + _i * 8192), 16, 0, 0); } while (0)
; #define PG8_LDA(dst, b, h) do { _Pragma("unroll") for (int m = 0; m < 4; ++m) _Pragma("unroll") for (int k = 0; k < 2; ++k) dst[m][k] = *(const PG8_LAS bf16x8*)(lds + PG8_SA(b, h) + aoff + m * 2048 + k * 1024); } while (0)
; #define PG8_MMA(ai, bj, At, Bt) do { __builtin_amdgcn_s_setprio(1); _Pragma("unroll") for (int m = 0; m < 4; ++m) _Pragma("unroll") for (int n = 0; n < 2; ++n) _Pragma("unroll") for (int k = 0; k < 2; ++k) \
;         acc[ai][bj][m][n] = __builtin_amdgcn_mfma_f32_16x16x32_bf16(Bt[n][k], At[m][k], acc[ai][bj][m][n], 0, 0, 0); __builtin_amdgcn_s_setprio(0); } while (0)
; #define PG8_WAIT_V(n) asm volatile("s_waitcnt vmcnt(" #n ")" ::: "memory")
; #define PG8_WAIT_L(n) asm volatile("s_waitcnt lgkmcnt(" #n ")" ::: "memory")
; #define PG8_BAR __builtin_amdgcn_s_barrier()
; #define PG8_SCHED __builtin_amdgcn_sched_barrier(0)
;     ...
;             PG8_LDA(At, 1, 1); PG8_STAGE(PG8_SB(1, 0), b3, voffB); PG8_STAGE(PG8_SB(1, 1), b3 + hstepB, voffB); PG8_STAGE(PG8_SA(1, 0), a3, voffA);
;             PG8_WAIT_V(8); PG8_WAIT_L(0); PG8_BAR; PG8_MMA(1, 0, At, B0); PG8_MMA(1, 1, At, B1); PG8_BAR; PG8_SCHED;
;         }
;         if (wr == 0) PG8_BAR;
;         if (!has_next && wmat && gtid * 128u < wbytes) asm volatile("global_load_dword %0, %1, off" : "+v"(warmm) : "v"(wmat + (size_t)gtid * 128u) : "memory");
	s_add_i32 s48, s85, s52
	v_lshl_add_u64 v[222:223], v[222:223], 0, s[90:91]
	s_mov_b32 m0, s48
	ds_read_b128 v[190:193], v180 offset:49152
	ds_read_b128 v[194:197], v180 offset:50176
	ds_read_b128 v[198:201], v180 offset:51200
	ds_read_b128 v[204:207], v180 offset:52224
	ds_read_b128 v[218:221], v180 offset:53248
	ds_read_b128 v[238:241], v180 offset:54272
	ds_read_b128 v[242:245], v180 offset:55296
	ds_read_b128 v[246:249], v180 offset:56320
	global_load_lds_dwordx4 v[222:223], off
	s_add_i32 m0, s48, 0x2000
	s_add_u32 s46, s46, 0x40080
	v_lshl_add_u64 v[222:223], v[224:225], 0, s[90:91]
	s_addc_u32 s47, s47, 0
	s_add_i32 s48, s86, s52
	global_load_lds_dwordx4 v[222:223], off
	v_lshl_add_u64 v[222:223], s[46:47], 0, v[146:147]
	s_mov_b32 m0, s48
	s_nop 0
	global_load_lds_dwordx4 v[222:223], off
	v_lshl_add_u64 v[222:223], s[46:47], 0, v[150:151]
	s_add_i32 m0, s48, 0x2000
	s_nop 0
	global_load_lds_dwordx4 v[222:223], off
	v_lshl_add_u64 v[222:223], s[28:29], 0, v[144:145]
	s_mov_b32 m0, s60
	s_nop 0
	global_load_lds_dwordx4 v[222:223], off
	v_lshl_add_u64 v[222:223], s[28:29], 0, v[148:149]
	s_mov_b32 m0, s61
	s_nop 0
	global_load_lds_dwordx4 v[222:223], off
	s_waitcnt vmcnt(8)
	s_waitcnt lgkmcnt(0)
	s_barrier
	s_setprio 1
	s_waitcnt lgkmcnt(0)
	v_mfma_f32_16x16x32_bf16 v[60:63], v[132:135], v[190:193], v[60:63]
	v_mfma_f32_16x16x32_bf16 v[56:59], v[140:143], v[190:193], v[56:59]
	v_mfma_f32_16x16x32_bf16 v[40:43], v[140:143], v[198:201], v[40:43]
	v_mfma_f32_16x16x32_bf16 v[44:47], v[132:135], v[198:201], v[44:47]
	v_mfma_f32_16x16x32_bf16 v[28:31], v[132:135], v[218:221], v[28:31]
	v_mfma_f32_16x16x32_bf16 v[24:27], v[140:143], v[218:221], v[24:27]
	v_mfma_f32_16x16x32_bf16 v[8:11], v[140:143], v[242:245], v[8:11]
	v_mfma_f32_16x16x32_bf16 v[12:15], v[132:135], v[242:245], v[12:15]
	v_mfma_f32_16x16x32_bf16 v[60:63], v[136:139], v[194:197], v[60:63]
	v_mfma_f32_16x16x32_bf16 v[56:59], v[158:161], v[194:197], v[56:59]
	v_mfma_f32_16x16x32_bf16 v[40:43], v[158:161], v[204:207], v[40:43]
	v_mfma_f32_16x16x32_bf16 v[44:47], v[136:139], v[204:207], v[44:47]
	v_mfma_f32_16x16x32_bf16 v[28:31], v[136:139], v[238:241], v[28:31]
	v_mfma_f32_16x16x32_bf16 v[24:27], v[158:161], v[238:241], v[24:27]
	v_mfma_f32_16x16x32_bf16 v[8:11], v[158:161], v[246:249], v[8:11]
	v_mfma_f32_16x16x32_bf16 v[12:15], v[136:139], v[246:249], v[12:15]
	s_setprio 0
	s_setprio 1
	v_mfma_f32_16x16x32_bf16 v[52:55], v[162:165], v[190:193], v[52:55]
	v_mfma_f32_16x16x32_bf16 v[48:51], v[182:185], v[190:193], v[48:51]
	v_mfma_f32_16x16x32_bf16 v[32:35], v[182:185], v[198:201], v[32:35]
	v_mfma_f32_16x16x32_bf16 v[36:39], v[162:165], v[198:201], v[36:39]
	v_mfma_f32_16x16x32_bf16 v[20:23], v[162:165], v[218:221], v[20:23]
	v_mfma_f32_16x16x32_bf16 v[16:19], v[182:185], v[218:221], v[16:19]
	v_mfma_f32_16x16x32_bf16 v[0:3], v[182:185], v[242:245], v[0:3]
	v_mfma_f32_16x16x32_bf16 v[4:7], v[162:165], v[242:245], v[4:7]
	v_mfma_f32_16x16x32_bf16 v[52:55], v[166:169], v[194:197], v[52:55]
	v_mfma_f32_16x16x32_bf16 v[48:51], v[186:189], v[194:197], v[48:51]
	v_mfma_f32_16x16x32_bf16 v[32:35], v[186:189], v[204:207], v[32:35]
	v_mfma_f32_16x16x32_bf16 v[36:39], v[166:169], v[204:207], v[36:39]
	v_mfma_f32_16x16x32_bf16 v[20:23], v[166:169], v[238:241], v[20:23]
	v_mfma_f32_16x16x32_bf16 v[16:19], v[186:189], v[238:241], v[16:19]
	v_mfma_f32_16x16x32_bf16 v[0:3], v[186:189], v[246:249], v[0:3]
	v_mfma_f32_16x16x32_bf16 v[4:7], v[166:169], v[246:249], v[4:7]
	s_setprio 0
	s_barrier
	s_add_i32 s84, s84, 2
	s_add_u32 s2, s2, 0x100
	s_addc_u32 s3, s3, 0
	s_cmp_gt_u32 s84, 13
	s_cbranch_scc0 .LBB0_380
	s_and_b64 vcc, exec, s[30:31]
	s_cbranch_vccz .LBB0_385
	s_barrier
	s_and_b64 s[28:29], s[20:21], s[44:45]
	s_and_saveexec_b64 s[2:3], s[28:29]
	s_cbranch_execnz .LBB0_386

;     __device__ __forceinline__ const char* tile(const Unit& u, int t) const { return A + (size_t)u.pm * 2 * hstep() + (size_t)t * (BK * 2); }
;     __device__ __forceinline__ const char* tile(const Unit& u, int t) const { return U + (long)(t >> 2) * xoff + (size_t)u.pn * (1024 * 512) + (size_t)u.pm * 2 * hstep() + (size_t)(t & 3) * (BK * 2); }
; #define PG8_STAGE(bufoff, gbase, voff) do { _Pragma("unroll") for (int _i = 0; _i < 2; ++_i) \
;         __builtin_amdgcn_global_load_lds((const unsigned*)((const char*)(gbase) + (voff)[_i]), (PG8_LAS unsigned*)(lds + (bufoff) + ldsw + _i * 8192), 16, 0, 0); } while (0)
; #define PG8_LDA(dst, b, h) do { _Pragma("unroll") for (int m = 0; m < 4; ++m) _Pragma("unroll") for (int k = 0; k < 2; ++k) dst[m][k] = *(const PG8_LAS bf16x8*)(lds + PG8_SA(b, h) + aoff + m * 2048 + k * 1024); } while (0)
; #define PG8_LDB(dst, b, h) do { _Pragma("unroll") for (int n = 0; n < 2; ++n) _Pragma("unroll") for (int k = 0; k < 2; ++k) dst[n][k] = *(const PG8_LAS bf16x8*)(lds + PG8_SB(b, h) + boff + n * 2048 + k * 1024); } while (0)
; #define PG8_MMA(ai, bj, At, Bt) do { __builtin_amdgcn_s_setprio(1); _Pragma("unroll") for (int m = 0; m < 4; ++m) _Pragma("unroll") for (int n = 0; n < 2; ++n) _Pragma("unroll") for (int k = 0; k < 2; ++k) \
;         acc[ai][bj][m][n] = __builtin_amdgcn_mfma_f32_16x16x32_bf16(Bt[n][k], At[m][k], acc[ai][bj][m][n], 0, 0, 0); __builtin_amdgcn_s_setprio(0); } while (0)
; #define PG8_WAIT_V(n) asm volatile("s_waitcnt vmcnt(" #n ")" ::: "memory")
;     ...
;             const bool last = (t == nt - 2);
;             const char* a1 = AS.tile(cur, t + 1);
;             const char* a2 = last ? AS.tile(nu, 0) : AS.tile(cur, t + 2); const char* b2 = last ? nB : cB + (size_t)(t + 2) * kstep;
;             const char* a3 = last ? AS.tile(nu, 1) : AS.tile(cur, t + 3); const char* b3 = b2 + kstep;
;             PG8_LDB(B0, 0, 0); PG8_LDB(B1, 0, 1); PG8_SCHED; PG8_LDA(At, 0, 0); PG8_STAGE(PG8_SA(1, 1), a1 + hstepA, voffA);
;             PG8_WAIT_V(8); PG8_WAIT_L(0); PG8_BAR; PG8_MMA(0, 0, At, B0); PG8_MMA(0, 1, At, B1); PG8_BAR; PG8_SCHED;
;             PG8_LDA(At, 0, 1); PG8_STAGE(PG8_SB(0, 0), b2, voffB); PG8_STAGE(PG8_SB(0, 1), b2 + hstepB, voffB); PG8_STAGE(PG8_SA(0, 0), a2, voffA);
;             PG8_WAIT_V(8); PG8_WAIT_L(0); PG8_BAR; PG8_MMA(1, 0, At, B0); PG8_MMA(1, 1, At, B1); PG8_BAR; PG8_SCHED;
.LBB0_451:
	s_add_u32 s20, s61, s18
	s_addc_u32 s21, s64, s19
	s_add_u32 s26, s20, 0x3600100
	s_addc_u32 s27, s21, 0
	s_add_u32 s24, s65, s18
	s_addc_u32 s25, s66, s19
	s_add_u32 s20, s20, 0x3600180
	s_addc_u32 s21, s21, 0
	s_add_i32 s68, 0, 0x10000
	s_add_i32 s70, 0, 0x14000
	v_add_u32_e32 v144, s68, v203
	v_add_u32_e32 v174, s70, v203
	ds_read_b128 v[132:135], v144
	ds_read_b128 v[136:139], v144 offset:1024
	ds_read_b128 v[140:143], v144 offset:2048
	ds_read_b128 v[144:147], v144 offset:3072
	ds_read_b128 v[148:151], v174
	ds_read_b128 v[152:155], v174 offset:1024
	ds_read_b128 v[170:173], v174 offset:2048
	ds_read_b128 v[174:177], v174 offset:3072
	s_cmpk_eq_i32 s18, 0x700
	s_cselect_b32 s21, s60, s21
	s_cselect_b32 s20, s59, s20
	s_cselect_b32 s25, s57, s25
	s_cselect_b32 s24, s56, s24
	s_cselect_b32 s27, s58, s27
	s_cselect_b32 s26, s3, s26
	v_lshl_add_u64 v[238:239], v[112:113], 0, s[18:19]
	s_add_i32 m0, s35, 0xc000
	ds_read_b128 v[178:181], v211
	ds_read_b128 v[182:185], v211 offset:1024
	ds_read_b128 v[186:189], v211 offset:2048
	ds_read_b128 v[190:193], v211 offset:3072
	ds_read_b128 v[194:197], v211 offset:4096
	ds_read_b128 v[198:201], v211 offset:5120
	ds_read_b128 v[218:221], v211 offset:6144
	ds_read_b128 v[222:225], v211 offset:7168
	global_load_lds_dwordx4 v[238:239], off
	v_lshl_add_u64 v[238:239], v[114:115], 0, s[18:19]
	s_add_i32 m0, s35, 0xe000
	s_nop 0
	global_load_lds_dwordx4 v[238:239], off
	s_waitcnt vmcnt(8)
	s_waitcnt lgkmcnt(0)
	s_barrier
	s_setprio 1
	s_waitcnt lgkmcnt(0)
	v_mfma_f32_16x16x32_bf16 v[120:123], v[132:135], v[178:181], v[120:123]
	v_mfma_f32_16x16x32_bf16 v[116:119], v[140:143], v[178:181], v[116:119]
	v_mfma_f32_16x16x32_bf16 v[104:107], v[140:143], v[186:189], v[104:107]
	v_mfma_f32_16x16x32_bf16 v[108:111], v[132:135], v[186:189], v[108:111]
	v_mfma_f32_16x16x32_bf16 v[92:95], v[132:135], v[194:197], v[92:95]
	v_mfma_f32_16x16x32_bf16 v[88:91], v[140:143], v[194:197], v[88:91]
	v_mfma_f32_16x16x32_bf16 v[72:75], v[140:143], v[218:221], v[72:75]
	v_mfma_f32_16x16x32_bf16 v[76:79], v[132:135], v[218:221], v[76:79]
	v_mfma_f32_16x16x32_bf16 v[120:123], v[136:139], v[182:185], v[120:123]
	v_mfma_f32_16x16x32_bf16 v[116:119], v[144:147], v[182:185], v[116:119]
	v_mfma_f32_16x16x32_bf16 v[104:107], v[144:147], v[190:193], v[104:107]
	v_mfma_f32_16x16x32_bf16 v[108:111], v[136:139], v[190:193], v[108:111]
	v_mfma_f32_16x16x32_bf16 v[92:95], v[136:139], v[198:201], v[92:95]
	v_mfma_f32_16x16x32_bf16 v[88:91], v[144:147], v[198:201], v[88:91]
	v_mfma_f32_16x16x32_bf16 v[72:75], v[144:147], v[222:225], v[72:75]
	v_mfma_f32_16x16x32_bf16 v[76:79], v[136:139], v[222:225], v[76:79]
	s_setprio 0
	s_setprio 1
	v_mfma_f32_16x16x32_bf16 v[128:131], v[148:151], v[178:181], v[128:131]
	v_mfma_f32_16x16x32_bf16 v[124:127], v[170:173], v[178:181], v[124:127]
	v_mfma_f32_16x16x32_bf16 v[96:99], v[170:173], v[186:189], v[96:99]
	v_mfma_f32_16x16x32_bf16 v[100:103], v[148:151], v[186:189], v[100:103]
	v_mfma_f32_16x16x32_bf16 v[84:87], v[148:151], v[194:197], v[84:87]
	v_mfma_f32_16x16x32_bf16 v[80:83], v[170:173], v[194:197], v[80:83]
	v_mfma_f32_16x16x32_bf16 v[64:67], v[170:173], v[218:221], v[64:67]
	v_mfma_f32_16x16x32_bf16 v[68:71], v[148:151], v[218:221], v[68:71]
	v_mfma_f32_16x16x32_bf16 v[128:131], v[152:155], v[182:185], v[128:131]
	v_mfma_f32_16x16x32_bf16 v[124:127], v[174:177], v[182:185], v[124:127]
	v_mfma_f32_16x16x32_bf16 v[96:99], v[174:177], v[190:193], v[96:99]
	v_mfma_f32_16x16x32_bf16 v[100:103], v[152:155], v[190:193], v[100:103]
	v_mfma_f32_16x16x32_bf16 v[84:87], v[152:155], v[198:201], v[84:87]
	v_mfma_f32_16x16x32_bf16 v[80:83], v[174:177], v[198:201], v[80:83]
	v_mfma_f32_16x16x32_bf16 v[64:67], v[174:177], v[222:225], v[64:67]
	v_mfma_f32_16x16x32_bf16 v[68:71], v[152:155], v[222:225], v[68:71]
	s_setprio 0
	s_barrier
	s_add_i32 s68, s68, s31
	v_lshl_add_u64 v[238:239], s[24:25], 0, v[208:209]
	s_mov_b32 m0, s68
	ds_read_b128 v[178:181], v211 offset:16384
	ds_read_b128 v[182:185], v211 offset:17408
	ds_read_b128 v[186:189], v211 offset:18432
	ds_read_b128 v[190:193], v211 offset:19456
	ds_read_b128 v[194:197], v211 offset:20480
	ds_read_b128 v[198:201], v211 offset:21504
	ds_read_b128 v[218:221], v211 offset:22528
	ds_read_b128 v[222:225], v211 offset:23552
	global_load_lds_dwordx4 v[238:239], off
	s_add_i32 m0, s68, 0x2000
	s_add_u32 s68, s24, 0x40000
	v_lshl_add_u64 v[240:241], s[24:25], 0, v[156:157]
	s_addc_u32 s69, s25, 0
	s_add_i32 s70, s70, s31
	global_load_lds_dwordx4 v[240:241], off
	v_lshl_add_u64 v[242:243], s[68:69], 0, v[208:209]
	s_mov_b32 m0, s70
	s_nop 0
	global_load_lds_dwordx4 v[242:243], off
	v_lshl_add_u64 v[242:243], s[68:69], 0, v[156:157]
	s_add_i32 m0, s70, 0x2000
	s_nop 0
	global_load_lds_dwordx4 v[242:243], off
	v_lshl_add_u64 v[242:243], s[26:27], 0, v[160:161]
	s_mov_b32 m0, s35
	s_nop 0
	global_load_lds_dwordx4 v[242:243], off
	v_lshl_add_u64 v[242:243], s[26:27], 0, v[158:159]
	s_mov_b32 m0, s44
	s_nop 0
	global_load_lds_dwordx4 v[242:243], off
	s_waitcnt vmcnt(8)
	s_waitcnt lgkmcnt(0)
	s_barrier
; #define PG8_STAGE(bufoff, gbase, voff) do { _Pragma("unroll") for (int _i = 0; _i < 2; ++_i) \
;         __builtin_amdgcn_global_load_lds((const unsigned*)((const char*)(gbase) + (voff)[_i]), (PG8_LAS unsigned*)(lds + (bufoff) + ldsw + _i * 8192), 16, 0, 0); } while (0)
; #define PG8_LDA(dst, b, h) do { _Pragma("unroll") for (int m = 0; m < 4; ++m) _Pragma("unroll") for (int k = 0; k < 2; ++k) dst[m][k] = *(const PG8_LAS bf16x8*)(lds + PG8_SA(b, h) + aoff + m * 2048 + k * 1024); } while (0)
; #define PG8_LDB(dst, b, h) do { _Pragma("unroll") for (int n = 0; n < 2; ++n) _Pragma("unroll") for (int k = 0; k < 2; ++k) dst[n][k] = *(const PG8_LAS bf16x8*)(lds + PG8_SB(b, h) + boff + n * 2048 + k * 1024); } while (0)
; #define PG8_MMA(ai, bj, At, Bt) do { __builtin_amdgcn_s_setprio(1); _Pragma("unroll") for (int m = 0; m < 4; ++m) _Pragma("unroll") for (int n = 0; n < 2; ++n) _Pragma("unroll") for (int k = 0; k < 2; ++k) \
;         acc[ai][bj][m][n] = __builtin_amdgcn_mfma_f32_16x16x32_bf16(Bt[n][k], At[m][k], acc[ai][bj][m][n], 0, 0, 0); __builtin_amdgcn_s_setprio(0); } while (0)
; #define PG8_WAIT_V(n) asm volatile("s_waitcnt vmcnt(" #n ")" ::: "memory")
; #define PG8_WAIT_L(n) asm volatile("s_waitcnt lgkmcnt(" #n ")" ::: "memory")
; #define PG8_BAR __builtin_amdgcn_s_barrier()
; #define PG8_SCHED __builtin_amdgcn_sched_barrier(0)
;     ...
;             PG8_WAIT_V(8); PG8_WAIT_L(0); PG8_BAR; PG8_MMA(1, 0, At, B0); PG8_MMA(1, 1, At, B1); PG8_BAR; PG8_SCHED;
;             PG8_LDB(B0, 1, 0); PG8_LDB(B1, 1, 1); PG8_SCHED; PG8_LDA(At, 1, 0); PG8_STAGE(PG8_SA(0, 1), a2 + hstepA, voffA);
;             PG8_WAIT_V(8); PG8_WAIT_L(0); PG8_BAR; PG8_MMA(0, 0, At, B0); PG8_MMA(0, 1, At, B1); PG8_BAR; PG8_SCHED;
	s_setprio 1
	s_waitcnt lgkmcnt(0)
	v_mfma_f32_16x16x32_bf16 v[60:63], v[132:135], v[178:181], v[60:63]
	v_mfma_f32_16x16x32_bf16 v[56:59], v[140:143], v[178:181], v[56:59]
	v_mfma_f32_16x16x32_bf16 v[40:43], v[140:143], v[186:189], v[40:43]
	v_mfma_f32_16x16x32_bf16 v[44:47], v[132:135], v[186:189], v[44:47]
	v_mfma_f32_16x16x32_bf16 v[28:31], v[132:135], v[194:197], v[28:31]
	v_mfma_f32_16x16x32_bf16 v[24:27], v[140:143], v[194:197], v[24:27]
	v_mfma_f32_16x16x32_bf16 v[8:11], v[140:143], v[218:221], v[8:11]
	v_mfma_f32_16x16x32_bf16 v[12:15], v[132:135], v[218:221], v[12:15]
	v_mfma_f32_16x16x32_bf16 v[60:63], v[136:139], v[182:185], v[60:63]
	v_mfma_f32_16x16x32_bf16 v[56:59], v[144:147], v[182:185], v[56:59]
	v_mfma_f32_16x16x32_bf16 v[40:43], v[144:147], v[190:193], v[40:43]
	v_mfma_f32_16x16x32_bf16 v[44:47], v[136:139], v[190:193], v[44:47]
	v_mfma_f32_16x16x32_bf16 v[28:31], v[136:139], v[198:201], v[28:31]
	v_mfma_f32_16x16x32_bf16 v[24:27], v[144:147], v[198:201], v[24:27]
	v_mfma_f32_16x16x32_bf16 v[8:11], v[144:147], v[222:225], v[8:11]
	v_mfma_f32_16x16x32_bf16 v[12:15], v[136:139], v[222:225], v[12:15]
	s_setprio 0
	s_setprio 1
	v_mfma_f32_16x16x32_bf16 v[52:55], v[148:151], v[178:181], v[52:55]
	v_mfma_f32_16x16x32_bf16 v[48:51], v[170:173], v[178:181], v[48:51]
	v_mfma_f32_16x16x32_bf16 v[32:35], v[170:173], v[186:189], v[32:35]
	v_mfma_f32_16x16x32_bf16 v[36:39], v[148:151], v[186:189], v[36:39]
	v_mfma_f32_16x16x32_bf16 v[20:23], v[148:151], v[194:197], v[20:23]
	v_mfma_f32_16x16x32_bf16 v[16:19], v[170:173], v[194:197], v[16:19]
	v_mfma_f32_16x16x32_bf16 v[0:3], v[170:173], v[218:221], v[0:3]
	v_mfma_f32_16x16x32_bf16 v[4:7], v[148:151], v[218:221], v[4:7]
	v_mfma_f32_16x16x32_bf16 v[52:55], v[152:155], v[182:185], v[52:55]
	v_mfma_f32_16x16x32_bf16 v[48:51], v[174:177], v[182:185], v[48:51]
	v_mfma_f32_16x16x32_bf16 v[32:35], v[174:177], v[190:193], v[32:35]
	v_mfma_f32_16x16x32_bf16 v[36:39], v[152:155], v[190:193], v[36:39]
	v_mfma_f32_16x16x32_bf16 v[20:23], v[152:155], v[198:201], v[20:23]
	v_mfma_f32_16x16x32_bf16 v[16:19], v[174:177], v[198:201], v[16:19]
	v_mfma_f32_16x16x32_bf16 v[0:3], v[174:177], v[222:225], v[0:3]
	v_mfma_f32_16x16x32_bf16 v[4:7], v[152:155], v[222:225], v[4:7]
	s_setprio 0
	s_barrier
	s_add_i32 s68, 0, 0x18000
	s_add_i32 s69, 0, 0x1c000
	v_add_u32_e32 v144, s68, v203
	v_add_u32_e32 v174, s69, v203
	ds_read_b128 v[132:135], v144
	ds_read_b128 v[136:139], v144 offset:1024
	ds_read_b128 v[140:143], v144 offset:2048
	ds_read_b128 v[144:147], v144 offset:3072
	ds_read_b128 v[148:151], v174
	ds_read_b128 v[152:155], v174 offset:1024
	ds_read_b128 v[170:173], v174 offset:2048
	ds_read_b128 v[174:177], v174 offset:3072
	s_add_u32 s26, s26, 0x40000
	s_addc_u32 s27, s27, 0
	s_mov_b32 m0, s45
	v_lshl_add_u64 v[242:243], s[26:27], 0, v[160:161]
	ds_read_b128 v[178:181], v211 offset:32768
	ds_read_b128 v[182:185], v211 offset:33792
	ds_read_b128 v[186:189], v211 offset:34816
	ds_read_b128 v[190:193], v211 offset:35840
	ds_read_b128 v[194:197], v211 offset:36864
	ds_read_b128 v[198:201], v211 offset:37888
	ds_read_b128 v[218:221], v211 offset:38912
	ds_read_b128 v[222:225], v211 offset:39936
	global_load_lds_dwordx4 v[242:243], off
	v_lshl_add_u64 v[242:243], s[26:27], 0, v[158:159]
	s_mov_b32 m0, s46
	s_nop 0
	global_load_lds_dwordx4 v[242:243], off
	s_waitcnt vmcnt(8)
	s_waitcnt lgkmcnt(0)
	s_barrier
	s_setprio 1
	s_waitcnt lgkmcnt(0)
	v_mfma_f32_16x16x32_bf16 v[120:123], v[132:135], v[178:181], v[120:123]
	v_mfma_f32_16x16x32_bf16 v[116:119], v[140:143], v[178:181], v[116:119]
	v_mfma_f32_16x16x32_bf16 v[104:107], v[140:143], v[186:189], v[104:107]
	v_mfma_f32_16x16x32_bf16 v[108:111], v[132:135], v[186:189], v[108:111]
	v_mfma_f32_16x16x32_bf16 v[92:95], v[132:135], v[194:197], v[92:95]
	v_mfma_f32_16x16x32_bf16 v[88:91], v[140:143], v[194:197], v[88:91]
	v_mfma_f32_16x16x32_bf16 v[72:75], v[140:143], v[218:221], v[72:75]
	v_mfma_f32_16x16x32_bf16 v[76:79], v[132:135], v[218:221], v[76:79]
	v_mfma_f32_16x16x32_bf16 v[120:123], v[136:139], v[182:185], v[120:123]
	v_mfma_f32_16x16x32_bf16 v[116:119], v[144:147], v[182:185], v[116:119]
	v_mfma_f32_16x16x32_bf16 v[104:107], v[144:147], v[190:193], v[104:107]
	v_mfma_f32_16x16x32_bf16 v[108:111], v[136:139], v[190:193], v[108:111]
	v_mfma_f32_16x16x32_bf16 v[92:95], v[136:139], v[198:201], v[92:95]
	v_mfma_f32_16x16x32_bf16 v[88:91], v[144:147], v[198:201], v[88:91]
	v_mfma_f32_16x16x32_bf16 v[72:75], v[144:147], v[222:225], v[72:75]
	v_mfma_f32_16x16x32_bf16 v[76:79], v[136:139], v[222:225], v[76:79]
	s_setprio 0
	s_setprio 1
	v_mfma_f32_16x16x32_bf16 v[128:131], v[148:151], v[178:181], v[128:131]
	v_mfma_f32_16x16x32_bf16 v[124:127], v[170:173], v[178:181], v[124:127]
	v_mfma_f32_16x16x32_bf16 v[96:99], v[170:173], v[186:189], v[96:99]
	v_mfma_f32_16x16x32_bf16 v[100:103], v[148:151], v[186:189], v[100:103]
	v_mfma_f32_16x16x32_bf16 v[84:87], v[148:151], v[194:197], v[84:87]
	v_mfma_f32_16x16x32_bf16 v[80:83], v[170:173], v[194:197], v[80:83]
	v_mfma_f32_16x16x32_bf16 v[64:67], v[170:173], v[218:221], v[64:67]
	v_mfma_f32_16x16x32_bf16 v[68:71], v[148:151], v[218:221], v[68:71]
	v_mfma_f32_16x16x32_bf16 v[128:131], v[152:155], v[182:185], v[128:131]
	v_mfma_f32_16x16x32_bf16 v[124:127], v[174:177], v[182:185], v[124:127]
	v_mfma_f32_16x16x32_bf16 v[96:99], v[174:177], v[190:193], v[96:99]
	v_mfma_f32_16x16x32_bf16 v[100:103], v[152:155], v[190:193], v[100:103]
	v_mfma_f32_16x16x32_bf16 v[84:87], v[152:155], v[198:201], v[84:87]
	v_mfma_f32_16x16x32_bf16 v[80:83], v[174:177], v[198:201], v[80:83]
	v_mfma_f32_16x16x32_bf16 v[64:67], v[174:177], v[222:225], v[64:67]
	v_mfma_f32_16x16x32_bf16 v[68:71], v[152:155], v[222:225], v[68:71]
	s_setprio 0
	s_barrier
; #define PG8_STAGE(bufoff, gbase, voff) do { _Pragma("unroll") for (int _i = 0; _i < 2; ++_i) \
;         __builtin_amdgcn_global_load_lds((const unsigned*)((const char*)(gbase) + (voff)[_i]), (PG8_LAS unsigned*)(lds + (bufoff) + ldsw + _i * 8192), 16, 0, 0); } while (0)
; #define PG8_LDA(dst, b, h) do { _Pragma("unroll") for (int m = 0; m < 4; ++m) _Pragma("unroll") for (int k = 0; k < 2; ++k) dst[m][k] = *(const PG8_LAS bf16x8*)(lds + PG8_SA(b, h) + aoff + m * 2048 + k * 1024); } while (0)
; #define PG8_MMA(ai, bj, At, Bt) do { __builtin_amdgcn_s_setprio(1); _Pragma("unroll") for (int m = 0; m < 4; ++m) _Pragma("unroll") for (int n = 0; n < 2; ++n) _Pragma("unroll") for (int k = 0; k < 2; ++k) \
;         acc[ai][bj][m][n] = __builtin_amdgcn_mfma_f32_16x16x32_bf16(Bt[n][k], At[m][k], acc[ai][bj][m][n], 0, 0, 0); __builtin_amdgcn_s_setprio(0); } while (0)
; #define PG8_WAIT_V(n) asm volatile("s_waitcnt vmcnt(" #n ")" ::: "memory")
; #define PG8_WAIT_L(n) asm volatile("s_waitcnt lgkmcnt(" #n ")" ::: "memory")
; #define PG8_BAR __builtin_amdgcn_s_barrier()
; #define PG8_SCHED __builtin_amdgcn_sched_barrier(0)
;     ...
;             PG8_LDA(At, 1, 1); PG8_STAGE(PG8_SB(1, 0), b3, voffB); PG8_STAGE(PG8_SB(1, 1), b3 + hstepB, voffB); PG8_STAGE(PG8_SA(1, 0), a3, voffA);
;             PG8_WAIT_V(8); PG8_WAIT_L(0); PG8_BAR; PG8_MMA(1, 0, At, B0); PG8_MMA(1, 1, At, B1); PG8_BAR; PG8_SCHED;
;         }
;         if (wr == 0) PG8_BAR;
;         if (!has_next && wmat && gtid * 128u < wbytes) asm volatile("global_load_dword %0, %1, off" : "+v"(warmm) : "v"(wmat + (size_t)gtid * 128u) : "memory");
	s_add_i32 s26, s68, s31
	v_lshl_add_u64 v[238:239], v[238:239], 0, s[72:73]
	s_mov_b32 m0, s26
	ds_read_b128 v[178:181], v211 offset:49152
	ds_read_b128 v[182:185], v211 offset:50176
	ds_read_b128 v[186:189], v211 offset:51200
	ds_read_b128 v[190:193], v211 offset:52224
	ds_read_b128 v[194:197], v211 offset:53248
	ds_read_b128 v[198:201], v211 offset:54272
	ds_read_b128 v[218:221], v211 offset:55296
	ds_read_b128 v[222:225], v211 offset:56320
	global_load_lds_dwordx4 v[238:239], off
	s_add_i32 m0, s26, 0x2000
	s_add_u32 s24, s24, 0x40080
	v_lshl_add_u64 v[238:239], v[240:241], 0, s[72:73]
	s_addc_u32 s25, s25, 0
	s_add_i32 s26, s69, s31
	global_load_lds_dwordx4 v[238:239], off
	v_lshl_add_u64 v[238:239], s[24:25], 0, v[208:209]
	s_mov_b32 m0, s26
	s_nop 0
	global_load_lds_dwordx4 v[238:239], off
	v_lshl_add_u64 v[238:239], s[24:25], 0, v[156:157]
	s_add_i32 m0, s26, 0x2000
	s_nop 0
	global_load_lds_dwordx4 v[238:239], off
	v_lshl_add_u64 v[238:239], s[20:21], 0, v[160:161]
	s_mov_b32 m0, s47
	s_nop 0
	global_load_lds_dwordx4 v[238:239], off
	v_lshl_add_u64 v[238:239], s[20:21], 0, v[158:159]
	s_mov_b32 m0, s48
	s_nop 0
	global_load_lds_dwordx4 v[238:239], off
	s_waitcnt vmcnt(8)
	s_waitcnt lgkmcnt(0)
	s_barrier
	s_setprio 1
	s_waitcnt lgkmcnt(0)
	v_mfma_f32_16x16x32_bf16 v[60:63], v[132:135], v[178:181], v[60:63]
	v_mfma_f32_16x16x32_bf16 v[56:59], v[140:143], v[178:181], v[56:59]
	v_mfma_f32_16x16x32_bf16 v[40:43], v[140:143], v[186:189], v[40:43]
	v_mfma_f32_16x16x32_bf16 v[44:47], v[132:135], v[186:189], v[44:47]
	v_mfma_f32_16x16x32_bf16 v[28:31], v[132:135], v[194:197], v[28:31]
	v_mfma_f32_16x16x32_bf16 v[24:27], v[140:143], v[194:197], v[24:27]
	v_mfma_f32_16x16x32_bf16 v[8:11], v[140:143], v[218:221], v[8:11]
	v_mfma_f32_16x16x32_bf16 v[12:15], v[132:135], v[218:221], v[12:15]
	v_mfma_f32_16x16x32_bf16 v[60:63], v[136:139], v[182:185], v[60:63]
	v_mfma_f32_16x16x32_bf16 v[56:59], v[144:147], v[182:185], v[56:59]
	v_mfma_f32_16x16x32_bf16 v[40:43], v[144:147], v[190:193], v[40:43]
	v_mfma_f32_16x16x32_bf16 v[44:47], v[136:139], v[190:193], v[44:47]
	v_mfma_f32_16x16x32_bf16 v[28:31], v[136:139], v[198:201], v[28:31]
	v_mfma_f32_16x16x32_bf16 v[24:27], v[144:147], v[198:201], v[24:27]
	v_mfma_f32_16x16x32_bf16 v[8:11], v[144:147], v[222:225], v[8:11]
	v_mfma_f32_16x16x32_bf16 v[12:15], v[136:139], v[222:225], v[12:15]
	s_setprio 0
	s_setprio 1
	v_mfma_f32_16x16x32_bf16 v[52:55], v[148:151], v[178:181], v[52:55]
	v_mfma_f32_16x16x32_bf16 v[48:51], v[170:173], v[178:181], v[48:51]
	v_mfma_f32_16x16x32_bf16 v[32:35], v[170:173], v[186:189], v[32:35]
	v_mfma_f32_16x16x32_bf16 v[36:39], v[148:151], v[186:189], v[36:39]
	v_mfma_f32_16x16x32_bf16 v[20:23], v[148:151], v[194:197], v[20:23]
	v_mfma_f32_16x16x32_bf16 v[16:19], v[170:173], v[194:197], v[16:19]
	v_mfma_f32_16x16x32_bf16 v[0:3], v[170:173], v[218:221], v[0:3]
	v_mfma_f32_16x16x32_bf16 v[4:7], v[148:151], v[218:221], v[4:7]
	v_mfma_f32_16x16x32_bf16 v[52:55], v[152:155], v[182:185], v[52:55]
	v_mfma_f32_16x16x32_bf16 v[48:51], v[174:177], v[182:185], v[48:51]
	v_mfma_f32_16x16x32_bf16 v[32:35], v[174:177], v[190:193], v[32:35]
	v_mfma_f32_16x16x32_bf16 v[36:39], v[152:155], v[190:193], v[36:39]
	v_mfma_f32_16x16x32_bf16 v[20:23], v[152:155], v[198:201], v[20:23]
	v_mfma_f32_16x16x32_bf16 v[16:19], v[174:177], v[198:201], v[16:19]
	v_mfma_f32_16x16x32_bf16 v[0:3], v[174:177], v[222:225], v[0:3]
	v_mfma_f32_16x16x32_bf16 v[4:7], v[152:155], v[222:225], v[4:7]
	s_setprio 0
	s_barrier
	s_add_i32 s67, s67, 2
	s_add_u32 s18, s18, 0x100
	s_addc_u32 s19, s19, 0
	s_cmp_gt_u32 s67, 13
	s_cbranch_scc0 .LBB0_451
	s_and_b64 vcc, exec, s[16:17]
	s_cbranch_vccz .LBB0_473
	s_barrier
	s_nor_b64 s[20:21], s[36:37], s[40:41]
	s_and_saveexec_b64 s[18:19], s[20:21]
	s_cbranch_execnz .LBB0_474

;     __device__ __forceinline__ const char* tile(const Unit& u, int t) const { return A + (size_t)u.pm * 2 * hstep() + (size_t)t * (BK * 2); }
;     __device__ __forceinline__ const char* tile(const Unit& u, int t) const { return U + (long)(t >> 2) * xoff + (size_t)u.pn * (1024 * 512) + (size_t)u.pm * 2 * hstep() + (size_t)(t & 3) * (BK * 2); }
; #define PG8_STAGE(bufoff, gbase, voff) do { _Pragma("unroll") for (int _i = 0; _i < 2; ++_i) \
;         __builtin_amdgcn_global_load_lds((const unsigned*)((const char*)(gbase) + (voff)[_i]), (PG8_LAS unsigned*)(lds + (bufoff) + ldsw + _i * 8192), 16, 0, 0); } while (0)
; #define PG8_LDA(dst, b, h) do { _Pragma("unroll") for (int m = 0; m < 4; ++m) _Pragma("unroll") for (int k = 0; k < 2; ++k) dst[m][k] = *(const PG8_LAS bf16x8*)(lds + PG8_SA(b, h) + aoff + m * 2048 + k * 1024); } while (0)
; #define PG8_LDB(dst, b, h) do { _Pragma("unroll") for (int n = 0; n < 2; ++n) _Pragma("unroll") for (int k = 0; k < 2; ++k) dst[n][k] = *(const PG8_LAS bf16x8*)(lds + PG8_SB(b, h) + boff + n * 2048 + k * 1024); } while (0)
; #define PG8_MMA(ai, bj, At, Bt) do { __builtin_amdgcn_s_setprio(1); _Pragma("unroll") for (int m = 0; m < 4; ++m) _Pragma("unroll") for (int n = 0; n < 2; ++n) _Pragma("unroll") for (int k = 0; k < 2; ++k) \
;         acc[ai][bj][m][n] = __builtin_amdgcn_mfma_f32_16x16x32_bf16(Bt[n][k], At[m][k], acc[ai][bj][m][n], 0, 0, 0); __builtin_amdgcn_s_setprio(0); } while (0)
; #define PG8_WAIT_V(n) asm volatile("s_waitcnt vmcnt(" #n ")" ::: "memory")
;     ...
;             const bool last = (t == nt - 2);
;             const char* a1 = AS.tile(cur, t + 1);
;             const char* a2 = last ? AS.tile(nu, 0) : AS.tile(cur, t + 2); const char* b2 = last ? nB : cB + (size_t)(t + 2) * kstep;
;             const char* a3 = last ? AS.tile(nu, 1) : AS.tile(cur, t + 3); const char* b3 = b2 + kstep;
;             PG8_LDB(B0, 0, 0); PG8_LDB(B1, 0, 1); PG8_SCHED; PG8_LDA(At, 0, 0); PG8_STAGE(PG8_SA(1, 1), a1 + hstepA, voffA);
;             PG8_WAIT_V(8); PG8_WAIT_L(0); PG8_BAR; PG8_MMA(0, 0, At, B0); PG8_MMA(0, 1, At, B1); PG8_BAR; PG8_SCHED;
;             PG8_LDA(At, 0, 1); PG8_STAGE(PG8_SB(0, 0), b2, voffB); PG8_STAGE(PG8_SB(0, 1), b2 + hstepB, voffB); PG8_STAGE(PG8_SA(0, 0), a2, voffA);
;             PG8_WAIT_V(8); PG8_WAIT_L(0); PG8_BAR; PG8_MMA(1, 0, At, B0); PG8_MMA(1, 1, At, B1); PG8_BAR; PG8_SCHED;
.LBB0_504:
	s_add_u32 s14, s52, s12
	s_addc_u32 s15, s53, s13
	s_add_u32 s18, s14, 0x400100
	s_addc_u32 s19, s15, 0
	s_add_u32 s16, s54, s12
	s_addc_u32 s17, s55, s13
	s_add_u32 s14, s14, 0x400180
	s_addc_u32 s15, s15, 0
	s_add_i32 s57, 0, 0x10000
	s_add_i32 s60, 0, 0x14000
	v_add_u32_e32 v146, s57, v149
	ds_read_b128 v[156:159], v146
	ds_read_b128 v[160:163], v146 offset:1024
	ds_read_b128 v[164:167], v146 offset:2048
	ds_read_b128 v[168:171], v146 offset:3072
	v_add_u32_e32 v146, s60, v149
	ds_read_b128 v[172:175], v146
	ds_read_b128 v[176:179], v146 offset:1024
	ds_read_b128 v[180:183], v146 offset:2048
	ds_read_b128 v[184:187], v146 offset:3072
	s_cmpk_eq_i32 s12, 0x700
	s_cselect_b32 s15, s51, s15
	s_cselect_b32 s14, s50, s14
	s_cselect_b32 s17, s48, s17
	s_cselect_b32 s16, s47, s16
	s_cselect_b32 s19, s49, s19
	s_cselect_b32 s18, s11, s18
	v_lshl_add_u64 v[146:147], v[142:143], 0, s[12:13]
	s_add_i32 m0, s26, 0xc000
	ds_read_b128 v[188:191], v152
	ds_read_b128 v[192:195], v152 offset:1024
	ds_read_b128 v[196:199], v152 offset:2048
	ds_read_b128 v[200:203], v152 offset:3072
	ds_read_b128 v[204:207], v152 offset:4096
	ds_read_b128 v[218:221], v152 offset:5120
	ds_read_b128 v[222:225], v152 offset:6144
	ds_read_b128 v[238:241], v152 offset:7168
	global_load_lds_dwordx4 v[146:147], off
	v_lshl_add_u64 v[146:147], v[144:145], 0, s[12:13]
	s_add_i32 m0, s26, 0xe000
	s_nop 0
	global_load_lds_dwordx4 v[146:147], off
	s_waitcnt vmcnt(8)
	s_waitcnt lgkmcnt(0)
	s_barrier
	s_setprio 1
	s_waitcnt lgkmcnt(0)
	v_mfma_f32_16x16x32_bf16 v[124:127], v[156:159], v[188:191], v[124:127]
	v_mfma_f32_16x16x32_bf16 v[120:123], v[164:167], v[188:191], v[120:123]
	v_mfma_f32_16x16x32_bf16 v[104:107], v[164:167], v[196:199], v[104:107]
	v_mfma_f32_16x16x32_bf16 v[108:111], v[156:159], v[196:199], v[108:111]
	v_mfma_f32_16x16x32_bf16 v[92:95], v[156:159], v[204:207], v[92:95]
	v_mfma_f32_16x16x32_bf16 v[88:91], v[164:167], v[204:207], v[88:91]
	v_mfma_f32_16x16x32_bf16 v[72:75], v[164:167], v[222:225], v[72:75]
	v_mfma_f32_16x16x32_bf16 v[76:79], v[156:159], v[222:225], v[76:79]
	v_mfma_f32_16x16x32_bf16 v[124:127], v[160:163], v[192:195], v[124:127]
	v_mfma_f32_16x16x32_bf16 v[120:123], v[168:171], v[192:195], v[120:123]
	v_mfma_f32_16x16x32_bf16 v[104:107], v[168:171], v[200:203], v[104:107]
	v_mfma_f32_16x16x32_bf16 v[108:111], v[160:163], v[200:203], v[108:111]
	v_mfma_f32_16x16x32_bf16 v[92:95], v[160:163], v[218:221], v[92:95]
	v_mfma_f32_16x16x32_bf16 v[88:91], v[168:171], v[218:221], v[88:91]
	v_mfma_f32_16x16x32_bf16 v[72:75], v[168:171], v[238:241], v[72:75]
	v_mfma_f32_16x16x32_bf16 v[76:79], v[160:163], v[238:241], v[76:79]
	s_setprio 0
	s_setprio 1
	v_mfma_f32_16x16x32_bf16 v[116:119], v[172:175], v[188:191], v[116:119]
	v_mfma_f32_16x16x32_bf16 v[112:115], v[180:183], v[188:191], v[112:115]
	v_mfma_f32_16x16x32_bf16 v[96:99], v[180:183], v[196:199], v[96:99]
	v_mfma_f32_16x16x32_bf16 v[100:103], v[172:175], v[196:199], v[100:103]
	v_mfma_f32_16x16x32_bf16 v[84:87], v[172:175], v[204:207], v[84:87]
	v_mfma_f32_16x16x32_bf16 v[80:83], v[180:183], v[204:207], v[80:83]
	v_mfma_f32_16x16x32_bf16 v[64:67], v[180:183], v[222:225], v[64:67]
	v_mfma_f32_16x16x32_bf16 v[68:71], v[172:175], v[222:225], v[68:71]
	v_mfma_f32_16x16x32_bf16 v[116:119], v[176:179], v[192:195], v[116:119]
	v_mfma_f32_16x16x32_bf16 v[112:115], v[184:187], v[192:195], v[112:115]
	v_mfma_f32_16x16x32_bf16 v[96:99], v[184:187], v[200:203], v[96:99]
	v_mfma_f32_16x16x32_bf16 v[100:103], v[176:179], v[200:203], v[100:103]
	v_mfma_f32_16x16x32_bf16 v[84:87], v[176:179], v[218:221], v[84:87]
	v_mfma_f32_16x16x32_bf16 v[80:83], v[184:187], v[218:221], v[80:83]
	v_mfma_f32_16x16x32_bf16 v[64:67], v[184:187], v[238:241], v[64:67]
	v_mfma_f32_16x16x32_bf16 v[68:71], v[176:179], v[238:241], v[68:71]
	s_setprio 0
	s_barrier
	s_add_i32 s57, s57, s25
	v_lshl_add_u64 v[146:147], s[16:17], 0, v[208:209]
	s_mov_b32 m0, s57
	ds_read_b128 v[188:191], v152 offset:16384
	ds_read_b128 v[192:195], v152 offset:17408
	ds_read_b128 v[196:199], v152 offset:18432
	ds_read_b128 v[200:203], v152 offset:19456
	ds_read_b128 v[204:207], v152 offset:20480
	ds_read_b128 v[218:221], v152 offset:21504
	ds_read_b128 v[222:225], v152 offset:22528
	ds_read_b128 v[238:241], v152 offset:23552
	global_load_lds_dwordx4 v[146:147], off
	s_add_i32 m0, s57, 0x2000
	s_add_u32 s58, s16, 0x40000
	v_lshl_add_u64 v[242:243], s[16:17], 0, v[128:129]
	s_addc_u32 s59, s17, 0
	s_add_i32 s57, s60, s25
	global_load_lds_dwordx4 v[242:243], off
	v_lshl_add_u64 v[244:245], s[58:59], 0, v[208:209]
	s_mov_b32 m0, s57
	s_nop 0
	global_load_lds_dwordx4 v[244:245], off
	v_lshl_add_u64 v[244:245], s[58:59], 0, v[128:129]
	s_add_i32 m0, s57, 0x2000
	s_nop 0
	global_load_lds_dwordx4 v[244:245], off
	v_lshl_add_u64 v[244:245], s[18:19], 0, v[132:133]
	s_mov_b32 m0, s26
	s_nop 0
	global_load_lds_dwordx4 v[244:245], off
	v_lshl_add_u64 v[244:245], s[18:19], 0, v[130:131]
	s_mov_b32 m0, s27
	s_nop 0
	global_load_lds_dwordx4 v[244:245], off
	s_waitcnt vmcnt(8)
	s_waitcnt lgkmcnt(0)
	s_barrier
; #define PG8_STAGE(bufoff, gbase, voff) do { _Pragma("unroll") for (int _i = 0; _i < 2; ++_i) \
;         __builtin_amdgcn_global_load_lds((const unsigned*)((const char*)(gbase) + (voff)[_i]), (PG8_LAS unsigned*)(lds + (bufoff) + ldsw + _i * 8192), 16, 0, 0); } while (0)
; #define PG8_LDA(dst, b, h) do { _Pragma("unroll") for (int m = 0; m < 4; ++m) _Pragma("unroll") for (int k = 0; k < 2; ++k) dst[m][k] = *(const PG8_LAS bf16x8*)(lds + PG8_SA(b, h) + aoff + m * 2048 + k * 1024); } while (0)
; #define PG8_LDB(dst, b, h) do { _Pragma("unroll") for (int n = 0; n < 2; ++n) _Pragma("unroll") for (int k = 0; k < 2; ++k) dst[n][k] = *(const PG8_LAS bf16x8*)(lds + PG8_SB(b, h) + boff + n * 2048 + k * 1024); } while (0)
; #define PG8_MMA(ai, bj, At, Bt) do { __builtin_amdgcn_s_setprio(1); _Pragma("unroll") for (int m = 0; m < 4; ++m) _Pragma("unroll") for (int n = 0; n < 2; ++n) _Pragma("unroll") for (int k = 0; k < 2; ++k) \
;         acc[ai][bj][m][n] = __builtin_amdgcn_mfma_f32_16x16x32_bf16(Bt[n][k], At[m][k], acc[ai][bj][m][n], 0, 0, 0); __builtin_amdgcn_s_setprio(0); } while (0)
; #define PG8_WAIT_V(n) asm volatile("s_waitcnt vmcnt(" #n ")" ::: "memory")
; #define PG8_WAIT_L(n) asm volatile("s_waitcnt lgkmcnt(" #n ")" ::: "memory")
; #define PG8_BAR __builtin_amdgcn_s_barrier()
; #define PG8_SCHED __builtin_amdgcn_sched_barrier(0)
;     ...
;             PG8_WAIT_V(8); PG8_WAIT_L(0); PG8_BAR; PG8_MMA(1, 0, At, B0); PG8_MMA(1, 1, At, B1); PG8_BAR; PG8_SCHED;
;             PG8_LDB(B0, 1, 0); PG8_LDB(B1, 1, 1); PG8_SCHED; PG8_LDA(At, 1, 0); PG8_STAGE(PG8_SA(0, 1), a2 + hstepA, voffA);
;             PG8_WAIT_V(8); PG8_WAIT_L(0); PG8_BAR; PG8_MMA(0, 0, At, B0); PG8_MMA(0, 1, At, B1); PG8_BAR; PG8_SCHED;
	s_setprio 1
	s_waitcnt lgkmcnt(0)
	v_mfma_f32_16x16x32_bf16 v[60:63], v[156:159], v[188:191], v[60:63]
	v_mfma_f32_16x16x32_bf16 v[56:59], v[164:167], v[188:191], v[56:59]
	v_mfma_f32_16x16x32_bf16 v[40:43], v[164:167], v[196:199], v[40:43]
	v_mfma_f32_16x16x32_bf16 v[44:47], v[156:159], v[196:199], v[44:47]
	v_mfma_f32_16x16x32_bf16 v[28:31], v[156:159], v[204:207], v[28:31]
	v_mfma_f32_16x16x32_bf16 v[24:27], v[164:167], v[204:207], v[24:27]
	v_mfma_f32_16x16x32_bf16 v[8:11], v[164:167], v[222:225], v[8:11]
	v_mfma_f32_16x16x32_bf16 v[12:15], v[156:159], v[222:225], v[12:15]
	v_mfma_f32_16x16x32_bf16 v[60:63], v[160:163], v[192:195], v[60:63]
	v_mfma_f32_16x16x32_bf16 v[56:59], v[168:171], v[192:195], v[56:59]
	v_mfma_f32_16x16x32_bf16 v[40:43], v[168:171], v[200:203], v[40:43]
	v_mfma_f32_16x16x32_bf16 v[44:47], v[160:163], v[200:203], v[44:47]
	v_mfma_f32_16x16x32_bf16 v[28:31], v[160:163], v[218:221], v[28:31]
	v_mfma_f32_16x16x32_bf16 v[24:27], v[168:171], v[218:221], v[24:27]
	v_mfma_f32_16x16x32_bf16 v[8:11], v[168:171], v[238:241], v[8:11]
	v_mfma_f32_16x16x32_bf16 v[12:15], v[160:163], v[238:241], v[12:15]
	s_setprio 0
	s_setprio 1
	v_mfma_f32_16x16x32_bf16 v[52:55], v[172:175], v[188:191], v[52:55]
	v_mfma_f32_16x16x32_bf16 v[48:51], v[180:183], v[188:191], v[48:51]
	v_mfma_f32_16x16x32_bf16 v[32:35], v[180:183], v[196:199], v[32:35]
	v_mfma_f32_16x16x32_bf16 v[36:39], v[172:175], v[196:199], v[36:39]
	v_mfma_f32_16x16x32_bf16 v[20:23], v[172:175], v[204:207], v[20:23]
	v_mfma_f32_16x16x32_bf16 v[16:19], v[180:183], v[204:207], v[16:19]
	v_mfma_f32_16x16x32_bf16 v[0:3], v[180:183], v[222:225], v[0:3]
	v_mfma_f32_16x16x32_bf16 v[4:7], v[172:175], v[222:225], v[4:7]
	v_mfma_f32_16x16x32_bf16 v[52:55], v[176:179], v[192:195], v[52:55]
	v_mfma_f32_16x16x32_bf16 v[48:51], v[184:187], v[192:195], v[48:51]
	v_mfma_f32_16x16x32_bf16 v[32:35], v[184:187], v[200:203], v[32:35]
	v_mfma_f32_16x16x32_bf16 v[36:39], v[176:179], v[200:203], v[36:39]
	v_mfma_f32_16x16x32_bf16 v[20:23], v[176:179], v[218:221], v[20:23]
	v_mfma_f32_16x16x32_bf16 v[16:19], v[184:187], v[218:221], v[16:19]
	v_mfma_f32_16x16x32_bf16 v[0:3], v[184:187], v[238:241], v[0:3]
	v_mfma_f32_16x16x32_bf16 v[4:7], v[176:179], v[238:241], v[4:7]
	s_setprio 0
	s_barrier
	s_add_i32 s57, 0, 0x18000
	v_add_u32_e32 v155, s57, v149
	s_add_i32 s58, 0, 0x1c000
	ds_read_b128 v[156:159], v155
	ds_read_b128 v[160:163], v155 offset:1024
	ds_read_b128 v[164:167], v155 offset:2048
	ds_read_b128 v[168:171], v155 offset:3072
	v_add_u32_e32 v155, s58, v149
	ds_read_b128 v[172:175], v155
	ds_read_b128 v[176:179], v155 offset:1024
	ds_read_b128 v[180:183], v155 offset:2048
	ds_read_b128 v[184:187], v155 offset:3072
	s_add_u32 s18, s18, 0x40000
	s_addc_u32 s19, s19, 0
	s_mov_b32 m0, s28
	v_lshl_add_u64 v[244:245], s[18:19], 0, v[132:133]
	ds_read_b128 v[188:191], v152 offset:32768
	ds_read_b128 v[192:195], v152 offset:33792
	ds_read_b128 v[196:199], v152 offset:34816
	ds_read_b128 v[200:203], v152 offset:35840
	ds_read_b128 v[204:207], v152 offset:36864
	ds_read_b128 v[218:221], v152 offset:37888
	ds_read_b128 v[222:225], v152 offset:38912
	ds_read_b128 v[238:241], v152 offset:39936
	global_load_lds_dwordx4 v[244:245], off
	v_lshl_add_u64 v[244:245], s[18:19], 0, v[130:131]
	s_mov_b32 m0, s29
	s_nop 0
	global_load_lds_dwordx4 v[244:245], off
	s_waitcnt vmcnt(8)
	s_waitcnt lgkmcnt(0)
	s_barrier
	s_setprio 1
	s_waitcnt lgkmcnt(0)
	v_mfma_f32_16x16x32_bf16 v[124:127], v[156:159], v[188:191], v[124:127]
	v_mfma_f32_16x16x32_bf16 v[120:123], v[164:167], v[188:191], v[120:123]
	v_mfma_f32_16x16x32_bf16 v[104:107], v[164:167], v[196:199], v[104:107]
	v_mfma_f32_16x16x32_bf16 v[108:111], v[156:159], v[196:199], v[108:111]
	v_mfma_f32_16x16x32_bf16 v[92:95], v[156:159], v[204:207], v[92:95]
	v_mfma_f32_16x16x32_bf16 v[88:91], v[164:167], v[204:207], v[88:91]
	v_mfma_f32_16x16x32_bf16 v[72:75], v[164:167], v[222:225], v[72:75]
	v_mfma_f32_16x16x32_bf16 v[76:79], v[156:159], v[222:225], v[76:79]
	v_mfma_f32_16x16x32_bf16 v[124:127], v[160:163], v[192:195], v[124:127]
	v_mfma_f32_16x16x32_bf16 v[120:123], v[168:171], v[192:195], v[120:123]
	v_mfma_f32_16x16x32_bf16 v[104:107], v[168:171], v[200:203], v[104:107]
	v_mfma_f32_16x16x32_bf16 v[108:111], v[160:163], v[200:203], v[108:111]
	v_mfma_f32_16x16x32_bf16 v[92:95], v[160:163], v[218:221], v[92:95]
	v_mfma_f32_16x16x32_bf16 v[88:91], v[168:171], v[218:221], v[88:91]
	v_mfma_f32_16x16x32_bf16 v[72:75], v[168:171], v[238:241], v[72:75]
	v_mfma_f32_16x16x32_bf16 v[76:79], v[160:163], v[238:241], v[76:79]
	s_setprio 0
	s_setprio 1
	v_mfma_f32_16x16x32_bf16 v[116:119], v[172:175], v[188:191], v[116:119]
	v_mfma_f32_16x16x32_bf16 v[112:115], v[180:183], v[188:191], v[112:115]
	v_mfma_f32_16x16x32_bf16 v[96:99], v[180:183], v[196:199], v[96:99]
	v_mfma_f32_16x16x32_bf16 v[100:103], v[172:175], v[196:199], v[100:103]
	v_mfma_f32_16x16x32_bf16 v[84:87], v[172:175], v[204:207], v[84:87]
	v_mfma_f32_16x16x32_bf16 v[80:83], v[180:183], v[204:207], v[80:83]
	v_mfma_f32_16x16x32_bf16 v[64:67], v[180:183], v[222:225], v[64:67]
	v_mfma_f32_16x16x32_bf16 v[68:71], v[172:175], v[222:225], v[68:71]
	v_mfma_f32_16x16x32_bf16 v[116:119], v[176:179], v[192:195], v[116:119]
	v_mfma_f32_16x16x32_bf16 v[112:115], v[184:187], v[192:195], v[112:115]
	v_mfma_f32_16x16x32_bf16 v[96:99], v[184:187], v[200:203], v[96:99]
	v_mfma_f32_16x16x32_bf16 v[100:103], v[176:179], v[200:203], v[100:103]
	v_mfma_f32_16x16x32_bf16 v[84:87], v[176:179], v[218:221], v[84:87]
	v_mfma_f32_16x16x32_bf16 v[80:83], v[184:187], v[218:221], v[80:83]
	v_mfma_f32_16x16x32_bf16 v[64:67], v[184:187], v[238:241], v[64:67]
	v_mfma_f32_16x16x32_bf16 v[68:71], v[176:179], v[238:241], v[68:71]
	s_setprio 0
	s_barrier
; #define PG8_STAGE(bufoff, gbase, voff) do { _Pragma("unroll") for (int _i = 0; _i < 2; ++_i) \
;         __builtin_amdgcn_global_load_lds((const unsigned*)((const char*)(gbase) + (voff)[_i]), (PG8_LAS unsigned*)(lds + (bufoff) + ldsw + _i * 8192), 16, 0, 0); } while (0)
; #define PG8_LDA(dst, b, h) do { _Pragma("unroll") for (int m = 0; m < 4; ++m) _Pragma("unroll") for (int k = 0; k < 2; ++k) dst[m][k] = *(const PG8_LAS bf16x8*)(lds + PG8_SA(b, h) + aoff + m * 2048 + k * 1024); } while (0)
; #define PG8_MMA(ai, bj, At, Bt) do { __builtin_amdgcn_s_setprio(1); _Pragma("unroll") for (int m = 0; m < 4; ++m) _Pragma("unroll") for (int n = 0; n < 2; ++n) _Pragma("unroll") for (int k = 0; k < 2; ++k) \
;         acc[ai][bj][m][n] = __builtin_amdgcn_mfma_f32_16x16x32_bf16(Bt[n][k], At[m][k], acc[ai][bj][m][n], 0, 0, 0); __builtin_amdgcn_s_setprio(0); } while (0)
; #define PG8_WAIT_V(n) asm volatile("s_waitcnt vmcnt(" #n ")" ::: "memory")
; #define PG8_WAIT_L(n) asm volatile("s_waitcnt lgkmcnt(" #n ")" ::: "memory")
; #define PG8_BAR __builtin_amdgcn_s_barrier()
; #define PG8_SCHED __builtin_amdgcn_sched_barrier(0)
;     ...
;             PG8_LDA(At, 1, 1); PG8_STAGE(PG8_SB(1, 0), b3, voffB); PG8_STAGE(PG8_SB(1, 1), b3 + hstepB, voffB); PG8_STAGE(PG8_SA(1, 0), a3, voffA);
;             PG8_WAIT_V(8); PG8_WAIT_L(0); PG8_BAR; PG8_MMA(1, 0, At, B0); PG8_MMA(1, 1, At, B1); PG8_BAR; PG8_SCHED;
;         }
;         if (wr == 0) PG8_BAR;
;         if (!has_next && wmat && gtid * 128u < wbytes) asm volatile("global_load_dword %0, %1, off" : "+v"(warmm) : "v"(wmat + (size_t)gtid * 128u) : "memory");
	s_add_i32 s18, s57, s25
	v_lshl_add_u64 v[146:147], v[146:147], 0, s[64:65]
	s_mov_b32 m0, s18
	ds_read_b128 v[188:191], v152 offset:49152
	ds_read_b128 v[192:195], v152 offset:50176
	ds_read_b128 v[196:199], v152 offset:51200
	ds_read_b128 v[200:203], v152 offset:52224
	ds_read_b128 v[204:207], v152 offset:53248
	ds_read_b128 v[218:221], v152 offset:54272
	ds_read_b128 v[222:225], v152 offset:55296
	ds_read_b128 v[238:241], v152 offset:56320
	global_load_lds_dwordx4 v[146:147], off
	s_add_i32 m0, s18, 0x2000
	s_add_u32 s16, s16, 0x40080
	v_lshl_add_u64 v[146:147], v[242:243], 0, s[64:65]
	s_addc_u32 s17, s17, 0
	s_add_i32 s18, s58, s25
	global_load_lds_dwordx4 v[146:147], off
	v_lshl_add_u64 v[146:147], s[16:17], 0, v[208:209]
	s_mov_b32 m0, s18
	s_nop 0
	global_load_lds_dwordx4 v[146:147], off
	v_lshl_add_u64 v[146:147], s[16:17], 0, v[128:129]
	s_add_i32 m0, s18, 0x2000
	s_nop 0
	global_load_lds_dwordx4 v[146:147], off
	v_lshl_add_u64 v[146:147], s[14:15], 0, v[132:133]
	s_mov_b32 m0, s30
	s_nop 0
	global_load_lds_dwordx4 v[146:147], off
	v_lshl_add_u64 v[146:147], s[14:15], 0, v[130:131]
	s_mov_b32 m0, s31
	s_nop 0
	global_load_lds_dwordx4 v[146:147], off
	s_waitcnt vmcnt(8)
	s_waitcnt lgkmcnt(0)
	s_barrier
	s_setprio 1
	s_waitcnt lgkmcnt(0)
	v_mfma_f32_16x16x32_bf16 v[60:63], v[156:159], v[188:191], v[60:63]
	v_mfma_f32_16x16x32_bf16 v[56:59], v[164:167], v[188:191], v[56:59]
	v_mfma_f32_16x16x32_bf16 v[40:43], v[164:167], v[196:199], v[40:43]
	v_mfma_f32_16x16x32_bf16 v[44:47], v[156:159], v[196:199], v[44:47]
	v_mfma_f32_16x16x32_bf16 v[28:31], v[156:159], v[204:207], v[28:31]
	v_mfma_f32_16x16x32_bf16 v[24:27], v[164:167], v[204:207], v[24:27]
	v_mfma_f32_16x16x32_bf16 v[8:11], v[164:167], v[222:225], v[8:11]
	v_mfma_f32_16x16x32_bf16 v[12:15], v[156:159], v[222:225], v[12:15]
	v_mfma_f32_16x16x32_bf16 v[60:63], v[160:163], v[192:195], v[60:63]
	v_mfma_f32_16x16x32_bf16 v[56:59], v[168:171], v[192:195], v[56:59]
	v_mfma_f32_16x16x32_bf16 v[40:43], v[168:171], v[200:203], v[40:43]
	v_mfma_f32_16x16x32_bf16 v[44:47], v[160:163], v[200:203], v[44:47]
	v_mfma_f32_16x16x32_bf16 v[28:31], v[160:163], v[218:221], v[28:31]
	v_mfma_f32_16x16x32_bf16 v[24:27], v[168:171], v[218:221], v[24:27]
	v_mfma_f32_16x16x32_bf16 v[8:11], v[168:171], v[238:241], v[8:11]
	v_mfma_f32_16x16x32_bf16 v[12:15], v[160:163], v[238:241], v[12:15]
	s_setprio 0
	s_setprio 1
	v_mfma_f32_16x16x32_bf16 v[52:55], v[172:175], v[188:191], v[52:55]
	v_mfma_f32_16x16x32_bf16 v[48:51], v[180:183], v[188:191], v[48:51]
	v_mfma_f32_16x16x32_bf16 v[32:35], v[180:183], v[196:199], v[32:35]
	v_mfma_f32_16x16x32_bf16 v[36:39], v[172:175], v[196:199], v[36:39]
	v_mfma_f32_16x16x32_bf16 v[20:23], v[172:175], v[204:207], v[20:23]
	v_mfma_f32_16x16x32_bf16 v[16:19], v[180:183], v[204:207], v[16:19]
	v_mfma_f32_16x16x32_bf16 v[0:3], v[180:183], v[222:225], v[0:3]
	v_mfma_f32_16x16x32_bf16 v[4:7], v[172:175], v[222:225], v[4:7]
	v_mfma_f32_16x16x32_bf16 v[52:55], v[176:179], v[192:195], v[52:55]
	v_mfma_f32_16x16x32_bf16 v[48:51], v[184:187], v[192:195], v[48:51]
	v_mfma_f32_16x16x32_bf16 v[32:35], v[184:187], v[200:203], v[32:35]
	v_mfma_f32_16x16x32_bf16 v[36:39], v[176:179], v[200:203], v[36:39]
	v_mfma_f32_16x16x32_bf16 v[20:23], v[176:179], v[218:221], v[20:23]
	v_mfma_f32_16x16x32_bf16 v[16:19], v[184:187], v[218:221], v[16:19]
	v_mfma_f32_16x16x32_bf16 v[0:3], v[184:187], v[238:241], v[0:3]
	v_mfma_f32_16x16x32_bf16 v[4:7], v[176:179], v[238:241], v[4:7]
	s_setprio 0
	s_barrier
	s_add_i32 s56, s56, 2
	s_add_u32 s12, s12, 0x100
	s_addc_u32 s13, s13, 0
	s_cmp_gt_u32 s56, 13
	s_cbranch_scc0 .LBB0_504
	s_and_b64 vcc, exec, s[6:7]
	s_cbranch_vccz .LBB0_515
	s_barrier
	s_nor_b64 s[14:15], s[36:37], s[38:39]
	s_and_saveexec_b64 s[12:13], s[14:15]
	s_cbranch_execnz .LBB0_516

;     __device__ __forceinline__ const char* tile(const Unit& u, int t) const { return A + (size_t)u.pm * 2 * hstep() + (size_t)t * (BK * 2); }
;     __device__ __forceinline__ const char* tile(const Unit& u, int t) const { return U + (long)(t >> 2) * xoff + (size_t)u.pn * (1024 * 512) + (size_t)u.pm * 2 * hstep() + (size_t)(t & 3) * (BK * 2); }
; #define PG8_STAGE(bufoff, gbase, voff) do { _Pragma("unroll") for (int _i = 0; _i < 2; ++_i) \
;         __builtin_amdgcn_global_load_lds((const unsigned*)((const char*)(gbase) + (voff)[_i]), (PG8_LAS unsigned*)(lds + (bufoff) + ldsw + _i * 8192), 16, 0, 0); } while (0)
; #define PG8_LDA(dst, b, h) do { _Pragma("unroll") for (int m = 0; m < 4; ++m) _Pragma("unroll") for (int k = 0; k < 2; ++k) dst[m][k] = *(const PG8_LAS bf16x8*)(lds + PG8_SA(b, h) + aoff + m * 2048 + k * 1024); } while (0)
; #define PG8_LDB(dst, b, h) do { _Pragma("unroll") for (int n = 0; n < 2; ++n) _Pragma("unroll") for (int k = 0; k < 2; ++k) dst[n][k] = *(const PG8_LAS bf16x8*)(lds + PG8_SB(b, h) + boff + n * 2048 + k * 1024); } while (0)
; #define PG8_MMA(ai, bj, At, Bt) do { __builtin_amdgcn_s_setprio(1); _Pragma("unroll") for (int m = 0; m < 4; ++m) _Pragma("unroll") for (int n = 0; n < 2; ++n) _Pragma("unroll") for (int k = 0; k < 2; ++k) \
;         acc[ai][bj][m][n] = __builtin_amdgcn_mfma_f32_16x16x32_bf16(Bt[n][k], At[m][k], acc[ai][bj][m][n], 0, 0, 0); __builtin_amdgcn_s_setprio(0); } while (0)
; #define PG8_WAIT_V(n) asm volatile("s_waitcnt vmcnt(" #n ")" ::: "memory")
;     ...
;             const bool last = (t == nt - 2);
;             const char* a1 = AS.tile(cur, t + 1);
;             const char* a2 = last ? AS.tile(nu, 0) : AS.tile(cur, t + 2); const char* b2 = last ? nB : cB + (size_t)(t + 2) * kstep;
;             const char* a3 = last ? AS.tile(nu, 1) : AS.tile(cur, t + 3); const char* b3 = b2 + kstep;
;             PG8_LDB(B0, 0, 0); PG8_LDB(B1, 0, 1); PG8_SCHED; PG8_LDA(At, 0, 0); PG8_STAGE(PG8_SA(1, 1), a1 + hstepA, voffA);
;             PG8_WAIT_V(8); PG8_WAIT_L(0); PG8_BAR; PG8_MMA(0, 0, At, B0); PG8_MMA(0, 1, At, B1); PG8_BAR; PG8_SCHED;
;             PG8_LDA(At, 0, 1); PG8_STAGE(PG8_SB(0, 0), b2, voffB); PG8_STAGE(PG8_SB(0, 1), b2 + hstepB, voffB); PG8_STAGE(PG8_SA(0, 0), a2, voffA);
;             PG8_WAIT_V(8); PG8_WAIT_L(0); PG8_BAR; PG8_MMA(1, 0, At, B0); PG8_MMA(1, 1, At, B1); PG8_BAR; PG8_SCHED;
.LBB0_534:
	s_add_i32 s68, s2, 2
	s_add_u32 s3, s82, s64
	s_addc_u32 s20, s83, s65
	s_add_u32 s69, s3, 0x100
	s_addc_u32 s21, s20, 0
	s_add_u32 s70, s82, s66
	s_addc_u32 s71, s83, s67
	s_add_u32 s72, s3, 0x180
	s_addc_u32 s3, s20, 0
	s_add_i32 s73, 0, 0x10000
	s_add_i32 s74, 0, 0x14000
	v_add_u32_e32 v108, s73, v212
	v_add_u32_e32 v152, s74, v212
	ds_read_b128 v[76:79], v108
	ds_read_b128 v[88:91], v108 offset:1024
	ds_read_b128 v[100:103], v108 offset:2048
	ds_read_b128 v[108:111], v108 offset:3072
	ds_read_b128 v[124:127], v152
	ds_read_b128 v[128:131], v152 offset:1024
	ds_read_b128 v[144:147], v152 offset:2048
	ds_read_b128 v[152:155], v152 offset:3072
	s_cmp_eq_u32 s51, s2
	s_cselect_b32 s2, s60, s72
	s_cselect_b32 s3, s61, s3
	s_cselect_b32 s71, s41, s71
	s_cselect_b32 s70, s40, s70
	s_cselect_b32 s21, s59, s21
	s_cselect_b32 s20, s1, s69
	v_lshl_add_u64 v[222:223], s[82:83], 0, v[64:65]
	s_add_i32 m0, s35, 0xc000
	ds_read_b128 v[156:159], v241
	ds_read_b128 v[168:171], v241 offset:1024
	ds_read_b128 v[172:175], v241 offset:2048
	ds_read_b128 v[176:179], v241 offset:3072
	ds_read_b128 v[180:183], v241 offset:4096
	ds_read_b128 v[184:187], v241 offset:5120
	ds_read_b128 v[188:191], v241 offset:6144
	ds_read_b128 v[218:221], v241 offset:7168
	global_load_lds_dwordx4 v[222:223], off
	v_lshl_add_u64 v[222:223], s[82:83], 0, v[66:67]
	s_add_i32 m0, s35, 0xe000
	s_nop 0
	global_load_lds_dwordx4 v[222:223], off
	s_waitcnt vmcnt(8)
	s_waitcnt lgkmcnt(0)
	s_barrier
	s_setprio 1
	s_waitcnt lgkmcnt(0)
	v_mfma_f32_16x16x32_bf16 v[164:167], v[76:79], v[156:159], v[164:167]
	v_mfma_f32_16x16x32_bf16 v[160:163], v[100:103], v[156:159], v[160:163]
	v_mfma_f32_16x16x32_bf16 v[132:135], v[100:103], v[172:175], v[132:135]
	v_mfma_f32_16x16x32_bf16 v[136:139], v[76:79], v[172:175], v[136:139]
	v_mfma_f32_16x16x32_bf16 v[112:115], v[76:79], v[180:183], v[112:115]
	v_mfma_f32_16x16x32_bf16 v[104:107], v[100:103], v[180:183], v[104:107]
	v_mfma_f32_16x16x32_bf16 v[80:83], v[100:103], v[188:191], v[80:83]
	v_mfma_f32_16x16x32_bf16 v[84:87], v[76:79], v[188:191], v[84:87]
	v_mfma_f32_16x16x32_bf16 v[164:167], v[88:91], v[168:171], v[164:167]
	v_mfma_f32_16x16x32_bf16 v[160:163], v[108:111], v[168:171], v[160:163]
	v_mfma_f32_16x16x32_bf16 v[132:135], v[108:111], v[176:179], v[132:135]
	v_mfma_f32_16x16x32_bf16 v[136:139], v[88:91], v[176:179], v[136:139]
	v_mfma_f32_16x16x32_bf16 v[112:115], v[88:91], v[184:187], v[112:115]
	v_mfma_f32_16x16x32_bf16 v[104:107], v[108:111], v[184:187], v[104:107]
	v_mfma_f32_16x16x32_bf16 v[80:83], v[108:111], v[218:221], v[80:83]
	v_mfma_f32_16x16x32_bf16 v[84:87], v[88:91], v[218:221], v[84:87]
	s_setprio 0
	s_setprio 1
	v_mfma_f32_16x16x32_bf16 v[148:151], v[124:127], v[156:159], v[148:151]
	v_mfma_f32_16x16x32_bf16 v[140:143], v[144:147], v[156:159], v[140:143]
	v_mfma_f32_16x16x32_bf16 v[116:119], v[144:147], v[172:175], v[116:119]
	v_mfma_f32_16x16x32_bf16 v[120:123], v[124:127], v[172:175], v[120:123]
	v_mfma_f32_16x16x32_bf16 v[96:99], v[124:127], v[180:183], v[96:99]
	v_mfma_f32_16x16x32_bf16 v[92:95], v[144:147], v[180:183], v[92:95]
	v_mfma_f32_16x16x32_bf16 v[68:71], v[144:147], v[188:191], v[68:71]
	v_mfma_f32_16x16x32_bf16 v[72:75], v[124:127], v[188:191], v[72:75]
	v_mfma_f32_16x16x32_bf16 v[148:151], v[128:131], v[168:171], v[148:151]
	v_mfma_f32_16x16x32_bf16 v[140:143], v[152:155], v[168:171], v[140:143]
	v_mfma_f32_16x16x32_bf16 v[116:119], v[152:155], v[176:179], v[116:119]
	v_mfma_f32_16x16x32_bf16 v[120:123], v[128:131], v[176:179], v[120:123]
	v_mfma_f32_16x16x32_bf16 v[96:99], v[128:131], v[184:187], v[96:99]
	v_mfma_f32_16x16x32_bf16 v[92:95], v[152:155], v[184:187], v[92:95]
	v_mfma_f32_16x16x32_bf16 v[68:71], v[152:155], v[218:221], v[68:71]
	v_mfma_f32_16x16x32_bf16 v[72:75], v[128:131], v[218:221], v[72:75]
	s_setprio 0
	s_barrier
	s_add_i32 s69, s73, s25
	v_lshl_add_u64 v[222:223], s[70:71], 0, v[196:197]
	s_mov_b32 m0, s69
	ds_read_b128 v[156:159], v241 offset:16384
	ds_read_b128 v[168:171], v241 offset:17408
	ds_read_b128 v[172:175], v241 offset:18432
	ds_read_b128 v[176:179], v241 offset:19456
	ds_read_b128 v[180:183], v241 offset:20480
	ds_read_b128 v[184:187], v241 offset:21504
	ds_read_b128 v[188:191], v241 offset:22528
	ds_read_b128 v[218:221], v241 offset:23552
	global_load_lds_dwordx4 v[222:223], off
	s_add_i32 m0, s69, 0x2000
	v_lshl_add_u64 v[224:225], s[70:71], 0, v[192:193]
	s_add_u32 s70, s70, s24
	s_addc_u32 s71, s71, 0
	s_add_i32 s69, s74, s25
	global_load_lds_dwordx4 v[224:225], off
	v_lshl_add_u64 v[244:245], s[70:71], 0, v[196:197]
	s_mov_b32 m0, s69
	v_lshl_add_u64 v[246:247], s[70:71], 0, v[192:193]
	global_load_lds_dwordx4 v[244:245], off
	s_add_i32 m0, s69, 0x2000
	v_lshl_add_u64 v[248:249], s[20:21], 0, v[198:199]
	global_load_lds_dwordx4 v[246:247], off
	s_mov_b32 m0, s35
	s_nop 0
	global_load_lds_dwordx4 v[248:249], off
	v_lshl_add_u64 v[248:249], s[20:21], 0, v[194:195]
	s_mov_b32 m0, s44
	s_nop 0
	global_load_lds_dwordx4 v[248:249], off
	s_waitcnt vmcnt(8)
	s_waitcnt lgkmcnt(0)
	s_barrier
; #define PG8_STAGE(bufoff, gbase, voff) do { _Pragma("unroll") for (int _i = 0; _i < 2; ++_i) \
;         __builtin_amdgcn_global_load_lds((const unsigned*)((const char*)(gbase) + (voff)[_i]), (PG8_LAS unsigned*)(lds + (bufoff) + ldsw + _i * 8192), 16, 0, 0); } while (0)
; #define PG8_LDA(dst, b, h) do { _Pragma("unroll") for (int m = 0; m < 4; ++m) _Pragma("unroll") for (int k = 0; k < 2; ++k) dst[m][k] = *(const PG8_LAS bf16x8*)(lds + PG8_SA(b, h) + aoff + m * 2048 + k * 1024); } while (0)
; #define PG8_LDB(dst, b, h) do { _Pragma("unroll") for (int n = 0; n < 2; ++n) _Pragma("unroll") for (int k = 0; k < 2; ++k) dst[n][k] = *(const PG8_LAS bf16x8*)(lds + PG8_SB(b, h) + boff + n * 2048 + k * 1024); } while (0)
; #define PG8_MMA(ai, bj, At, Bt) do { __builtin_amdgcn_s_setprio(1); _Pragma("unroll") for (int m = 0; m < 4; ++m) _Pragma("unroll") for (int n = 0; n < 2; ++n) _Pragma("unroll") for (int k = 0; k < 2; ++k) \
;         acc[ai][bj][m][n] = __builtin_amdgcn_mfma_f32_16x16x32_bf16(Bt[n][k], At[m][k], acc[ai][bj][m][n], 0, 0, 0); __builtin_amdgcn_s_setprio(0); } while (0)
; #define PG8_WAIT_V(n) asm volatile("s_waitcnt vmcnt(" #n ")" ::: "memory")
; #define PG8_WAIT_L(n) asm volatile("s_waitcnt lgkmcnt(" #n ")" ::: "memory")
; #define PG8_BAR __builtin_amdgcn_s_barrier()
; #define PG8_SCHED __builtin_amdgcn_sched_barrier(0)
;     ...
;             PG8_WAIT_V(8); PG8_WAIT_L(0); PG8_BAR; PG8_MMA(1, 0, At, B0); PG8_MMA(1, 1, At, B1); PG8_BAR; PG8_SCHED;
;             PG8_LDB(B0, 1, 0); PG8_LDB(B1, 1, 1); PG8_SCHED; PG8_LDA(At, 1, 0); PG8_STAGE(PG8_SA(0, 1), a2 + hstepA, voffA);
;             PG8_WAIT_V(8); PG8_WAIT_L(0); PG8_BAR; PG8_MMA(0, 0, At, B0); PG8_MMA(0, 1, At, B1); PG8_BAR; PG8_SCHED;
	s_setprio 1
	s_waitcnt lgkmcnt(0)
	v_mfma_f32_16x16x32_bf16 v[60:63], v[76:79], v[156:159], v[60:63]
	v_mfma_f32_16x16x32_bf16 v[56:59], v[100:103], v[156:159], v[56:59]
	v_mfma_f32_16x16x32_bf16 v[40:43], v[100:103], v[172:175], v[40:43]
	v_mfma_f32_16x16x32_bf16 v[44:47], v[76:79], v[172:175], v[44:47]
	v_mfma_f32_16x16x32_bf16 v[28:31], v[76:79], v[180:183], v[28:31]
	v_mfma_f32_16x16x32_bf16 v[24:27], v[100:103], v[180:183], v[24:27]
	v_mfma_f32_16x16x32_bf16 v[8:11], v[100:103], v[188:191], v[8:11]
	v_mfma_f32_16x16x32_bf16 v[12:15], v[76:79], v[188:191], v[12:15]
	v_mfma_f32_16x16x32_bf16 v[60:63], v[88:91], v[168:171], v[60:63]
	v_mfma_f32_16x16x32_bf16 v[56:59], v[108:111], v[168:171], v[56:59]
	v_mfma_f32_16x16x32_bf16 v[40:43], v[108:111], v[176:179], v[40:43]
	v_mfma_f32_16x16x32_bf16 v[44:47], v[88:91], v[176:179], v[44:47]
	v_mfma_f32_16x16x32_bf16 v[28:31], v[88:91], v[184:187], v[28:31]
	v_mfma_f32_16x16x32_bf16 v[24:27], v[108:111], v[184:187], v[24:27]
	v_mfma_f32_16x16x32_bf16 v[8:11], v[108:111], v[218:221], v[8:11]
	v_mfma_f32_16x16x32_bf16 v[12:15], v[88:91], v[218:221], v[12:15]
	s_setprio 0
	s_setprio 1
	v_mfma_f32_16x16x32_bf16 v[52:55], v[124:127], v[156:159], v[52:55]
	v_mfma_f32_16x16x32_bf16 v[48:51], v[144:147], v[156:159], v[48:51]
	v_mfma_f32_16x16x32_bf16 v[32:35], v[144:147], v[172:175], v[32:35]
	v_mfma_f32_16x16x32_bf16 v[36:39], v[124:127], v[172:175], v[36:39]
	v_mfma_f32_16x16x32_bf16 v[20:23], v[124:127], v[180:183], v[20:23]
	v_mfma_f32_16x16x32_bf16 v[16:19], v[144:147], v[180:183], v[16:19]
	v_mfma_f32_16x16x32_bf16 v[0:3], v[144:147], v[188:191], v[0:3]
	v_mfma_f32_16x16x32_bf16 v[4:7], v[124:127], v[188:191], v[4:7]
	v_mfma_f32_16x16x32_bf16 v[52:55], v[128:131], v[168:171], v[52:55]
	v_mfma_f32_16x16x32_bf16 v[48:51], v[152:155], v[168:171], v[48:51]
	v_mfma_f32_16x16x32_bf16 v[32:35], v[152:155], v[176:179], v[32:35]
	v_mfma_f32_16x16x32_bf16 v[36:39], v[128:131], v[176:179], v[36:39]
	v_mfma_f32_16x16x32_bf16 v[20:23], v[128:131], v[184:187], v[20:23]
	v_mfma_f32_16x16x32_bf16 v[16:19], v[152:155], v[184:187], v[16:19]
	v_mfma_f32_16x16x32_bf16 v[0:3], v[152:155], v[218:221], v[0:3]
	v_mfma_f32_16x16x32_bf16 v[4:7], v[128:131], v[218:221], v[4:7]
	s_setprio 0
	s_barrier
	s_add_i32 s69, 0, 0x18000
	s_add_i32 s70, 0, 0x1c000
	v_add_u32_e32 v108, s69, v212
	v_add_u32_e32 v152, s70, v212
	ds_read_b128 v[76:79], v108
	ds_read_b128 v[88:91], v108 offset:1024
	ds_read_b128 v[100:103], v108 offset:2048
	ds_read_b128 v[108:111], v108 offset:3072
	ds_read_b128 v[124:127], v152
	ds_read_b128 v[128:131], v152 offset:1024
	ds_read_b128 v[144:147], v152 offset:2048
	ds_read_b128 v[152:155], v152 offset:3072
	s_add_u32 s20, s20, s24
	s_addc_u32 s21, s21, 0
	s_mov_b32 m0, s45
	v_lshl_add_u64 v[248:249], s[20:21], 0, v[198:199]
	ds_read_b128 v[156:159], v241 offset:32768
	ds_read_b128 v[168:171], v241 offset:33792
	ds_read_b128 v[172:175], v241 offset:34816
	ds_read_b128 v[176:179], v241 offset:35840
	ds_read_b128 v[180:183], v241 offset:36864
	ds_read_b128 v[184:187], v241 offset:37888
	ds_read_b128 v[188:191], v241 offset:38912
	ds_read_b128 v[218:221], v241 offset:39936
	global_load_lds_dwordx4 v[248:249], off
	v_lshl_add_u64 v[248:249], s[20:21], 0, v[194:195]
	s_mov_b32 m0, s46
	s_nop 0
	global_load_lds_dwordx4 v[248:249], off
	s_waitcnt vmcnt(8)
	s_waitcnt lgkmcnt(0)
	s_barrier
	s_setprio 1
	s_waitcnt lgkmcnt(0)
	v_mfma_f32_16x16x32_bf16 v[164:167], v[76:79], v[156:159], v[164:167]
	v_mfma_f32_16x16x32_bf16 v[160:163], v[100:103], v[156:159], v[160:163]
	v_mfma_f32_16x16x32_bf16 v[132:135], v[100:103], v[172:175], v[132:135]
	v_mfma_f32_16x16x32_bf16 v[136:139], v[76:79], v[172:175], v[136:139]
	v_mfma_f32_16x16x32_bf16 v[112:115], v[76:79], v[180:183], v[112:115]
	v_mfma_f32_16x16x32_bf16 v[104:107], v[100:103], v[180:183], v[104:107]
	v_mfma_f32_16x16x32_bf16 v[80:83], v[100:103], v[188:191], v[80:83]
	v_mfma_f32_16x16x32_bf16 v[84:87], v[76:79], v[188:191], v[84:87]
	v_mfma_f32_16x16x32_bf16 v[164:167], v[88:91], v[168:171], v[164:167]
	v_mfma_f32_16x16x32_bf16 v[160:163], v[108:111], v[168:171], v[160:163]
	v_mfma_f32_16x16x32_bf16 v[132:135], v[108:111], v[176:179], v[132:135]
	v_mfma_f32_16x16x32_bf16 v[136:139], v[88:91], v[176:179], v[136:139]
	v_mfma_f32_16x16x32_bf16 v[112:115], v[88:91], v[184:187], v[112:115]
	v_mfma_f32_16x16x32_bf16 v[104:107], v[108:111], v[184:187], v[104:107]
	v_mfma_f32_16x16x32_bf16 v[80:83], v[108:111], v[218:221], v[80:83]
	v_mfma_f32_16x16x32_bf16 v[84:87], v[88:91], v[218:221], v[84:87]
	s_setprio 0
	s_setprio 1
	v_mfma_f32_16x16x32_bf16 v[148:151], v[124:127], v[156:159], v[148:151]
	v_mfma_f32_16x16x32_bf16 v[140:143], v[144:147], v[156:159], v[140:143]
	v_mfma_f32_16x16x32_bf16 v[116:119], v[144:147], v[172:175], v[116:119]
	v_mfma_f32_16x16x32_bf16 v[120:123], v[124:127], v[172:175], v[120:123]
	v_mfma_f32_16x16x32_bf16 v[96:99], v[124:127], v[180:183], v[96:99]
	v_mfma_f32_16x16x32_bf16 v[92:95], v[144:147], v[180:183], v[92:95]
	v_mfma_f32_16x16x32_bf16 v[68:71], v[144:147], v[188:191], v[68:71]
	v_mfma_f32_16x16x32_bf16 v[72:75], v[124:127], v[188:191], v[72:75]
	v_mfma_f32_16x16x32_bf16 v[148:151], v[128:131], v[168:171], v[148:151]
	v_mfma_f32_16x16x32_bf16 v[140:143], v[152:155], v[168:171], v[140:143]
	v_mfma_f32_16x16x32_bf16 v[116:119], v[152:155], v[176:179], v[116:119]
	v_mfma_f32_16x16x32_bf16 v[120:123], v[128:131], v[176:179], v[120:123]
	v_mfma_f32_16x16x32_bf16 v[96:99], v[128:131], v[184:187], v[96:99]
	v_mfma_f32_16x16x32_bf16 v[92:95], v[152:155], v[184:187], v[92:95]
	v_mfma_f32_16x16x32_bf16 v[68:71], v[152:155], v[218:221], v[68:71]
	v_mfma_f32_16x16x32_bf16 v[72:75], v[128:131], v[218:221], v[72:75]
	s_setprio 0
	s_barrier
; #define PG8_STAGE(bufoff, gbase, voff) do { _Pragma("unroll") for (int _i = 0; _i < 2; ++_i) \
;         __builtin_amdgcn_global_load_lds((const unsigned*)((const char*)(gbase) + (voff)[_i]), (PG8_LAS unsigned*)(lds + (bufoff) + ldsw + _i * 8192), 16, 0, 0); } while (0)
; #define PG8_LDA(dst, b, h) do { _Pragma("unroll") for (int m = 0; m < 4; ++m) _Pragma("unroll") for (int k = 0; k < 2; ++k) dst[m][k] = *(const PG8_LAS bf16x8*)(lds + PG8_SA(b, h) + aoff + m * 2048 + k * 1024); } while (0)
; #define PG8_MMA(ai, bj, At, Bt) do { __builtin_amdgcn_s_setprio(1); _Pragma("unroll") for (int m = 0; m < 4; ++m) _Pragma("unroll") for (int n = 0; n < 2; ++n) _Pragma("unroll") for (int k = 0; k < 2; ++k) \
;         acc[ai][bj][m][n] = __builtin_amdgcn_mfma_f32_16x16x32_bf16(Bt[n][k], At[m][k], acc[ai][bj][m][n], 0, 0, 0); __builtin_amdgcn_s_setprio(0); } while (0)
; #define PG8_WAIT_V(n) asm volatile("s_waitcnt vmcnt(" #n ")" ::: "memory")
; #define PG8_WAIT_L(n) asm volatile("s_waitcnt lgkmcnt(" #n ")" ::: "memory")
; #define PG8_BAR __builtin_amdgcn_s_barrier()
; #define PG8_SCHED __builtin_amdgcn_sched_barrier(0)
;     ...
;             PG8_LDA(At, 1, 1); PG8_STAGE(PG8_SB(1, 0), b3, voffB); PG8_STAGE(PG8_SB(1, 1), b3 + hstepB, voffB); PG8_STAGE(PG8_SA(1, 0), a3, voffA);
;             PG8_WAIT_V(8); PG8_WAIT_L(0); PG8_BAR; PG8_MMA(1, 0, At, B0); PG8_MMA(1, 1, At, B1); PG8_BAR; PG8_SCHED;
;         }
;         if (wr == 0) PG8_BAR;
;         if (!has_next && wmat && gtid * 128u < wbytes) asm volatile("global_load_dword %0, %1, off" : "+v"(warmm) : "v"(wmat + (size_t)gtid * 128u) : "memory");
	s_add_i32 s20, s69, s25
	v_lshl_add_u64 v[222:223], v[222:223], 0, s[76:77]
	s_mov_b32 m0, s20
	ds_read_b128 v[156:159], v241 offset:49152
	ds_read_b128 v[168:171], v241 offset:50176
	ds_read_b128 v[172:175], v241 offset:51200
	ds_read_b128 v[176:179], v241 offset:52224
	ds_read_b128 v[180:183], v241 offset:53248
	ds_read_b128 v[184:187], v241 offset:54272
	ds_read_b128 v[188:191], v241 offset:55296
	ds_read_b128 v[218:221], v241 offset:56320
	global_load_lds_dwordx4 v[222:223], off
	v_lshl_add_u64 v[222:223], v[224:225], 0, s[76:77]
	s_add_i32 m0, s20, 0x2000
	s_add_i32 s20, s70, s25
	global_load_lds_dwordx4 v[222:223], off
	v_lshl_add_u64 v[222:223], v[244:245], 0, s[76:77]
	s_mov_b32 m0, s20
	s_nop 0
	global_load_lds_dwordx4 v[222:223], off
	v_lshl_add_u64 v[222:223], v[246:247], 0, s[76:77]
	s_add_i32 m0, s20, 0x2000
	s_nop 0
	global_load_lds_dwordx4 v[222:223], off
	v_lshl_add_u64 v[222:223], s[2:3], 0, v[198:199]
	s_mov_b32 m0, s47
	s_nop 0
	global_load_lds_dwordx4 v[222:223], off
	v_lshl_add_u64 v[222:223], s[2:3], 0, v[194:195]
	s_mov_b32 m0, s48
	s_nop 0
	global_load_lds_dwordx4 v[222:223], off
	s_waitcnt vmcnt(8)
	s_waitcnt lgkmcnt(0)
	s_barrier
	s_setprio 1
	s_waitcnt lgkmcnt(0)
	v_mfma_f32_16x16x32_bf16 v[60:63], v[76:79], v[156:159], v[60:63]
	v_mfma_f32_16x16x32_bf16 v[56:59], v[100:103], v[156:159], v[56:59]
	v_mfma_f32_16x16x32_bf16 v[40:43], v[100:103], v[172:175], v[40:43]
	v_mfma_f32_16x16x32_bf16 v[44:47], v[76:79], v[172:175], v[44:47]
	v_mfma_f32_16x16x32_bf16 v[28:31], v[76:79], v[180:183], v[28:31]
	v_mfma_f32_16x16x32_bf16 v[24:27], v[100:103], v[180:183], v[24:27]
	v_mfma_f32_16x16x32_bf16 v[8:11], v[100:103], v[188:191], v[8:11]
	v_mfma_f32_16x16x32_bf16 v[12:15], v[76:79], v[188:191], v[12:15]
	v_mfma_f32_16x16x32_bf16 v[60:63], v[88:91], v[168:171], v[60:63]
	v_mfma_f32_16x16x32_bf16 v[56:59], v[108:111], v[168:171], v[56:59]
	v_mfma_f32_16x16x32_bf16 v[40:43], v[108:111], v[176:179], v[40:43]
	v_mfma_f32_16x16x32_bf16 v[44:47], v[88:91], v[176:179], v[44:47]
	v_mfma_f32_16x16x32_bf16 v[28:31], v[88:91], v[184:187], v[28:31]
	v_mfma_f32_16x16x32_bf16 v[24:27], v[108:111], v[184:187], v[24:27]
	v_mfma_f32_16x16x32_bf16 v[8:11], v[108:111], v[218:221], v[8:11]
	v_mfma_f32_16x16x32_bf16 v[12:15], v[88:91], v[218:221], v[12:15]
	s_setprio 0
	s_setprio 1
	v_mfma_f32_16x16x32_bf16 v[52:55], v[124:127], v[156:159], v[52:55]
	v_mfma_f32_16x16x32_bf16 v[48:51], v[144:147], v[156:159], v[48:51]
	v_mfma_f32_16x16x32_bf16 v[32:35], v[144:147], v[172:175], v[32:35]
	v_mfma_f32_16x16x32_bf16 v[36:39], v[124:127], v[172:175], v[36:39]
	v_mfma_f32_16x16x32_bf16 v[20:23], v[124:127], v[180:183], v[20:23]
	v_mfma_f32_16x16x32_bf16 v[16:19], v[144:147], v[180:183], v[16:19]
	v_mfma_f32_16x16x32_bf16 v[0:3], v[144:147], v[188:191], v[0:3]
	v_mfma_f32_16x16x32_bf16 v[4:7], v[124:127], v[188:191], v[4:7]
	v_mfma_f32_16x16x32_bf16 v[52:55], v[128:131], v[168:171], v[52:55]
	v_mfma_f32_16x16x32_bf16 v[48:51], v[152:155], v[168:171], v[48:51]
	v_mfma_f32_16x16x32_bf16 v[32:35], v[152:155], v[176:179], v[32:35]
	v_mfma_f32_16x16x32_bf16 v[36:39], v[128:131], v[176:179], v[36:39]
	v_mfma_f32_16x16x32_bf16 v[20:23], v[128:131], v[184:187], v[20:23]
	v_mfma_f32_16x16x32_bf16 v[16:19], v[152:155], v[184:187], v[16:19]
	v_mfma_f32_16x16x32_bf16 v[0:3], v[152:155], v[218:221], v[0:3]
	v_mfma_f32_16x16x32_bf16 v[4:7], v[128:131], v[218:221], v[4:7]
	s_setprio 0
	s_barrier
	s_add_u32 s64, s64, 0x100
	s_addc_u32 s65, s65, 0
	s_add_u32 s66, s66, 0x100
	s_addc_u32 s67, s67, 0
	v_lshl_add_u64 v[64:65], v[64:65], 0, s[78:79]
	v_lshl_add_u64 v[66:67], v[66:67], 0, s[78:79]
	s_cmp_ge_u32 s68, s50
	s_mov_b32 s2, s68
	s_cbranch_scc0 .LBB0_534
	s_and_b64 vcc, exec, s[12:13]
	s_cbranch_vccz .LBB0_541
	s_barrier
	s_nor_b64 s[20:21], s[14:15], s[38:39]
	s_and_saveexec_b64 s[2:3], s[20:21]
	s_cbranch_execnz .LBB0_542

;     __device__ __forceinline__ const char* tile(const Unit& u, int t) const { return A + (size_t)u.pm * 2 * hstep() + (size_t)t * (BK * 2); }
;     __device__ __forceinline__ const char* tile(const Unit& u, int t) const { return U + (long)(t >> 2) * xoff + (size_t)u.pn * (1024 * 512) + (size_t)u.pm * 2 * hstep() + (size_t)(t & 3) * (BK * 2); }
; #define PG8_STAGE(bufoff, gbase, voff) do { _Pragma("unroll") for (int _i = 0; _i < 2; ++_i) \
;         __builtin_amdgcn_global_load_lds((const unsigned*)((const char*)(gbase) + (voff)[_i]), (PG8_LAS unsigned*)(lds + (bufoff) + ldsw + _i * 8192), 16, 0, 0); } while (0)
; #define PG8_LDA(dst, b, h) do { _Pragma("unroll") for (int m = 0; m < 4; ++m) _Pragma("unroll") for (int k = 0; k < 2; ++k) dst[m][k] = *(const PG8_LAS bf16x8*)(lds + PG8_SA(b, h) + aoff + m * 2048 + k * 1024); } while (0)
; #define PG8_LDB(dst, b, h) do { _Pragma("unroll") for (int n = 0; n < 2; ++n) _Pragma("unroll") for (int k = 0; k < 2; ++k) dst[n][k] = *(const PG8_LAS bf16x8*)(lds + PG8_SB(b, h) + boff + n * 2048 + k * 1024); } while (0)
; #define PG8_MMA(ai, bj, At, Bt) do { __builtin_amdgcn_s_setprio(1); _Pragma("unroll") for (int m = 0; m < 4; ++m) _Pragma("unroll") for (int n = 0; n < 2; ++n) _Pragma("unroll") for (int k = 0; k < 2; ++k) \
;         acc[ai][bj][m][n] = __builtin_amdgcn_mfma_f32_16x16x32_bf16(Bt[n][k], At[m][k], acc[ai][bj][m][n], 0, 0, 0); __builtin_amdgcn_s_setprio(0); } while (0)
; #define PG8_WAIT_V(n) asm volatile("s_waitcnt vmcnt(" #n ")" ::: "memory")
;     ...
;             const bool last = (t == nt - 2);
;             const char* a1 = AS.tile(cur, t + 1);
;             const char* a2 = last ? AS.tile(nu, 0) : AS.tile(cur, t + 2); const char* b2 = last ? nB : cB + (size_t)(t + 2) * kstep;
;             const char* a3 = last ? AS.tile(nu, 1) : AS.tile(cur, t + 3); const char* b3 = b2 + kstep;
;             PG8_LDB(B0, 0, 0); PG8_LDB(B1, 0, 1); PG8_SCHED; PG8_LDA(At, 0, 0); PG8_STAGE(PG8_SA(1, 1), a1 + hstepA, voffA);
;             PG8_WAIT_V(8); PG8_WAIT_L(0); PG8_BAR; PG8_MMA(0, 0, At, B0); PG8_MMA(0, 1, At, B1); PG8_BAR; PG8_SCHED;
;             PG8_LDA(At, 0, 1); PG8_STAGE(PG8_SB(0, 0), b2, voffB); PG8_STAGE(PG8_SB(0, 1), b2 + hstepB, voffB); PG8_STAGE(PG8_SA(0, 0), a2, voffA);
;             PG8_WAIT_V(8); PG8_WAIT_L(0); PG8_BAR; PG8_MMA(1, 0, At, B0); PG8_MMA(1, 1, At, B1); PG8_BAR; PG8_SCHED;
.LBB0_702:
	s_add_u32 s20, s40, s2
	s_addc_u32 s21, s41, s3
	s_add_u32 s26, s20, 0x400100
	s_addc_u32 s27, s21, 0
	s_add_u32 s24, s42, s2
	s_addc_u32 s25, s43, s3
	s_add_u32 s20, s20, 0x400180
	s_addc_u32 s21, s21, 0
	s_add_i32 s63, 0, 0x10000
	s_add_i32 s66, 0, 0x14000
	v_add_u32_e32 v156, s63, v185
	v_add_u32_e32 v172, s66, v185
	ds_read_b128 v[132:135], v156
	ds_read_b128 v[136:139], v156 offset:1024
	ds_read_b128 v[140:143], v156 offset:2048
	ds_read_b128 v[156:159], v156 offset:3072
	ds_read_b128 v[160:163], v172
	ds_read_b128 v[164:167], v172 offset:1024
	ds_read_b128 v[168:171], v172 offset:2048
	ds_read_b128 v[172:175], v172 offset:3072
	s_cmpk_eq_i32 s2, 0x700
	s_cselect_b32 s21, s31, s21
	s_cselect_b32 s20, s30, s20
	s_cselect_b32 s25, s28, s25
	s_cselect_b32 s24, s1, s24
	s_cselect_b32 s27, s29, s27
	s_cselect_b32 s26, s19, s26
	v_lshl_add_u64 v[238:239], v[128:129], 0, s[2:3]
	s_add_i32 m0, s49, 0xc000
	ds_read_b128 v[176:179], v190
	ds_read_b128 v[180:183], v190 offset:1024
	ds_read_b128 v[192:195], v190 offset:2048
	ds_read_b128 v[196:199], v190 offset:3072
	ds_read_b128 v[200:203], v190 offset:4096
	ds_read_b128 v[204:207], v190 offset:5120
	ds_read_b128 v[218:221], v190 offset:6144
	ds_read_b128 v[222:225], v190 offset:7168
	global_load_lds_dwordx4 v[238:239], off
	v_lshl_add_u64 v[238:239], v[130:131], 0, s[2:3]
	s_add_i32 m0, s49, 0xe000
	s_nop 0
	global_load_lds_dwordx4 v[238:239], off
	s_waitcnt vmcnt(8)
	s_waitcnt lgkmcnt(0)
	s_barrier
	s_setprio 1
	s_waitcnt lgkmcnt(0)
	v_mfma_f32_16x16x32_bf16 v[124:127], v[132:135], v[176:179], v[124:127]
	v_mfma_f32_16x16x32_bf16 v[120:123], v[140:143], v[176:179], v[120:123]
	v_mfma_f32_16x16x32_bf16 v[104:107], v[140:143], v[192:195], v[104:107]
	v_mfma_f32_16x16x32_bf16 v[112:115], v[132:135], v[192:195], v[112:115]
	v_mfma_f32_16x16x32_bf16 v[96:99], v[132:135], v[200:203], v[96:99]
	v_mfma_f32_16x16x32_bf16 v[88:91], v[140:143], v[200:203], v[88:91]
	v_mfma_f32_16x16x32_bf16 v[72:75], v[140:143], v[218:221], v[72:75]
	v_mfma_f32_16x16x32_bf16 v[80:83], v[132:135], v[218:221], v[80:83]
	v_mfma_f32_16x16x32_bf16 v[124:127], v[136:139], v[180:183], v[124:127]
	v_mfma_f32_16x16x32_bf16 v[120:123], v[156:159], v[180:183], v[120:123]
	v_mfma_f32_16x16x32_bf16 v[104:107], v[156:159], v[196:199], v[104:107]
	v_mfma_f32_16x16x32_bf16 v[112:115], v[136:139], v[196:199], v[112:115]
	v_mfma_f32_16x16x32_bf16 v[96:99], v[136:139], v[204:207], v[96:99]
	v_mfma_f32_16x16x32_bf16 v[88:91], v[156:159], v[204:207], v[88:91]
	v_mfma_f32_16x16x32_bf16 v[72:75], v[156:159], v[222:225], v[72:75]
	v_mfma_f32_16x16x32_bf16 v[80:83], v[136:139], v[222:225], v[80:83]
	s_setprio 0
	s_setprio 1
	v_mfma_f32_16x16x32_bf16 v[116:119], v[160:163], v[176:179], v[116:119]
	v_mfma_f32_16x16x32_bf16 v[108:111], v[168:171], v[176:179], v[108:111]
	v_mfma_f32_16x16x32_bf16 v[92:95], v[168:171], v[192:195], v[92:95]
	v_mfma_f32_16x16x32_bf16 v[100:103], v[160:163], v[192:195], v[100:103]
	v_mfma_f32_16x16x32_bf16 v[84:87], v[160:163], v[200:203], v[84:87]
	v_mfma_f32_16x16x32_bf16 v[76:79], v[168:171], v[200:203], v[76:79]
	v_mfma_f32_16x16x32_bf16 v[64:67], v[168:171], v[218:221], v[64:67]
	v_mfma_f32_16x16x32_bf16 v[68:71], v[160:163], v[218:221], v[68:71]
	v_mfma_f32_16x16x32_bf16 v[116:119], v[164:167], v[180:183], v[116:119]
	v_mfma_f32_16x16x32_bf16 v[108:111], v[172:175], v[180:183], v[108:111]
	v_mfma_f32_16x16x32_bf16 v[92:95], v[172:175], v[196:199], v[92:95]
	v_mfma_f32_16x16x32_bf16 v[100:103], v[164:167], v[196:199], v[100:103]
	v_mfma_f32_16x16x32_bf16 v[84:87], v[164:167], v[204:207], v[84:87]
	v_mfma_f32_16x16x32_bf16 v[76:79], v[172:175], v[204:207], v[76:79]
	v_mfma_f32_16x16x32_bf16 v[64:67], v[172:175], v[222:225], v[64:67]
	v_mfma_f32_16x16x32_bf16 v[68:71], v[164:167], v[222:225], v[68:71]
	s_setprio 0
	s_barrier
	s_add_i32 s63, s63, s48
	v_lshl_add_u64 v[238:239], s[24:25], 0, v[148:149]
	s_mov_b32 m0, s63
	ds_read_b128 v[176:179], v190 offset:16384
	ds_read_b128 v[180:183], v190 offset:17408
	ds_read_b128 v[192:195], v190 offset:18432
	ds_read_b128 v[196:199], v190 offset:19456
	ds_read_b128 v[200:203], v190 offset:20480
	ds_read_b128 v[204:207], v190 offset:21504
	ds_read_b128 v[218:221], v190 offset:22528
	ds_read_b128 v[222:225], v190 offset:23552
	global_load_lds_dwordx4 v[238:239], off
	s_add_i32 m0, s63, 0x2000
	s_add_u32 s64, s24, 0x40000
	v_lshl_add_u64 v[240:241], s[24:25], 0, v[144:145]
	s_addc_u32 s65, s25, 0
	s_add_i32 s63, s66, s48
	global_load_lds_dwordx4 v[240:241], off
	v_lshl_add_u64 v[242:243], s[64:65], 0, v[148:149]
	s_mov_b32 m0, s63
	s_nop 0
	global_load_lds_dwordx4 v[242:243], off
	v_lshl_add_u64 v[242:243], s[64:65], 0, v[144:145]
	s_add_i32 m0, s63, 0x2000
	s_nop 0
	global_load_lds_dwordx4 v[242:243], off
	v_lshl_add_u64 v[242:243], s[26:27], 0, v[150:151]
	s_mov_b32 m0, s49
	s_nop 0
	global_load_lds_dwordx4 v[242:243], off
	v_lshl_add_u64 v[242:243], s[26:27], 0, v[146:147]
	s_mov_b32 m0, s50
	s_nop 0
	global_load_lds_dwordx4 v[242:243], off
	s_waitcnt vmcnt(8)
	s_waitcnt lgkmcnt(0)
	s_barrier
; #define PG8_STAGE(bufoff, gbase, voff) do { _Pragma("unroll") for (int _i = 0; _i < 2; ++_i) \
;         __builtin_amdgcn_global_load_lds((const unsigned*)((const char*)(gbase) + (voff)[_i]), (PG8_LAS unsigned*)(lds + (bufoff) + ldsw + _i * 8192), 16, 0, 0); } while (0)
; #define PG8_LDA(dst, b, h) do { _Pragma("unroll") for (int m = 0; m < 4; ++m) _Pragma("unroll") for (int k = 0; k < 2; ++k) dst[m][k] = *(const PG8_LAS bf16x8*)(lds + PG8_SA(b, h) + aoff + m * 2048 + k * 1024); } while (0)
; #define PG8_LDB(dst, b, h) do { _Pragma("unroll") for (int n = 0; n < 2; ++n) _Pragma("unroll") for (int k = 0; k < 2; ++k) dst[n][k] = *(const PG8_LAS bf16x8*)(lds + PG8_SB(b, h) + boff + n * 2048 + k * 1024); } while (0)
; #define PG8_MMA(ai, bj, At, Bt) do { __builtin_amdgcn_s_setprio(1); _Pragma("unroll") for (int m = 0; m < 4; ++m) _Pragma("unroll") for (int n = 0; n < 2; ++n) _Pragma("unroll") for (int k = 0; k < 2; ++k) \
;         acc[ai][bj][m][n] = __builtin_amdgcn_mfma_f32_16x16x32_bf16(Bt[n][k], At[m][k], acc[ai][bj][m][n], 0, 0, 0); __builtin_amdgcn_s_setprio(0); } while (0)
; #define PG8_WAIT_V(n) asm volatile("s_waitcnt vmcnt(" #n ")" ::: "memory")
; #define PG8_WAIT_L(n) asm volatile("s_waitcnt lgkmcnt(" #n ")" ::: "memory")
; #define PG8_BAR __builtin_amdgcn_s_barrier()
; #define PG8_SCHED __builtin_amdgcn_sched_barrier(0)
;     ...
;             PG8_WAIT_V(8); PG8_WAIT_L(0); PG8_BAR; PG8_MMA(1, 0, At, B0); PG8_MMA(1, 1, At, B1); PG8_BAR; PG8_SCHED;
;             PG8_LDB(B0, 1, 0); PG8_LDB(B1, 1, 1); PG8_SCHED; PG8_LDA(At, 1, 0); PG8_STAGE(PG8_SA(0, 1), a2 + hstepA, voffA);
;             PG8_WAIT_V(8); PG8_WAIT_L(0); PG8_BAR; PG8_MMA(0, 0, At, B0); PG8_MMA(0, 1, At, B1); PG8_BAR; PG8_SCHED;
	s_setprio 1
	s_waitcnt lgkmcnt(0)
	v_mfma_f32_16x16x32_bf16 v[60:63], v[132:135], v[176:179], v[60:63]
	v_mfma_f32_16x16x32_bf16 v[56:59], v[140:143], v[176:179], v[56:59]
	v_mfma_f32_16x16x32_bf16 v[40:43], v[140:143], v[192:195], v[40:43]
	v_mfma_f32_16x16x32_bf16 v[48:51], v[132:135], v[192:195], v[48:51]
	v_mfma_f32_16x16x32_bf16 v[32:35], v[132:135], v[200:203], v[32:35]
	v_mfma_f32_16x16x32_bf16 v[24:27], v[140:143], v[200:203], v[24:27]
	v_mfma_f32_16x16x32_bf16 v[8:11], v[140:143], v[218:221], v[8:11]
	v_mfma_f32_16x16x32_bf16 v[16:19], v[132:135], v[218:221], v[16:19]
	v_mfma_f32_16x16x32_bf16 v[60:63], v[136:139], v[180:183], v[60:63]
	v_mfma_f32_16x16x32_bf16 v[56:59], v[156:159], v[180:183], v[56:59]
	v_mfma_f32_16x16x32_bf16 v[40:43], v[156:159], v[196:199], v[40:43]
	v_mfma_f32_16x16x32_bf16 v[48:51], v[136:139], v[196:199], v[48:51]
	v_mfma_f32_16x16x32_bf16 v[32:35], v[136:139], v[204:207], v[32:35]
	v_mfma_f32_16x16x32_bf16 v[24:27], v[156:159], v[204:207], v[24:27]
	v_mfma_f32_16x16x32_bf16 v[8:11], v[156:159], v[222:225], v[8:11]
	v_mfma_f32_16x16x32_bf16 v[16:19], v[136:139], v[222:225], v[16:19]
	s_setprio 0
	s_setprio 1
	v_mfma_f32_16x16x32_bf16 v[52:55], v[160:163], v[176:179], v[52:55]
	v_mfma_f32_16x16x32_bf16 v[44:47], v[168:171], v[176:179], v[44:47]
	v_mfma_f32_16x16x32_bf16 v[28:31], v[168:171], v[192:195], v[28:31]
	v_mfma_f32_16x16x32_bf16 v[36:39], v[160:163], v[192:195], v[36:39]
	v_mfma_f32_16x16x32_bf16 v[20:23], v[160:163], v[200:203], v[20:23]
	v_mfma_f32_16x16x32_bf16 v[12:15], v[168:171], v[200:203], v[12:15]
	v_mfma_f32_16x16x32_bf16 v[0:3], v[168:171], v[218:221], v[0:3]
	v_mfma_f32_16x16x32_bf16 v[4:7], v[160:163], v[218:221], v[4:7]
	v_mfma_f32_16x16x32_bf16 v[52:55], v[164:167], v[180:183], v[52:55]
	v_mfma_f32_16x16x32_bf16 v[44:47], v[172:175], v[180:183], v[44:47]
	v_mfma_f32_16x16x32_bf16 v[28:31], v[172:175], v[196:199], v[28:31]
	v_mfma_f32_16x16x32_bf16 v[36:39], v[164:167], v[196:199], v[36:39]
	v_mfma_f32_16x16x32_bf16 v[20:23], v[164:167], v[204:207], v[20:23]
	v_mfma_f32_16x16x32_bf16 v[12:15], v[172:175], v[204:207], v[12:15]
	v_mfma_f32_16x16x32_bf16 v[0:3], v[172:175], v[222:225], v[0:3]
	v_mfma_f32_16x16x32_bf16 v[4:7], v[164:167], v[222:225], v[4:7]
	s_setprio 0
	s_barrier
	s_add_i32 s63, 0, 0x18000
	s_add_i32 s64, 0, 0x1c000
	v_add_u32_e32 v156, s63, v185
	v_add_u32_e32 v172, s64, v185
	ds_read_b128 v[132:135], v156
	ds_read_b128 v[136:139], v156 offset:1024
	ds_read_b128 v[140:143], v156 offset:2048
	ds_read_b128 v[156:159], v156 offset:3072
	ds_read_b128 v[160:163], v172
	ds_read_b128 v[164:167], v172 offset:1024
	ds_read_b128 v[168:171], v172 offset:2048
	ds_read_b128 v[172:175], v172 offset:3072
	s_add_u32 s26, s26, 0x40000
	s_addc_u32 s27, s27, 0
	s_mov_b32 m0, s51
	v_lshl_add_u64 v[242:243], s[26:27], 0, v[150:151]
	ds_read_b128 v[176:179], v190 offset:32768
	ds_read_b128 v[180:183], v190 offset:33792
	ds_read_b128 v[192:195], v190 offset:34816
	ds_read_b128 v[196:199], v190 offset:35840
	ds_read_b128 v[200:203], v190 offset:36864
	ds_read_b128 v[204:207], v190 offset:37888
	ds_read_b128 v[218:221], v190 offset:38912
	ds_read_b128 v[222:225], v190 offset:39936
	global_load_lds_dwordx4 v[242:243], off
	v_lshl_add_u64 v[242:243], s[26:27], 0, v[146:147]
	s_mov_b32 m0, s52
	s_nop 0
	global_load_lds_dwordx4 v[242:243], off
	s_waitcnt vmcnt(8)
	s_waitcnt lgkmcnt(0)
	s_barrier
	s_setprio 1
	s_waitcnt lgkmcnt(0)
	v_mfma_f32_16x16x32_bf16 v[124:127], v[132:135], v[176:179], v[124:127]
	v_mfma_f32_16x16x32_bf16 v[120:123], v[140:143], v[176:179], v[120:123]
	v_mfma_f32_16x16x32_bf16 v[104:107], v[140:143], v[192:195], v[104:107]
	v_mfma_f32_16x16x32_bf16 v[112:115], v[132:135], v[192:195], v[112:115]
	v_mfma_f32_16x16x32_bf16 v[96:99], v[132:135], v[200:203], v[96:99]
	v_mfma_f32_16x16x32_bf16 v[88:91], v[140:143], v[200:203], v[88:91]
	v_mfma_f32_16x16x32_bf16 v[72:75], v[140:143], v[218:221], v[72:75]
	v_mfma_f32_16x16x32_bf16 v[80:83], v[132:135], v[218:221], v[80:83]
	v_mfma_f32_16x16x32_bf16 v[124:127], v[136:139], v[180:183], v[124:127]
	v_mfma_f32_16x16x32_bf16 v[120:123], v[156:159], v[180:183], v[120:123]
	v_mfma_f32_16x16x32_bf16 v[104:107], v[156:159], v[196:199], v[104:107]
	v_mfma_f32_16x16x32_bf16 v[112:115], v[136:139], v[196:199], v[112:115]
	v_mfma_f32_16x16x32_bf16 v[96:99], v[136:139], v[204:207], v[96:99]
	v_mfma_f32_16x16x32_bf16 v[88:91], v[156:159], v[204:207], v[88:91]
	v_mfma_f32_16x16x32_bf16 v[72:75], v[156:159], v[222:225], v[72:75]
	v_mfma_f32_16x16x32_bf16 v[80:83], v[136:139], v[222:225], v[80:83]
	s_setprio 0
	s_setprio 1
	v_mfma_f32_16x16x32_bf16 v[116:119], v[160:163], v[176:179], v[116:119]
	v_mfma_f32_16x16x32_bf16 v[108:111], v[168:171], v[176:179], v[108:111]
	v_mfma_f32_16x16x32_bf16 v[92:95], v[168:171], v[192:195], v[92:95]
	v_mfma_f32_16x16x32_bf16 v[100:103], v[160:163], v[192:195], v[100:103]
	v_mfma_f32_16x16x32_bf16 v[84:87], v[160:163], v[200:203], v[84:87]
	v_mfma_f32_16x16x32_bf16 v[76:79], v[168:171], v[200:203], v[76:79]
	v_mfma_f32_16x16x32_bf16 v[64:67], v[168:171], v[218:221], v[64:67]
	v_mfma_f32_16x16x32_bf16 v[68:71], v[160:163], v[218:221], v[68:71]
	v_mfma_f32_16x16x32_bf16 v[116:119], v[164:167], v[180:183], v[116:119]
	v_mfma_f32_16x16x32_bf16 v[108:111], v[172:175], v[180:183], v[108:111]
	v_mfma_f32_16x16x32_bf16 v[92:95], v[172:175], v[196:199], v[92:95]
	v_mfma_f32_16x16x32_bf16 v[100:103], v[164:167], v[196:199], v[100:103]
	v_mfma_f32_16x16x32_bf16 v[84:87], v[164:167], v[204:207], v[84:87]
	v_mfma_f32_16x16x32_bf16 v[76:79], v[172:175], v[204:207], v[76:79]
	v_mfma_f32_16x16x32_bf16 v[64:67], v[172:175], v[222:225], v[64:67]
	v_mfma_f32_16x16x32_bf16 v[68:71], v[164:167], v[222:225], v[68:71]
	s_setprio 0
	s_barrier
; #define PG8_STAGE(bufoff, gbase, voff) do { _Pragma("unroll") for (int _i = 0; _i < 2; ++_i) \
;         __builtin_amdgcn_global_load_lds((const unsigned*)((const char*)(gbase) + (voff)[_i]), (PG8_LAS unsigned*)(lds + (bufoff) + ldsw + _i * 8192), 16, 0, 0); } while (0)
; #define PG8_LDA(dst, b, h) do { _Pragma("unroll") for (int m = 0; m < 4; ++m) _Pragma("unroll") for (int k = 0; k < 2; ++k) dst[m][k] = *(const PG8_LAS bf16x8*)(lds + PG8_SA(b, h) + aoff + m * 2048 + k * 1024); } while (0)
; #define PG8_MMA(ai, bj, At, Bt) do { __builtin_amdgcn_s_setprio(1); _Pragma("unroll") for (int m = 0; m < 4; ++m) _Pragma("unroll") for (int n = 0; n < 2; ++n) _Pragma("unroll") for (int k = 0; k < 2; ++k) \
;         acc[ai][bj][m][n] = __builtin_amdgcn_mfma_f32_16x16x32_bf16(Bt[n][k], At[m][k], acc[ai][bj][m][n], 0, 0, 0); __builtin_amdgcn_s_setprio(0); } while (0)
; #define PG8_WAIT_V(n) asm volatile("s_waitcnt vmcnt(" #n ")" ::: "memory")
; #define PG8_WAIT_L(n) asm volatile("s_waitcnt lgkmcnt(" #n ")" ::: "memory")
; #define PG8_BAR __builtin_amdgcn_s_barrier()
; #define PG8_SCHED __builtin_amdgcn_sched_barrier(0)
;     ...
;             PG8_LDA(At, 1, 1); PG8_STAGE(PG8_SB(1, 0), b3, voffB); PG8_STAGE(PG8_SB(1, 1), b3 + hstepB, voffB); PG8_STAGE(PG8_SA(1, 0), a3, voffA);
;             PG8_WAIT_V(8); PG8_WAIT_L(0); PG8_BAR; PG8_MMA(1, 0, At, B0); PG8_MMA(1, 1, At, B1); PG8_BAR; PG8_SCHED;
;         }
;         if (wr == 0) PG8_BAR;
	s_add_i32 s26, s63, s48
	v_lshl_add_u64 v[238:239], v[238:239], 0, s[68:69]
	s_mov_b32 m0, s26
	ds_read_b128 v[176:179], v190 offset:49152
	ds_read_b128 v[180:183], v190 offset:50176
	ds_read_b128 v[192:195], v190 offset:51200
	ds_read_b128 v[196:199], v190 offset:52224
	ds_read_b128 v[200:203], v190 offset:53248
	ds_read_b128 v[204:207], v190 offset:54272
	ds_read_b128 v[218:221], v190 offset:55296
	ds_read_b128 v[222:225], v190 offset:56320
	global_load_lds_dwordx4 v[238:239], off
	s_add_i32 m0, s26, 0x2000
	s_add_u32 s24, s24, 0x40080
	v_lshl_add_u64 v[238:239], v[240:241], 0, s[68:69]
	s_addc_u32 s25, s25, 0
	s_add_i32 s26, s64, s48
	global_load_lds_dwordx4 v[238:239], off
	v_lshl_add_u64 v[238:239], s[24:25], 0, v[148:149]
	s_mov_b32 m0, s26
	s_nop 0
	global_load_lds_dwordx4 v[238:239], off
	v_lshl_add_u64 v[238:239], s[24:25], 0, v[144:145]
	s_add_i32 m0, s26, 0x2000
	s_nop 0
	global_load_lds_dwordx4 v[238:239], off
	v_lshl_add_u64 v[238:239], s[20:21], 0, v[150:151]
	s_mov_b32 m0, s53
	s_nop 0
	global_load_lds_dwordx4 v[238:239], off
	v_lshl_add_u64 v[238:239], s[20:21], 0, v[146:147]
	s_mov_b32 m0, s54
	s_nop 0
	global_load_lds_dwordx4 v[238:239], off
	s_waitcnt vmcnt(8)
	s_waitcnt lgkmcnt(0)
	s_barrier
	s_setprio 1
	s_waitcnt lgkmcnt(0)
	v_mfma_f32_16x16x32_bf16 v[60:63], v[132:135], v[176:179], v[60:63]
	v_mfma_f32_16x16x32_bf16 v[56:59], v[140:143], v[176:179], v[56:59]
	v_mfma_f32_16x16x32_bf16 v[40:43], v[140:143], v[192:195], v[40:43]
	v_mfma_f32_16x16x32_bf16 v[48:51], v[132:135], v[192:195], v[48:51]
	v_mfma_f32_16x16x32_bf16 v[32:35], v[132:135], v[200:203], v[32:35]
	v_mfma_f32_16x16x32_bf16 v[24:27], v[140:143], v[200:203], v[24:27]
	v_mfma_f32_16x16x32_bf16 v[8:11], v[140:143], v[218:221], v[8:11]
	v_mfma_f32_16x16x32_bf16 v[16:19], v[132:135], v[218:221], v[16:19]
	v_mfma_f32_16x16x32_bf16 v[60:63], v[136:139], v[180:183], v[60:63]
	v_mfma_f32_16x16x32_bf16 v[56:59], v[156:159], v[180:183], v[56:59]
	v_mfma_f32_16x16x32_bf16 v[40:43], v[156:159], v[196:199], v[40:43]
	v_mfma_f32_16x16x32_bf16 v[48:51], v[136:139], v[196:199], v[48:51]
	v_mfma_f32_16x16x32_bf16 v[32:35], v[136:139], v[204:207], v[32:35]
	v_mfma_f32_16x16x32_bf16 v[24:27], v[156:159], v[204:207], v[24:27]
	v_mfma_f32_16x16x32_bf16 v[8:11], v[156:159], v[222:225], v[8:11]
	v_mfma_f32_16x16x32_bf16 v[16:19], v[136:139], v[222:225], v[16:19]
	s_setprio 0
	s_setprio 1
	v_mfma_f32_16x16x32_bf16 v[52:55], v[160:163], v[176:179], v[52:55]
	v_mfma_f32_16x16x32_bf16 v[44:47], v[168:171], v[176:179], v[44:47]
	v_mfma_f32_16x16x32_bf16 v[28:31], v[168:171], v[192:195], v[28:31]
	v_mfma_f32_16x16x32_bf16 v[36:39], v[160:163], v[192:195], v[36:39]
	v_mfma_f32_16x16x32_bf16 v[20:23], v[160:163], v[200:203], v[20:23]
	v_mfma_f32_16x16x32_bf16 v[12:15], v[168:171], v[200:203], v[12:15]
	v_mfma_f32_16x16x32_bf16 v[0:3], v[168:171], v[218:221], v[0:3]
	v_mfma_f32_16x16x32_bf16 v[4:7], v[160:163], v[218:221], v[4:7]
	v_mfma_f32_16x16x32_bf16 v[52:55], v[164:167], v[180:183], v[52:55]
	v_mfma_f32_16x16x32_bf16 v[44:47], v[172:175], v[180:183], v[44:47]
	v_mfma_f32_16x16x32_bf16 v[28:31], v[172:175], v[196:199], v[28:31]
	v_mfma_f32_16x16x32_bf16 v[36:39], v[164:167], v[196:199], v[36:39]
	v_mfma_f32_16x16x32_bf16 v[20:23], v[164:167], v[204:207], v[20:23]
	v_mfma_f32_16x16x32_bf16 v[12:15], v[172:175], v[204:207], v[12:15]
	v_mfma_f32_16x16x32_bf16 v[0:3], v[172:175], v[222:225], v[0:3]
	v_mfma_f32_16x16x32_bf16 v[4:7], v[164:167], v[222:225], v[4:7]
	s_setprio 0
	s_barrier
	s_add_i32 s62, s62, 2
	s_add_u32 s2, s2, 0x100
	s_addc_u32 s3, s3, 0
	s_cmp_gt_u32 s62, 13
	s_cbranch_scc0 .LBB0_702
	s_and_b64 vcc, exec, s[12:13]
	s_cbranch_vccz .LBB0_705
	s_barrier

;     __device__ __forceinline__ unsigned voff(int R, int C) const { return (unsigned)(R * K + C) * 2u; }
;     __device__ __forceinline__ size_t hstep() const { return (size_t)HALF * K * 2; }
;     __device__ __forceinline__ const char* tile(const Unit& u, int t) const { return A + (size_t)u.pm * 2 * hstep() + (size_t)t * (BK * 2); }
; #define PG8_STAGE(bufoff, gbase, voff) do { _Pragma("unroll") for (int _i = 0; _i < 2; ++_i) \
;         __builtin_amdgcn_global_load_lds((const unsigned*)((const char*)(gbase) + (voff)[_i]), (PG8_LAS unsigned*)(lds + (bufoff) + ldsw + _i * 8192), 16, 0, 0); } while (0)
; #define PG8_LDA(dst, b, h) do { _Pragma("unroll") for (int m = 0; m < 4; ++m) _Pragma("unroll") for (int k = 0; k < 2; ++k) dst[m][k] = *(const PG8_LAS bf16x8*)(lds + PG8_SA(b, h) + aoff + m * 2048 + k * 1024); } while (0)
; #define PG8_LDB(dst, b, h) do { _Pragma("unroll") for (int n = 0; n < 2; ++n) _Pragma("unroll") for (int k = 0; k < 2; ++k) dst[n][k] = *(const PG8_LAS bf16x8*)(lds + PG8_SB(b, h) + boff + n * 2048 + k * 1024); } while (0)
; #define PG8_WAIT_V(n) asm volatile("s_waitcnt vmcnt(" #n ")" ::: "memory")
;     __device__ __forceinline__ unsigned voff(int R, int C) const { return (unsigned)(R * 256 + C) * 2u; }
;     __device__ __forceinline__ size_t hstep() const { return (size_t)HALF * 512; }
;     __device__ __forceinline__ const char* tile(const Unit& u, int t) const { return U + (long)(t >> 2) * xoff + (size_t)u.pn * (1024 * 512) + (size_t)u.pm * 2 * hstep() + (size_t)(t & 3) * (BK * 2); }
;     ...
;             const bool last = (t == nt - 2);
;             const char* a1 = AS.tile(cur, t + 1);
;             const char* a2 = last ? AS.tile(nu, 0) : AS.tile(cur, t + 2); const char* b2 = last ? nB : cB + (size_t)(t + 2) * kstep;
;             const char* a3 = last ? AS.tile(nu, 1) : AS.tile(cur, t + 3); const char* b3 = b2 + kstep;
;             PG8_LDB(B0, 0, 0); PG8_LDB(B1, 0, 1); PG8_SCHED; PG8_LDA(At, 0, 0); PG8_STAGE(PG8_SA(1, 1), a1 + hstepA, voffA);
;             PG8_WAIT_V(8); PG8_WAIT_L(0); PG8_BAR; PG8_MMA(0, 0, At, B0); PG8_MMA(0, 1, At, B1); PG8_BAR; PG8_SCHED;
;             PG8_LDA(At, 0, 1); PG8_STAGE(PG8_SB(0, 0), b2, voffB); PG8_STAGE(PG8_SB(0, 1), b2 + hstepB, voffB); PG8_STAGE(PG8_SA(0, 0), a2, voffA);
;             PG8_WAIT_V(8); PG8_WAIT_L(0); PG8_BAR; PG8_MMA(1, 0, At, B0); PG8_MMA(1, 1, At, B1); PG8_BAR; PG8_SCHED;
.LBB0_785:
	s_add_u32 s24, s9, s14
	s_addc_u32 s25, s47, 0
	s_xor_b32 s15, s14, 0x100
	s_add_u32 s15, s9, s15
	s_addc_u32 s20, s47, 0
	s_and_b64 s[18:19], s[16:17], exec
	s_cselect_b32 s21, s49, s20
	s_cselect_b32 s20, s48, s15
	s_add_u32 s15, s52, s14
	s_addc_u32 s18, s53, 0
	s_add_u32 s15, s15, 0x100
	s_addc_u32 s22, s18, 0
	s_and_b64 s[18:19], s[16:17], exec
	s_cselect_b32 s23, s46, s22
	s_cselect_b32 s22, s45, s15
	s_addk_i32 s14, 0x180
	s_and_b32 s14, s14, 0x180
	s_add_u32 s18, s9, s14
	s_addc_u32 s19, s47, 0
	s_and_b64 s[14:15], s[16:17], exec
	s_cselect_b32 s14, s50, s18
	s_cselect_b32 s15, s51, s19
	s_add_i32 s17, 0, 0x10000
	s_add_i32 s62, 0, 0x14000
	s_add_u32 s26, s24, 0x10080
	s_addc_u32 s27, s25, 0
	s_add_i32 s61, s17, s30
	s_add_i32 m0, s31, 0xc000
	s_add_i32 s64, s31, 0xe000
	s_add_i32 s58, s61, 0x2000
	v_add_u32_e32 v140, s17, v159
	s_add_u32 s24, s22, 0x10000
	ds_read_b128 v[162:165], v140
	ds_read_b128 v[166:169], v140 offset:1024
	ds_read_b128 v[170:173], v140 offset:2048
	ds_read_b128 v[174:177], v140 offset:3072
	v_add_u32_e32 v140, s62, v159
	s_addc_u32 s25, s23, 0
	s_add_i32 s60, s62, s30
	ds_read_b128 v[178:181], v140
	ds_read_b128 v[182:185], v140 offset:1024
	ds_read_b128 v[186:189], v140 offset:2048
	ds_read_b128 v[190:193], v140 offset:3072
	s_add_i32 s59, s60, 0x2000
	s_add_i32 s57, 0, 0x18000
	s_add_i32 s56, 0, 0x1c000
	s_add_u32 s18, s20, 0x10000
	s_addc_u32 s19, s21, 0
	s_add_i32 s55, s57, s30
	s_add_i32 s54, s55, 0x2000
	s_add_u32 s16, s22, 0x10080
	s_addc_u32 s17, s23, 0
	s_add_i32 s63, s56, s30
	s_add_i32 s62, s63, 0x2000
	v_lshl_add_u64 v[140:141], s[26:27], 0, v[128:129]
	ds_read_b128 v[194:197], v160
	ds_read_b128 v[198:201], v160 offset:1024
	ds_read_b128 v[202:205], v160 offset:2048
	ds_read_b128 v[218:221], v160 offset:3072
	ds_read_b128 v[222:225], v160 offset:4096
	ds_read_b128 v[238:241], v160 offset:5120
	ds_read_b128 v[242:245], v160 offset:6144
	ds_read_b128 v[246:249], v160 offset:7168
	global_load_lds_dwordx4 v[140:141], off
	v_lshl_add_u64 v[140:141], s[26:27], 0, v[130:131]
	s_mov_b32 m0, s64
	s_nop 0
	global_load_lds_dwordx4 v[140:141], off
	s_waitcnt vmcnt(8)
	s_waitcnt lgkmcnt(0)
	s_barrier
	s_setprio 1
	s_waitcnt lgkmcnt(0)
	v_mfma_f32_16x16x32_bf16 v[124:127], v[162:165], v[194:197], v[124:127]
	v_mfma_f32_16x16x32_bf16 v[120:123], v[170:173], v[194:197], v[120:123]
	v_mfma_f32_16x16x32_bf16 v[108:111], v[170:173], v[202:205], v[108:111]
	v_mfma_f32_16x16x32_bf16 v[116:119], v[162:165], v[202:205], v[116:119]
	v_mfma_f32_16x16x32_bf16 v[100:103], v[162:165], v[222:225], v[100:103]
	v_mfma_f32_16x16x32_bf16 v[92:95], v[170:173], v[222:225], v[92:95]
	v_mfma_f32_16x16x32_bf16 v[76:79], v[170:173], v[242:245], v[76:79]
	v_mfma_f32_16x16x32_bf16 v[84:87], v[162:165], v[242:245], v[84:87]
	v_mfma_f32_16x16x32_bf16 v[124:127], v[166:169], v[198:201], v[124:127]
	v_mfma_f32_16x16x32_bf16 v[120:123], v[174:177], v[198:201], v[120:123]
	v_mfma_f32_16x16x32_bf16 v[108:111], v[174:177], v[218:221], v[108:111]
	v_mfma_f32_16x16x32_bf16 v[116:119], v[166:169], v[218:221], v[116:119]
	v_mfma_f32_16x16x32_bf16 v[100:103], v[166:169], v[238:241], v[100:103]
	v_mfma_f32_16x16x32_bf16 v[92:95], v[174:177], v[238:241], v[92:95]
	v_mfma_f32_16x16x32_bf16 v[76:79], v[174:177], v[246:249], v[76:79]
	v_mfma_f32_16x16x32_bf16 v[84:87], v[166:169], v[246:249], v[84:87]
	s_setprio 0
	s_setprio 1
	v_mfma_f32_16x16x32_bf16 v[112:115], v[178:181], v[194:197], v[112:115]
	v_mfma_f32_16x16x32_bf16 v[104:107], v[186:189], v[194:197], v[104:107]
	v_mfma_f32_16x16x32_bf16 v[88:91], v[186:189], v[202:205], v[88:91]
	v_mfma_f32_16x16x32_bf16 v[96:99], v[178:181], v[202:205], v[96:99]
	v_mfma_f32_16x16x32_bf16 v[80:83], v[178:181], v[222:225], v[80:83]
	v_mfma_f32_16x16x32_bf16 v[72:75], v[186:189], v[222:225], v[72:75]
	v_mfma_f32_16x16x32_bf16 v[64:67], v[186:189], v[242:245], v[64:67]
	v_mfma_f32_16x16x32_bf16 v[68:71], v[178:181], v[242:245], v[68:71]
	v_mfma_f32_16x16x32_bf16 v[112:115], v[182:185], v[198:201], v[112:115]
	v_mfma_f32_16x16x32_bf16 v[104:107], v[190:193], v[198:201], v[104:107]
	v_mfma_f32_16x16x32_bf16 v[88:91], v[190:193], v[218:221], v[88:91]
	v_mfma_f32_16x16x32_bf16 v[96:99], v[182:185], v[218:221], v[96:99]
	v_mfma_f32_16x16x32_bf16 v[80:83], v[182:185], v[238:241], v[80:83]
	v_mfma_f32_16x16x32_bf16 v[72:75], v[190:193], v[238:241], v[72:75]
	v_mfma_f32_16x16x32_bf16 v[64:67], v[190:193], v[246:249], v[64:67]
	v_mfma_f32_16x16x32_bf16 v[68:71], v[182:185], v[246:249], v[68:71]
	s_setprio 0
	s_barrier
	s_mov_b32 m0, s61
	v_lshl_add_u64 v[140:141], s[22:23], 0, v[134:135]
	ds_read_b128 v[194:197], v160 offset:16384
	ds_read_b128 v[198:201], v160 offset:17408
	ds_read_b128 v[202:205], v160 offset:18432
	ds_read_b128 v[218:221], v160 offset:19456
	ds_read_b128 v[222:225], v160 offset:20480
	ds_read_b128 v[238:241], v160 offset:21504
	ds_read_b128 v[242:245], v160 offset:22528
	ds_read_b128 v[246:249], v160 offset:23552
	global_load_lds_dwordx4 v[140:141], off
	v_lshl_add_u64 v[206:207], s[22:23], 0, v[132:133]
	s_mov_b32 m0, s58
	v_lshl_add_u64 v[250:251], s[24:25], 0, v[134:135]
	global_load_lds_dwordx4 v[206:207], off
	s_mov_b32 m0, s60
	s_nop 0
	global_load_lds_dwordx4 v[250:251], off
	v_lshl_add_u64 v[250:251], s[24:25], 0, v[132:133]
	s_mov_b32 m0, s59
	s_nop 0
	global_load_lds_dwordx4 v[250:251], off
	v_lshl_add_u64 v[250:251], s[20:21], 0, v[128:129]
	s_mov_b32 m0, s31
	s_nop 0
	global_load_lds_dwordx4 v[250:251], off
	v_lshl_add_u64 v[250:251], s[20:21], 0, v[130:131]
	s_mov_b32 m0, s35
	s_nop 0
	global_load_lds_dwordx4 v[250:251], off
	s_waitcnt vmcnt(8)
	s_waitcnt lgkmcnt(0)
	s_barrier
; #define PG8_STAGE(bufoff, gbase, voff) do { _Pragma("unroll") for (int _i = 0; _i < 2; ++_i) \
;         __builtin_amdgcn_global_load_lds((const unsigned*)((const char*)(gbase) + (voff)[_i]), (PG8_LAS unsigned*)(lds + (bufoff) + ldsw + _i * 8192), 16, 0, 0); } while (0)
; #define PG8_LDA(dst, b, h) do { _Pragma("unroll") for (int m = 0; m < 4; ++m) _Pragma("unroll") for (int k = 0; k < 2; ++k) dst[m][k] = *(const PG8_LAS bf16x8*)(lds + PG8_SA(b, h) + aoff + m * 2048 + k * 1024); } while (0)
; #define PG8_LDB(dst, b, h) do { _Pragma("unroll") for (int n = 0; n < 2; ++n) _Pragma("unroll") for (int k = 0; k < 2; ++k) dst[n][k] = *(const PG8_LAS bf16x8*)(lds + PG8_SB(b, h) + boff + n * 2048 + k * 1024); } while (0)
; #define PG8_MMA(ai, bj, At, Bt) do { __builtin_amdgcn_s_setprio(1); _Pragma("unroll") for (int m = 0; m < 4; ++m) _Pragma("unroll") for (int n = 0; n < 2; ++n) _Pragma("unroll") for (int k = 0; k < 2; ++k) \
;         acc[ai][bj][m][n] = __builtin_amdgcn_mfma_f32_16x16x32_bf16(Bt[n][k], At[m][k], acc[ai][bj][m][n], 0, 0, 0); __builtin_amdgcn_s_setprio(0); } while (0)
; #define PG8_WAIT_V(n) asm volatile("s_waitcnt vmcnt(" #n ")" ::: "memory")
; #define PG8_WAIT_L(n) asm volatile("s_waitcnt lgkmcnt(" #n ")" ::: "memory")
; #define PG8_BAR __builtin_amdgcn_s_barrier()
; #define PG8_SCHED __builtin_amdgcn_sched_barrier(0)
;     ...
;             PG8_WAIT_V(8); PG8_WAIT_L(0); PG8_BAR; PG8_MMA(1, 0, At, B0); PG8_MMA(1, 1, At, B1); PG8_BAR; PG8_SCHED;
;             PG8_LDB(B0, 1, 0); PG8_LDB(B1, 1, 1); PG8_SCHED; PG8_LDA(At, 1, 0); PG8_STAGE(PG8_SA(0, 1), a2 + hstepA, voffA);
;             PG8_WAIT_V(8); PG8_WAIT_L(0); PG8_BAR; PG8_MMA(0, 0, At, B0); PG8_MMA(0, 1, At, B1); PG8_BAR; PG8_SCHED;
	s_setprio 1
	s_waitcnt lgkmcnt(0)
	v_mfma_f32_16x16x32_bf16 v[60:63], v[162:165], v[194:197], v[60:63]
	v_mfma_f32_16x16x32_bf16 v[56:59], v[170:173], v[194:197], v[56:59]
	v_mfma_f32_16x16x32_bf16 v[44:47], v[170:173], v[202:205], v[44:47]
	v_mfma_f32_16x16x32_bf16 v[52:55], v[162:165], v[202:205], v[52:55]
	v_mfma_f32_16x16x32_bf16 v[36:39], v[162:165], v[222:225], v[36:39]
	v_mfma_f32_16x16x32_bf16 v[28:31], v[170:173], v[222:225], v[28:31]
	v_mfma_f32_16x16x32_bf16 v[12:15], v[170:173], v[242:245], v[12:15]
	v_mfma_f32_16x16x32_bf16 v[20:23], v[162:165], v[242:245], v[20:23]
	v_mfma_f32_16x16x32_bf16 v[60:63], v[166:169], v[198:201], v[60:63]
	v_mfma_f32_16x16x32_bf16 v[56:59], v[174:177], v[198:201], v[56:59]
	v_mfma_f32_16x16x32_bf16 v[44:47], v[174:177], v[218:221], v[44:47]
	v_mfma_f32_16x16x32_bf16 v[52:55], v[166:169], v[218:221], v[52:55]
	v_mfma_f32_16x16x32_bf16 v[36:39], v[166:169], v[238:241], v[36:39]
	v_mfma_f32_16x16x32_bf16 v[28:31], v[174:177], v[238:241], v[28:31]
	v_mfma_f32_16x16x32_bf16 v[12:15], v[174:177], v[246:249], v[12:15]
	v_mfma_f32_16x16x32_bf16 v[20:23], v[166:169], v[246:249], v[20:23]
	s_setprio 0
	s_setprio 1
	v_mfma_f32_16x16x32_bf16 v[48:51], v[178:181], v[194:197], v[48:51]
	v_mfma_f32_16x16x32_bf16 v[40:43], v[186:189], v[194:197], v[40:43]
	v_mfma_f32_16x16x32_bf16 v[24:27], v[186:189], v[202:205], v[24:27]
	v_mfma_f32_16x16x32_bf16 v[32:35], v[178:181], v[202:205], v[32:35]
	v_mfma_f32_16x16x32_bf16 v[16:19], v[178:181], v[222:225], v[16:19]
	v_mfma_f32_16x16x32_bf16 v[8:11], v[186:189], v[222:225], v[8:11]
	v_mfma_f32_16x16x32_bf16 v[0:3], v[186:189], v[242:245], v[0:3]
	v_mfma_f32_16x16x32_bf16 v[4:7], v[178:181], v[242:245], v[4:7]
	v_mfma_f32_16x16x32_bf16 v[48:51], v[182:185], v[198:201], v[48:51]
	v_mfma_f32_16x16x32_bf16 v[40:43], v[190:193], v[198:201], v[40:43]
	v_mfma_f32_16x16x32_bf16 v[24:27], v[190:193], v[218:221], v[24:27]
	v_mfma_f32_16x16x32_bf16 v[32:35], v[182:185], v[218:221], v[32:35]
	v_mfma_f32_16x16x32_bf16 v[16:19], v[182:185], v[238:241], v[16:19]
	v_mfma_f32_16x16x32_bf16 v[8:11], v[190:193], v[238:241], v[8:11]
	v_mfma_f32_16x16x32_bf16 v[0:3], v[190:193], v[246:249], v[0:3]
	v_mfma_f32_16x16x32_bf16 v[4:7], v[182:185], v[246:249], v[4:7]
	s_setprio 0
	s_barrier
	v_add_u32_e32 v161, s57, v159
	ds_read_b128 v[162:165], v161
	ds_read_b128 v[166:169], v161 offset:1024
	ds_read_b128 v[170:173], v161 offset:2048
	ds_read_b128 v[174:177], v161 offset:3072
	v_add_u32_e32 v161, s56, v159
	ds_read_b128 v[178:181], v161
	ds_read_b128 v[182:185], v161 offset:1024
	ds_read_b128 v[186:189], v161 offset:2048
	ds_read_b128 v[190:193], v161 offset:3072
	s_mov_b32 m0, s36
	v_lshl_add_u64 v[250:251], s[18:19], 0, v[128:129]
	ds_read_b128 v[194:197], v160 offset:32768
	ds_read_b128 v[198:201], v160 offset:33792
	ds_read_b128 v[202:205], v160 offset:34816
	ds_read_b128 v[218:221], v160 offset:35840
	ds_read_b128 v[222:225], v160 offset:36864
	ds_read_b128 v[238:241], v160 offset:37888
	ds_read_b128 v[242:245], v160 offset:38912
	ds_read_b128 v[246:249], v160 offset:39936
	global_load_lds_dwordx4 v[250:251], off
	v_lshl_add_u64 v[250:251], s[18:19], 0, v[130:131]
	s_mov_b32 m0, s37
	s_nop 0
	global_load_lds_dwordx4 v[250:251], off
	s_waitcnt vmcnt(8)
	s_waitcnt lgkmcnt(0)
	s_barrier
	s_setprio 1
	s_waitcnt lgkmcnt(0)
	v_mfma_f32_16x16x32_bf16 v[124:127], v[162:165], v[194:197], v[124:127]
	v_mfma_f32_16x16x32_bf16 v[120:123], v[170:173], v[194:197], v[120:123]
	v_mfma_f32_16x16x32_bf16 v[108:111], v[170:173], v[202:205], v[108:111]
	v_mfma_f32_16x16x32_bf16 v[116:119], v[162:165], v[202:205], v[116:119]
	v_mfma_f32_16x16x32_bf16 v[100:103], v[162:165], v[222:225], v[100:103]
	v_mfma_f32_16x16x32_bf16 v[92:95], v[170:173], v[222:225], v[92:95]
	v_mfma_f32_16x16x32_bf16 v[76:79], v[170:173], v[242:245], v[76:79]
	v_mfma_f32_16x16x32_bf16 v[84:87], v[162:165], v[242:245], v[84:87]
	v_mfma_f32_16x16x32_bf16 v[124:127], v[166:169], v[198:201], v[124:127]
	v_mfma_f32_16x16x32_bf16 v[120:123], v[174:177], v[198:201], v[120:123]
	v_mfma_f32_16x16x32_bf16 v[108:111], v[174:177], v[218:221], v[108:111]
	v_mfma_f32_16x16x32_bf16 v[116:119], v[166:169], v[218:221], v[116:119]
	v_mfma_f32_16x16x32_bf16 v[100:103], v[166:169], v[238:241], v[100:103]
	v_mfma_f32_16x16x32_bf16 v[92:95], v[174:177], v[238:241], v[92:95]
	v_mfma_f32_16x16x32_bf16 v[76:79], v[174:177], v[246:249], v[76:79]
	v_mfma_f32_16x16x32_bf16 v[84:87], v[166:169], v[246:249], v[84:87]
	s_setprio 0
	s_setprio 1
	v_mfma_f32_16x16x32_bf16 v[112:115], v[178:181], v[194:197], v[112:115]
	v_mfma_f32_16x16x32_bf16 v[104:107], v[186:189], v[194:197], v[104:107]
	v_mfma_f32_16x16x32_bf16 v[88:91], v[186:189], v[202:205], v[88:91]
	v_mfma_f32_16x16x32_bf16 v[96:99], v[178:181], v[202:205], v[96:99]
	v_mfma_f32_16x16x32_bf16 v[80:83], v[178:181], v[222:225], v[80:83]
	v_mfma_f32_16x16x32_bf16 v[72:75], v[186:189], v[222:225], v[72:75]
	v_mfma_f32_16x16x32_bf16 v[64:67], v[186:189], v[242:245], v[64:67]
	v_mfma_f32_16x16x32_bf16 v[68:71], v[178:181], v[242:245], v[68:71]
	v_mfma_f32_16x16x32_bf16 v[112:115], v[182:185], v[198:201], v[112:115]
	v_mfma_f32_16x16x32_bf16 v[104:107], v[190:193], v[198:201], v[104:107]
	v_mfma_f32_16x16x32_bf16 v[88:91], v[190:193], v[218:221], v[88:91]
	v_mfma_f32_16x16x32_bf16 v[96:99], v[182:185], v[218:221], v[96:99]
	v_mfma_f32_16x16x32_bf16 v[80:83], v[182:185], v[238:241], v[80:83]
	v_mfma_f32_16x16x32_bf16 v[72:75], v[190:193], v[238:241], v[72:75]
	v_mfma_f32_16x16x32_bf16 v[64:67], v[190:193], v[246:249], v[64:67]
	v_mfma_f32_16x16x32_bf16 v[68:71], v[182:185], v[246:249], v[68:71]
	s_setprio 0
	s_barrier
; #define PG8_STAGE(bufoff, gbase, voff) do { _Pragma("unroll") for (int _i = 0; _i < 2; ++_i) \
;         __builtin_amdgcn_global_load_lds((const unsigned*)((const char*)(gbase) + (voff)[_i]), (PG8_LAS unsigned*)(lds + (bufoff) + ldsw + _i * 8192), 16, 0, 0); } while (0)
; #define PG8_LDA(dst, b, h) do { _Pragma("unroll") for (int m = 0; m < 4; ++m) _Pragma("unroll") for (int k = 0; k < 2; ++k) dst[m][k] = *(const PG8_LAS bf16x8*)(lds + PG8_SA(b, h) + aoff + m * 2048 + k * 1024); } while (0)
; #define PG8_MMA(ai, bj, At, Bt) do { __builtin_amdgcn_s_setprio(1); _Pragma("unroll") for (int m = 0; m < 4; ++m) _Pragma("unroll") for (int n = 0; n < 2; ++n) _Pragma("unroll") for (int k = 0; k < 2; ++k) \
;         acc[ai][bj][m][n] = __builtin_amdgcn_mfma_f32_16x16x32_bf16(Bt[n][k], At[m][k], acc[ai][bj][m][n], 0, 0, 0); __builtin_amdgcn_s_setprio(0); } while (0)
; #define PG8_WAIT_V(n) asm volatile("s_waitcnt vmcnt(" #n ")" ::: "memory")
; #define PG8_WAIT_L(n) asm volatile("s_waitcnt lgkmcnt(" #n ")" ::: "memory")
; #define PG8_BAR __builtin_amdgcn_s_barrier()
; #define PG8_SCHED __builtin_amdgcn_sched_barrier(0)
;     ...
;             PG8_LDA(At, 1, 1); PG8_STAGE(PG8_SB(1, 0), b3, voffB); PG8_STAGE(PG8_SB(1, 1), b3 + hstepB, voffB); PG8_STAGE(PG8_SA(1, 0), a3, voffA);
;             PG8_WAIT_V(8); PG8_WAIT_L(0); PG8_BAR; PG8_MMA(1, 0, At, B0); PG8_MMA(1, 1, At, B1); PG8_BAR; PG8_SCHED;
;         }
;         if (wr == 0) PG8_BAR;
	s_mov_b32 m0, s55
	v_lshl_add_u64 v[140:141], v[140:141], 0, s[66:67]
	ds_read_b128 v[194:197], v160 offset:49152
	ds_read_b128 v[198:201], v160 offset:50176
	ds_read_b128 v[202:205], v160 offset:51200
	ds_read_b128 v[218:221], v160 offset:52224
	ds_read_b128 v[222:225], v160 offset:53248
	ds_read_b128 v[238:241], v160 offset:54272
	ds_read_b128 v[242:245], v160 offset:55296
	ds_read_b128 v[246:249], v160 offset:56320
	global_load_lds_dwordx4 v[140:141], off
	v_lshl_add_u64 v[140:141], v[206:207], 0, s[66:67]
	s_mov_b32 m0, s54
	s_nop 0
	global_load_lds_dwordx4 v[140:141], off
	v_lshl_add_u64 v[140:141], s[16:17], 0, v[134:135]
	s_mov_b32 m0, s63
	s_nop 0
	global_load_lds_dwordx4 v[140:141], off
	v_lshl_add_u64 v[140:141], s[16:17], 0, v[132:133]
	s_mov_b32 m0, s62
	s_nop 0
	global_load_lds_dwordx4 v[140:141], off
	v_lshl_add_u64 v[140:141], s[14:15], 0, v[128:129]
	s_mov_b32 m0, s40
	s_nop 0
	global_load_lds_dwordx4 v[140:141], off
	v_lshl_add_u64 v[140:141], s[14:15], 0, v[130:131]
	s_mov_b32 m0, s41
	s_nop 0
	global_load_lds_dwordx4 v[140:141], off
	s_waitcnt vmcnt(8)
	s_waitcnt lgkmcnt(0)
	s_barrier
	s_setprio 1
	s_waitcnt lgkmcnt(0)
	v_mfma_f32_16x16x32_bf16 v[60:63], v[162:165], v[194:197], v[60:63]
	v_mfma_f32_16x16x32_bf16 v[56:59], v[170:173], v[194:197], v[56:59]
	v_mfma_f32_16x16x32_bf16 v[44:47], v[170:173], v[202:205], v[44:47]
	v_mfma_f32_16x16x32_bf16 v[52:55], v[162:165], v[202:205], v[52:55]
	v_mfma_f32_16x16x32_bf16 v[36:39], v[162:165], v[222:225], v[36:39]
	v_mfma_f32_16x16x32_bf16 v[28:31], v[170:173], v[222:225], v[28:31]
	v_mfma_f32_16x16x32_bf16 v[12:15], v[170:173], v[242:245], v[12:15]
	v_mfma_f32_16x16x32_bf16 v[20:23], v[162:165], v[242:245], v[20:23]
	v_mfma_f32_16x16x32_bf16 v[60:63], v[166:169], v[198:201], v[60:63]
	v_mfma_f32_16x16x32_bf16 v[56:59], v[174:177], v[198:201], v[56:59]
	v_mfma_f32_16x16x32_bf16 v[44:47], v[174:177], v[218:221], v[44:47]
	v_mfma_f32_16x16x32_bf16 v[52:55], v[166:169], v[218:221], v[52:55]
	v_mfma_f32_16x16x32_bf16 v[36:39], v[166:169], v[238:241], v[36:39]
	v_mfma_f32_16x16x32_bf16 v[28:31], v[174:177], v[238:241], v[28:31]
	v_mfma_f32_16x16x32_bf16 v[12:15], v[174:177], v[246:249], v[12:15]
	v_mfma_f32_16x16x32_bf16 v[20:23], v[166:169], v[246:249], v[20:23]
	s_setprio 0
	s_setprio 1
	v_mfma_f32_16x16x32_bf16 v[48:51], v[178:181], v[194:197], v[48:51]
	v_mfma_f32_16x16x32_bf16 v[40:43], v[186:189], v[194:197], v[40:43]
	v_mfma_f32_16x16x32_bf16 v[24:27], v[186:189], v[202:205], v[24:27]
	v_mfma_f32_16x16x32_bf16 v[32:35], v[178:181], v[202:205], v[32:35]
	v_mfma_f32_16x16x32_bf16 v[16:19], v[178:181], v[222:225], v[16:19]
	v_mfma_f32_16x16x32_bf16 v[8:11], v[186:189], v[222:225], v[8:11]
	v_mfma_f32_16x16x32_bf16 v[0:3], v[186:189], v[242:245], v[0:3]
	v_mfma_f32_16x16x32_bf16 v[4:7], v[178:181], v[242:245], v[4:7]
	v_mfma_f32_16x16x32_bf16 v[48:51], v[182:185], v[198:201], v[48:51]
	v_mfma_f32_16x16x32_bf16 v[40:43], v[190:193], v[198:201], v[40:43]
	v_mfma_f32_16x16x32_bf16 v[24:27], v[190:193], v[218:221], v[24:27]
	v_mfma_f32_16x16x32_bf16 v[32:35], v[182:185], v[218:221], v[32:35]
	v_mfma_f32_16x16x32_bf16 v[16:19], v[182:185], v[238:241], v[16:19]
	v_mfma_f32_16x16x32_bf16 v[8:11], v[190:193], v[238:241], v[8:11]
	v_mfma_f32_16x16x32_bf16 v[0:3], v[190:193], v[246:249], v[0:3]
	v_mfma_f32_16x16x32_bf16 v[4:7], v[182:185], v[246:249], v[4:7]
	s_setprio 0
	s_barrier
	s_andn2_b64 vcc, exec, s[12:13]
	s_mov_b64 s[16:17], -1
	s_mov_b64 s[12:13], 0
	s_movk_i32 s14, 0x100
	s_cbranch_vccz .LBB0_785
	s_and_b64 vcc, exec, s[4:5]
	s_cbranch_vccz .LBB0_788
	s_barrier

;     __device__ __forceinline__ unsigned voff(int R, int C) const { return (unsigned)(R * K + C) * 2u; }
;     __device__ __forceinline__ size_t hstep() const { return (size_t)HALF * K * 2; }
;     __device__ __forceinline__ const char* tile(const Unit& u, int t) const { return A + (size_t)u.pm * 2 * hstep() + (size_t)t * (BK * 2); }
; #define PG8_STAGE(bufoff, gbase, voff) do { _Pragma("unroll") for (int _i = 0; _i < 2; ++_i) \
;         __builtin_amdgcn_global_load_lds((const unsigned*)((const char*)(gbase) + (voff)[_i]), (PG8_LAS unsigned*)(lds + (bufoff) + ldsw + _i * 8192), 16, 0, 0); } while (0)
; #define PG8_LDA(dst, b, h) do { _Pragma("unroll") for (int m = 0; m < 4; ++m) _Pragma("unroll") for (int k = 0; k < 2; ++k) dst[m][k] = *(const PG8_LAS bf16x8*)(lds + PG8_SA(b, h) + aoff + m * 2048 + k * 1024); } while (0)
; #define PG8_LDB(dst, b, h) do { _Pragma("unroll") for (int n = 0; n < 2; ++n) _Pragma("unroll") for (int k = 0; k < 2; ++k) dst[n][k] = *(const PG8_LAS bf16x8*)(lds + PG8_SB(b, h) + boff + n * 2048 + k * 1024); } while (0)
; #define PG8_WAIT_V(n) asm volatile("s_waitcnt vmcnt(" #n ")" ::: "memory")
;     __device__ __forceinline__ unsigned voff(int R, int C) const { return (unsigned)(R * 256 + C) * 2u; }
;     __device__ __forceinline__ size_t hstep() const { return (size_t)HALF * 512; }
;     __device__ __forceinline__ const char* tile(const Unit& u, int t) const { return U + (long)(t >> 2) * xoff + (size_t)u.pn * (1024 * 512) + (size_t)u.pm * 2 * hstep() + (size_t)(t & 3) * (BK * 2); }
;     ...
;             const bool last = (t == nt - 2);
;             const char* a1 = AS.tile(cur, t + 1);
;             const char* a2 = last ? AS.tile(nu, 0) : AS.tile(cur, t + 2); const char* b2 = last ? nB : cB + (size_t)(t + 2) * kstep;
;             const char* a3 = last ? AS.tile(nu, 1) : AS.tile(cur, t + 3); const char* b3 = b2 + kstep;
;             PG8_LDB(B0, 0, 0); PG8_LDB(B1, 0, 1); PG8_SCHED; PG8_LDA(At, 0, 0); PG8_STAGE(PG8_SA(1, 1), a1 + hstepA, voffA);
;             PG8_WAIT_V(8); PG8_WAIT_L(0); PG8_BAR; PG8_MMA(0, 0, At, B0); PG8_MMA(0, 1, At, B1); PG8_BAR; PG8_SCHED;
;             PG8_LDA(At, 0, 1); PG8_STAGE(PG8_SB(0, 0), b2, voffB); PG8_STAGE(PG8_SB(0, 1), b2 + hstepB, voffB); PG8_STAGE(PG8_SA(0, 0), a2, voffA);
;             PG8_WAIT_V(8); PG8_WAIT_L(0); PG8_BAR; PG8_MMA(1, 0, At, B0); PG8_MMA(1, 1, At, B1); PG8_BAR; PG8_SCHED;
.LBB0_833:
	s_add_u32 s47, s44, s16
	s_addc_u32 s48, s45, s17
	s_and_b64 s[20:21], exec, s[20:21]
	s_cselect_b32 s21, s43, s48
	s_cselect_b32 s20, s42, s47
	s_add_i32 s47, s46, -3
	s_lshr_b32 s48, s47, 2
	s_mul_i32 s48, s48, 0x6000000
	s_add_u32 s48, s1, s48
	s_addc_u32 s49, s3, 0
	s_and_b32 s50, s16, 0x100
	s_add_u32 s48, s48, s50
	s_addc_u32 s49, s49, 0
	s_add_i32 s50, 0, 0x10000
	v_add_u32_e32 v137, s50, v144
	s_add_i32 s51, 0, 0x14000
	ds_read_b128 v[148:151], v137
	ds_read_b128 v[152:155], v137 offset:1024
	ds_read_b128 v[156:159], v137 offset:2048
	ds_read_b128 v[160:163], v137 offset:3072
	v_add_u32_e32 v137, s51, v144
	ds_read_b128 v[164:167], v137
	ds_read_b128 v[168:171], v137 offset:1024
	ds_read_b128 v[172:175], v137 offset:2048
	ds_read_b128 v[176:179], v137 offset:3072
	s_add_u32 s48, s48, 0x10080
	s_addc_u32 s49, s49, 0
	v_lshl_add_u64 v[140:141], s[48:49], 0, v[128:129]
	s_add_i32 m0, s27, 0xc000
	ds_read_b128 v[180:183], v142
	ds_read_b128 v[184:187], v142 offset:1024
	ds_read_b128 v[188:191], v142 offset:2048
	ds_read_b128 v[192:195], v142 offset:3072
	ds_read_b128 v[196:199], v142 offset:4096
	ds_read_b128 v[200:203], v142 offset:5120
	ds_read_b128 v[204:207], v142 offset:6144
	ds_read_b128 v[218:221], v142 offset:7168
	global_load_lds_dwordx4 v[140:141], off
	v_lshl_add_u64 v[140:141], s[48:49], 0, v[130:131]
	s_add_i32 m0, s27, 0xe000
	s_nop 0
	global_load_lds_dwordx4 v[140:141], off
	s_waitcnt vmcnt(8)
	s_waitcnt lgkmcnt(0)
	s_barrier
	s_setprio 1
	s_waitcnt lgkmcnt(0)
	v_mfma_f32_16x16x32_bf16 v[124:127], v[148:151], v[180:183], v[124:127]
	v_mfma_f32_16x16x32_bf16 v[120:123], v[156:159], v[180:183], v[120:123]
	v_mfma_f32_16x16x32_bf16 v[104:107], v[156:159], v[188:191], v[104:107]
	v_mfma_f32_16x16x32_bf16 v[108:111], v[148:151], v[188:191], v[108:111]
	v_mfma_f32_16x16x32_bf16 v[92:95], v[148:151], v[196:199], v[92:95]
	v_mfma_f32_16x16x32_bf16 v[88:91], v[156:159], v[196:199], v[88:91]
	v_mfma_f32_16x16x32_bf16 v[72:75], v[156:159], v[204:207], v[72:75]
	v_mfma_f32_16x16x32_bf16 v[76:79], v[148:151], v[204:207], v[76:79]
	v_mfma_f32_16x16x32_bf16 v[124:127], v[152:155], v[184:187], v[124:127]
	v_mfma_f32_16x16x32_bf16 v[120:123], v[160:163], v[184:187], v[120:123]
	v_mfma_f32_16x16x32_bf16 v[104:107], v[160:163], v[192:195], v[104:107]
	v_mfma_f32_16x16x32_bf16 v[108:111], v[152:155], v[192:195], v[108:111]
	v_mfma_f32_16x16x32_bf16 v[92:95], v[152:155], v[200:203], v[92:95]
	v_mfma_f32_16x16x32_bf16 v[88:91], v[160:163], v[200:203], v[88:91]
	v_mfma_f32_16x16x32_bf16 v[72:75], v[160:163], v[218:221], v[72:75]
	v_mfma_f32_16x16x32_bf16 v[76:79], v[152:155], v[218:221], v[76:79]
	s_setprio 0
	s_setprio 1
	v_mfma_f32_16x16x32_bf16 v[116:119], v[164:167], v[180:183], v[116:119]
	v_mfma_f32_16x16x32_bf16 v[112:115], v[172:175], v[180:183], v[112:115]
	v_mfma_f32_16x16x32_bf16 v[96:99], v[172:175], v[188:191], v[96:99]
	v_mfma_f32_16x16x32_bf16 v[100:103], v[164:167], v[188:191], v[100:103]
	v_mfma_f32_16x16x32_bf16 v[84:87], v[164:167], v[196:199], v[84:87]
	v_mfma_f32_16x16x32_bf16 v[80:83], v[172:175], v[196:199], v[80:83]
	v_mfma_f32_16x16x32_bf16 v[64:67], v[172:175], v[204:207], v[64:67]
	v_mfma_f32_16x16x32_bf16 v[68:71], v[164:167], v[204:207], v[68:71]
	v_mfma_f32_16x16x32_bf16 v[116:119], v[168:171], v[184:187], v[116:119]
	v_mfma_f32_16x16x32_bf16 v[112:115], v[176:179], v[184:187], v[112:115]
	v_mfma_f32_16x16x32_bf16 v[96:99], v[176:179], v[192:195], v[96:99]
	v_mfma_f32_16x16x32_bf16 v[100:103], v[168:171], v[192:195], v[100:103]
	v_mfma_f32_16x16x32_bf16 v[84:87], v[168:171], v[200:203], v[84:87]
	v_mfma_f32_16x16x32_bf16 v[80:83], v[176:179], v[200:203], v[80:83]
	v_mfma_f32_16x16x32_bf16 v[64:67], v[176:179], v[218:221], v[64:67]
	v_mfma_f32_16x16x32_bf16 v[68:71], v[168:171], v[218:221], v[68:71]
	s_setprio 0
	s_barrier
	s_add_i32 s48, s50, s26
	v_lshl_add_u64 v[140:141], s[20:21], 0, v[134:135]
	s_mov_b32 m0, s48
	ds_read_b128 v[180:183], v142 offset:16384
	ds_read_b128 v[184:187], v142 offset:17408
	ds_read_b128 v[188:191], v142 offset:18432
	ds_read_b128 v[192:195], v142 offset:19456
	ds_read_b128 v[196:199], v142 offset:20480
	ds_read_b128 v[200:203], v142 offset:21504
	ds_read_b128 v[204:207], v142 offset:22528
	ds_read_b128 v[218:221], v142 offset:23552
	global_load_lds_dwordx4 v[140:141], off
	s_add_i32 m0, s48, 0x2000
	s_add_u32 s48, s20, 0x20000
	v_lshl_add_u64 v[222:223], s[20:21], 0, v[132:133]
	s_addc_u32 s49, s21, 0
	s_add_i32 s50, s51, s26
	global_load_lds_dwordx4 v[222:223], off
	v_lshl_add_u64 v[224:225], s[48:49], 0, v[134:135]
	s_mov_b32 m0, s50
	s_nop 0
	global_load_lds_dwordx4 v[224:225], off
	v_lshl_add_u64 v[224:225], s[48:49], 0, v[132:133]
	s_add_i32 m0, s50, 0x2000
	s_nop 0
	global_load_lds_dwordx4 v[224:225], off
	v_lshl_add_u64 v[224:225], s[22:23], 0, v[128:129]
	s_mov_b32 m0, s27
	s_nop 0
	global_load_lds_dwordx4 v[224:225], off
	v_lshl_add_u64 v[224:225], s[22:23], 0, v[130:131]
	s_mov_b32 m0, s28
	s_nop 0
	global_load_lds_dwordx4 v[224:225], off
	s_waitcnt vmcnt(8)
	s_waitcnt lgkmcnt(0)
	s_barrier
; #define PG8_STAGE(bufoff, gbase, voff) do { _Pragma("unroll") for (int _i = 0; _i < 2; ++_i) \
;         __builtin_amdgcn_global_load_lds((const unsigned*)((const char*)(gbase) + (voff)[_i]), (PG8_LAS unsigned*)(lds + (bufoff) + ldsw + _i * 8192), 16, 0, 0); } while (0)
; #define PG8_LDA(dst, b, h) do { _Pragma("unroll") for (int m = 0; m < 4; ++m) _Pragma("unroll") for (int k = 0; k < 2; ++k) dst[m][k] = *(const PG8_LAS bf16x8*)(lds + PG8_SA(b, h) + aoff + m * 2048 + k * 1024); } while (0)
; #define PG8_LDB(dst, b, h) do { _Pragma("unroll") for (int n = 0; n < 2; ++n) _Pragma("unroll") for (int k = 0; k < 2; ++k) dst[n][k] = *(const PG8_LAS bf16x8*)(lds + PG8_SB(b, h) + boff + n * 2048 + k * 1024); } while (0)
; #define PG8_MMA(ai, bj, At, Bt) do { __builtin_amdgcn_s_setprio(1); _Pragma("unroll") for (int m = 0; m < 4; ++m) _Pragma("unroll") for (int n = 0; n < 2; ++n) _Pragma("unroll") for (int k = 0; k < 2; ++k) \
;         acc[ai][bj][m][n] = __builtin_amdgcn_mfma_f32_16x16x32_bf16(Bt[n][k], At[m][k], acc[ai][bj][m][n], 0, 0, 0); __builtin_amdgcn_s_setprio(0); } while (0)
; #define PG8_WAIT_V(n) asm volatile("s_waitcnt vmcnt(" #n ")" ::: "memory")
; #define PG8_WAIT_L(n) asm volatile("s_waitcnt lgkmcnt(" #n ")" ::: "memory")
; #define PG8_BAR __builtin_amdgcn_s_barrier()
; #define PG8_SCHED __builtin_amdgcn_sched_barrier(0)
;     ...
;             PG8_WAIT_V(8); PG8_WAIT_L(0); PG8_BAR; PG8_MMA(1, 0, At, B0); PG8_MMA(1, 1, At, B1); PG8_BAR; PG8_SCHED;
;             PG8_LDB(B0, 1, 0); PG8_LDB(B1, 1, 1); PG8_SCHED; PG8_LDA(At, 1, 0); PG8_STAGE(PG8_SA(0, 1), a2 + hstepA, voffA);
;             PG8_WAIT_V(8); PG8_WAIT_L(0); PG8_BAR; PG8_MMA(0, 0, At, B0); PG8_MMA(0, 1, At, B1); PG8_BAR; PG8_SCHED;
	s_setprio 1
	s_waitcnt lgkmcnt(0)
	v_mfma_f32_16x16x32_bf16 v[60:63], v[148:151], v[180:183], v[60:63]
	v_mfma_f32_16x16x32_bf16 v[56:59], v[156:159], v[180:183], v[56:59]
	v_mfma_f32_16x16x32_bf16 v[40:43], v[156:159], v[188:191], v[40:43]
	v_mfma_f32_16x16x32_bf16 v[44:47], v[148:151], v[188:191], v[44:47]
	v_mfma_f32_16x16x32_bf16 v[28:31], v[148:151], v[196:199], v[28:31]
	v_mfma_f32_16x16x32_bf16 v[24:27], v[156:159], v[196:199], v[24:27]
	v_mfma_f32_16x16x32_bf16 v[8:11], v[156:159], v[204:207], v[8:11]
	v_mfma_f32_16x16x32_bf16 v[12:15], v[148:151], v[204:207], v[12:15]
	v_mfma_f32_16x16x32_bf16 v[60:63], v[152:155], v[184:187], v[60:63]
	v_mfma_f32_16x16x32_bf16 v[56:59], v[160:163], v[184:187], v[56:59]
	v_mfma_f32_16x16x32_bf16 v[40:43], v[160:163], v[192:195], v[40:43]
	v_mfma_f32_16x16x32_bf16 v[44:47], v[152:155], v[192:195], v[44:47]
	v_mfma_f32_16x16x32_bf16 v[28:31], v[152:155], v[200:203], v[28:31]
	v_mfma_f32_16x16x32_bf16 v[24:27], v[160:163], v[200:203], v[24:27]
	v_mfma_f32_16x16x32_bf16 v[8:11], v[160:163], v[218:221], v[8:11]
	v_mfma_f32_16x16x32_bf16 v[12:15], v[152:155], v[218:221], v[12:15]
	s_setprio 0
	s_setprio 1
	v_mfma_f32_16x16x32_bf16 v[52:55], v[164:167], v[180:183], v[52:55]
	v_mfma_f32_16x16x32_bf16 v[48:51], v[172:175], v[180:183], v[48:51]
	v_mfma_f32_16x16x32_bf16 v[32:35], v[172:175], v[188:191], v[32:35]
	v_mfma_f32_16x16x32_bf16 v[36:39], v[164:167], v[188:191], v[36:39]
	v_mfma_f32_16x16x32_bf16 v[20:23], v[164:167], v[196:199], v[20:23]
	v_mfma_f32_16x16x32_bf16 v[16:19], v[172:175], v[196:199], v[16:19]
	v_mfma_f32_16x16x32_bf16 v[0:3], v[172:175], v[204:207], v[0:3]
	v_mfma_f32_16x16x32_bf16 v[4:7], v[164:167], v[204:207], v[4:7]
	v_mfma_f32_16x16x32_bf16 v[52:55], v[168:171], v[184:187], v[52:55]
	v_mfma_f32_16x16x32_bf16 v[48:51], v[176:179], v[184:187], v[48:51]
	v_mfma_f32_16x16x32_bf16 v[32:35], v[176:179], v[192:195], v[32:35]
	v_mfma_f32_16x16x32_bf16 v[36:39], v[168:171], v[192:195], v[36:39]
	v_mfma_f32_16x16x32_bf16 v[20:23], v[168:171], v[200:203], v[20:23]
	v_mfma_f32_16x16x32_bf16 v[16:19], v[176:179], v[200:203], v[16:19]
	v_mfma_f32_16x16x32_bf16 v[0:3], v[176:179], v[218:221], v[0:3]
	v_mfma_f32_16x16x32_bf16 v[4:7], v[168:171], v[218:221], v[4:7]
	s_setprio 0
	s_barrier
	s_add_i32 s48, 0, 0x18000
	v_add_u32_e32 v137, s48, v144
	s_add_i32 s49, 0, 0x1c000
	ds_read_b128 v[148:151], v137
	ds_read_b128 v[152:155], v137 offset:1024
	ds_read_b128 v[156:159], v137 offset:2048
	ds_read_b128 v[160:163], v137 offset:3072
	v_add_u32_e32 v137, s49, v144
	ds_read_b128 v[164:167], v137
	ds_read_b128 v[168:171], v137 offset:1024
	ds_read_b128 v[172:175], v137 offset:2048
	ds_read_b128 v[176:179], v137 offset:3072
	s_add_u32 s22, s22, 0x10000
	s_addc_u32 s23, s23, 0
	s_mov_b32 m0, s29
	v_lshl_add_u64 v[224:225], s[22:23], 0, v[128:129]
	ds_read_b128 v[180:183], v142 offset:32768
	ds_read_b128 v[184:187], v142 offset:33792
	ds_read_b128 v[188:191], v142 offset:34816
	ds_read_b128 v[192:195], v142 offset:35840
	ds_read_b128 v[196:199], v142 offset:36864
	ds_read_b128 v[200:203], v142 offset:37888
	ds_read_b128 v[204:207], v142 offset:38912
	ds_read_b128 v[218:221], v142 offset:39936
	global_load_lds_dwordx4 v[224:225], off
	v_lshl_add_u64 v[224:225], s[22:23], 0, v[130:131]
	s_mov_b32 m0, s30
	s_nop 0
	global_load_lds_dwordx4 v[224:225], off
	s_waitcnt vmcnt(8)
	s_waitcnt lgkmcnt(0)
	s_barrier
	s_setprio 1
	s_waitcnt lgkmcnt(0)
	v_mfma_f32_16x16x32_bf16 v[124:127], v[148:151], v[180:183], v[124:127]
	v_mfma_f32_16x16x32_bf16 v[120:123], v[156:159], v[180:183], v[120:123]
	v_mfma_f32_16x16x32_bf16 v[104:107], v[156:159], v[188:191], v[104:107]
	v_mfma_f32_16x16x32_bf16 v[108:111], v[148:151], v[188:191], v[108:111]
	v_mfma_f32_16x16x32_bf16 v[92:95], v[148:151], v[196:199], v[92:95]
	v_mfma_f32_16x16x32_bf16 v[88:91], v[156:159], v[196:199], v[88:91]
	v_mfma_f32_16x16x32_bf16 v[72:75], v[156:159], v[204:207], v[72:75]
	v_mfma_f32_16x16x32_bf16 v[76:79], v[148:151], v[204:207], v[76:79]
	v_mfma_f32_16x16x32_bf16 v[124:127], v[152:155], v[184:187], v[124:127]
	v_mfma_f32_16x16x32_bf16 v[120:123], v[160:163], v[184:187], v[120:123]
	v_mfma_f32_16x16x32_bf16 v[104:107], v[160:163], v[192:195], v[104:107]
	v_mfma_f32_16x16x32_bf16 v[108:111], v[152:155], v[192:195], v[108:111]
	v_mfma_f32_16x16x32_bf16 v[92:95], v[152:155], v[200:203], v[92:95]
	v_mfma_f32_16x16x32_bf16 v[88:91], v[160:163], v[200:203], v[88:91]
	v_mfma_f32_16x16x32_bf16 v[72:75], v[160:163], v[218:221], v[72:75]
	v_mfma_f32_16x16x32_bf16 v[76:79], v[152:155], v[218:221], v[76:79]
	s_setprio 0
	s_setprio 1
	v_mfma_f32_16x16x32_bf16 v[116:119], v[164:167], v[180:183], v[116:119]
	v_mfma_f32_16x16x32_bf16 v[112:115], v[172:175], v[180:183], v[112:115]
	v_mfma_f32_16x16x32_bf16 v[96:99], v[172:175], v[188:191], v[96:99]
	v_mfma_f32_16x16x32_bf16 v[100:103], v[164:167], v[188:191], v[100:103]
	v_mfma_f32_16x16x32_bf16 v[84:87], v[164:167], v[196:199], v[84:87]
	v_mfma_f32_16x16x32_bf16 v[80:83], v[172:175], v[196:199], v[80:83]
	v_mfma_f32_16x16x32_bf16 v[64:67], v[172:175], v[204:207], v[64:67]
	v_mfma_f32_16x16x32_bf16 v[68:71], v[164:167], v[204:207], v[68:71]
	v_mfma_f32_16x16x32_bf16 v[116:119], v[168:171], v[184:187], v[116:119]
	v_mfma_f32_16x16x32_bf16 v[112:115], v[176:179], v[184:187], v[112:115]
	v_mfma_f32_16x16x32_bf16 v[96:99], v[176:179], v[192:195], v[96:99]
	v_mfma_f32_16x16x32_bf16 v[100:103], v[168:171], v[192:195], v[100:103]
	v_mfma_f32_16x16x32_bf16 v[84:87], v[168:171], v[200:203], v[84:87]
	v_mfma_f32_16x16x32_bf16 v[80:83], v[176:179], v[200:203], v[80:83]
	v_mfma_f32_16x16x32_bf16 v[64:67], v[176:179], v[218:221], v[64:67]
	v_mfma_f32_16x16x32_bf16 v[68:71], v[168:171], v[218:221], v[68:71]
	s_setprio 0
	s_barrier
; #define PG8_STAGE(bufoff, gbase, voff) do { _Pragma("unroll") for (int _i = 0; _i < 2; ++_i) \
;         __builtin_amdgcn_global_load_lds((const unsigned*)((const char*)(gbase) + (voff)[_i]), (PG8_LAS unsigned*)(lds + (bufoff) + ldsw + _i * 8192), 16, 0, 0); } while (0)
; #define PG8_LDA(dst, b, h) do { _Pragma("unroll") for (int m = 0; m < 4; ++m) _Pragma("unroll") for (int k = 0; k < 2; ++k) dst[m][k] = *(const PG8_LAS bf16x8*)(lds + PG8_SA(b, h) + aoff + m * 2048 + k * 1024); } while (0)
; #define PG8_MMA(ai, bj, At, Bt) do { __builtin_amdgcn_s_setprio(1); _Pragma("unroll") for (int m = 0; m < 4; ++m) _Pragma("unroll") for (int n = 0; n < 2; ++n) _Pragma("unroll") for (int k = 0; k < 2; ++k) \
;         acc[ai][bj][m][n] = __builtin_amdgcn_mfma_f32_16x16x32_bf16(Bt[n][k], At[m][k], acc[ai][bj][m][n], 0, 0, 0); __builtin_amdgcn_s_setprio(0); } while (0)
; #define PG8_WAIT_V(n) asm volatile("s_waitcnt vmcnt(" #n ")" ::: "memory")
; #define PG8_WAIT_L(n) asm volatile("s_waitcnt lgkmcnt(" #n ")" ::: "memory")
; #define PG8_BAR __builtin_amdgcn_s_barrier()
; #define PG8_SCHED __builtin_amdgcn_sched_barrier(0)
;     ...
;             PG8_LDA(At, 1, 1); PG8_STAGE(PG8_SB(1, 0), b3, voffB); PG8_STAGE(PG8_SB(1, 1), b3 + hstepB, voffB); PG8_STAGE(PG8_SA(1, 0), a3, voffA);
;             PG8_WAIT_V(8); PG8_WAIT_L(0); PG8_BAR; PG8_MMA(1, 0, At, B0); PG8_MMA(1, 1, At, B1); PG8_BAR; PG8_SCHED;
;         }
	s_mov_b64 s[50:51], 0x80
	s_add_i32 s22, s48, s26
	v_lshl_add_u64 v[140:141], v[140:141], 0, s[50:51]
	s_mov_b32 m0, s22
	ds_read_b128 v[180:183], v142 offset:49152
	ds_read_b128 v[184:187], v142 offset:50176
	ds_read_b128 v[188:191], v142 offset:51200
	ds_read_b128 v[192:195], v142 offset:52224
	ds_read_b128 v[196:199], v142 offset:53248
	ds_read_b128 v[200:203], v142 offset:54272
	ds_read_b128 v[204:207], v142 offset:55296
	ds_read_b128 v[218:221], v142 offset:56320
	global_load_lds_dwordx4 v[140:141], off
	s_add_i32 m0, s22, 0x2000
	s_add_u32 s20, s20, 0x20080
	v_lshl_add_u64 v[140:141], v[222:223], 0, s[50:51]
	s_addc_u32 s21, s21, 0
	s_add_i32 s22, s49, s26
	global_load_lds_dwordx4 v[140:141], off
	v_lshl_add_u64 v[140:141], s[20:21], 0, v[134:135]
	s_mov_b32 m0, s22
	s_nop 0
	global_load_lds_dwordx4 v[140:141], off
	v_lshl_add_u64 v[140:141], s[20:21], 0, v[132:133]
	s_add_i32 m0, s22, 0x2000
	s_nop 0
	global_load_lds_dwordx4 v[140:141], off
	v_lshl_add_u64 v[140:141], s[18:19], 0, v[128:129]
	s_mov_b32 m0, s31
	s_nop 0
	global_load_lds_dwordx4 v[140:141], off
	v_lshl_add_u64 v[140:141], s[18:19], 0, v[130:131]
	s_mov_b32 m0, s34
	s_nop 0
	global_load_lds_dwordx4 v[140:141], off
	s_waitcnt vmcnt(8)
	s_waitcnt lgkmcnt(0)
	s_barrier
	s_setprio 1
	s_waitcnt lgkmcnt(0)
	v_mfma_f32_16x16x32_bf16 v[60:63], v[148:151], v[180:183], v[60:63]
	v_mfma_f32_16x16x32_bf16 v[56:59], v[156:159], v[180:183], v[56:59]
	v_mfma_f32_16x16x32_bf16 v[40:43], v[156:159], v[188:191], v[40:43]
	v_mfma_f32_16x16x32_bf16 v[44:47], v[148:151], v[188:191], v[44:47]
	v_mfma_f32_16x16x32_bf16 v[28:31], v[148:151], v[196:199], v[28:31]
	v_mfma_f32_16x16x32_bf16 v[24:27], v[156:159], v[196:199], v[24:27]
	v_mfma_f32_16x16x32_bf16 v[8:11], v[156:159], v[204:207], v[8:11]
	v_mfma_f32_16x16x32_bf16 v[12:15], v[148:151], v[204:207], v[12:15]
	v_mfma_f32_16x16x32_bf16 v[60:63], v[152:155], v[184:187], v[60:63]
	v_mfma_f32_16x16x32_bf16 v[56:59], v[160:163], v[184:187], v[56:59]
	v_mfma_f32_16x16x32_bf16 v[40:43], v[160:163], v[192:195], v[40:43]
	v_mfma_f32_16x16x32_bf16 v[44:47], v[152:155], v[192:195], v[44:47]
	v_mfma_f32_16x16x32_bf16 v[28:31], v[152:155], v[200:203], v[28:31]
	v_mfma_f32_16x16x32_bf16 v[24:27], v[160:163], v[200:203], v[24:27]
	v_mfma_f32_16x16x32_bf16 v[8:11], v[160:163], v[218:221], v[8:11]
	v_mfma_f32_16x16x32_bf16 v[12:15], v[152:155], v[218:221], v[12:15]
	s_setprio 0
	s_setprio 1
	v_mfma_f32_16x16x32_bf16 v[52:55], v[164:167], v[180:183], v[52:55]
	v_mfma_f32_16x16x32_bf16 v[48:51], v[172:175], v[180:183], v[48:51]
	v_mfma_f32_16x16x32_bf16 v[32:35], v[172:175], v[188:191], v[32:35]
	v_mfma_f32_16x16x32_bf16 v[36:39], v[164:167], v[188:191], v[36:39]
	v_mfma_f32_16x16x32_bf16 v[20:23], v[164:167], v[196:199], v[20:23]
	v_mfma_f32_16x16x32_bf16 v[16:19], v[172:175], v[196:199], v[16:19]
	v_mfma_f32_16x16x32_bf16 v[0:3], v[172:175], v[204:207], v[0:3]
	v_mfma_f32_16x16x32_bf16 v[4:7], v[164:167], v[204:207], v[4:7]
	v_mfma_f32_16x16x32_bf16 v[52:55], v[168:171], v[184:187], v[52:55]
	v_mfma_f32_16x16x32_bf16 v[48:51], v[176:179], v[184:187], v[48:51]
	v_mfma_f32_16x16x32_bf16 v[32:35], v[176:179], v[192:195], v[32:35]
	v_mfma_f32_16x16x32_bf16 v[36:39], v[168:171], v[192:195], v[36:39]
	v_mfma_f32_16x16x32_bf16 v[20:23], v[168:171], v[200:203], v[20:23]
	v_mfma_f32_16x16x32_bf16 v[16:19], v[176:179], v[200:203], v[16:19]
	v_mfma_f32_16x16x32_bf16 v[0:3], v[176:179], v[218:221], v[0:3]
	v_mfma_f32_16x16x32_bf16 v[4:7], v[168:171], v[218:221], v[4:7]
	s_setprio 0
	s_barrier
	s_add_u32 s16, s16, 0x100
	s_addc_u32 s17, s17, 0
	s_add_i32 s46, s46, 2
	s_cmp_gt_u32 s47, 5
	s_cbranch_scc1 .LBB0_838
